# static priority raise for waves 4-7 across each GEMM K-loop, all per-phase setprio flips removed
# baseline (speedup 1.0000x reference)
;     __device__ __forceinline__ bool next(int i, Unit& u) const { Unit t; if (!so.next(i / 3, t)) return false; const int br = i % 3; u.pm = t.pm + br * so.nM; u.pn = t.pn + br * so.nN; return true; }
;     __device__ __forceinline__ bool zero_after(const Unit& u) const { return (u.pn / nN) == 2; }
; #define PG8_STAGE(bufoff, gbase, voff) do { _Pragma("unroll") for (int _i = 0; _i < 2; ++_i) \
;         __builtin_amdgcn_global_load_lds((const unsigned*)((const char*)(gbase) + (voff)[_i]), (PG8_LAS unsigned*)(lds + (bufoff) + ldsw + _i * 8192), 16, 0, 0); } while (0)
; #define PG8_LDA(dst, b, h) do { _Pragma("unroll") for (int m = 0; m < 4; ++m) _Pragma("unroll") for (int k = 0; k < 2; ++k) dst[m][k] = *(const PG8_LAS bf16x8*)(lds + PG8_SA(b, h) + aoff + m * 2048 + k * 1024); } while (0)
; #define PG8_LDB(dst, b, h) do { _Pragma("unroll") for (int n = 0; n < 2; ++n) _Pragma("unroll") for (int k = 0; k < 2; ++k) dst[n][k] = *(const PG8_LAS bf16x8*)(lds + PG8_SB(b, h) + boff + n * 2048 + k * 1024); } while (0)
; template <class Epi, class Sched, bool ALIGN_EPI = false, bool SP2 = false>
; __device__ __forceinline__ void gemm_phase(PG8_LAS unsigned char* lds, const Gemm g, const Sched& S, const Epi& E) {
;     ...
;         const bool has_next = S.next(ui + 1, nxt);
;         const char* nA = has_next ? (const char*)g.A + (size_t)nxt.pm * tstep : cA; const char* nB = has_next ? (const char*)g.Bt + (size_t)nxt.pn * tstep : cB;
;         for (int t = 0; t < nt; t += 2) {
;             const bool last = (t == nt - 2);
;             const char* a1 = cA + (size_t)(t + 1) * kstep;
;             const char* a2 = last ? nA : cA + (size_t)(t + 2) * kstep; const char* b2 = last ? nB : cB + (size_t)(t + 2) * kstep;
;             const char* a3 = a2 + kstep; const char* b3 = b2 + kstep;
;             if (last && has_next) S.a_ready(nxt);
;             if constexpr (SP2) {
;             PG8_LDB(B0, 0, 0); PG8_LDB(B1, 0, 1); PG8_SCHED; PG8_LDA(At, 0, 0); PG8_STAGE(PG8_SA(1, 1), a1 + hstep, voffA);
;     ...
;         if (E.zero_after(cur)) {
; #pragma unroll
;         for (int a = 0; a < 2; ++a)
; #pragma unroll
;             for (int b = 0; b < 2; ++b)
; #pragma unroll
;                 for (int m = 0; m < 4; ++m)
; #pragma unroll
;                     for (int n = 0; n < 2; ++n) acc[a][b][m][n] = (f32x4){0.f, 0.f, 0.f, 0.f};
;         }
;         cur = nxt; cA = nA; cB = nB; ++ui;
.LBB0_147:
	s_ashr_i32 s25, s24, 31
	s_lshl_b64 s[26:27], s[24:25], 20
	s_add_u32 s26, s1, s26
	s_addc_u32 s27, s40, s27
	s_and_b64 s[28:29], s[4:5], exec
	s_cselect_b32 s25, s27, s7
	s_cselect_b32 s34, s26, s6
	s_ashr_i32 s23, s22, 31
	s_lshl_b64 s[28:29], s[22:23], 20
	s_add_u32 s28, s41, s28
	s_addc_u32 s29, s44, s29
	s_and_b64 s[30:31], s[4:5], exec
	s_cselect_b32 s23, s29, s9
	s_cselect_b32 s35, s28, s8
	s_add_u32 s6, s6, 0x80080
	s_addc_u32 s7, s7, 0
	s_add_u32 s36, s8, 0x100
	s_addc_u32 s37, s9, 0
	s_mov_b32 s38, -2
	v_mov_b64_e32 v[0:1], 0
	v_mov_b64_e32 v[2:3], 0
	v_mov_b64_e32 v[4:5], 0
	v_mov_b64_e32 v[6:7], 0
	v_mov_b64_e32 v[8:9], 0
	v_mov_b64_e32 v[10:11], 0
	v_mov_b64_e32 v[12:13], 0
	v_mov_b64_e32 v[14:15], 0
	v_mov_b64_e32 v[16:17], 0
	v_mov_b64_e32 v[18:19], 0
	v_mov_b64_e32 v[20:21], 0
	v_mov_b64_e32 v[22:23], 0
	v_mov_b64_e32 v[24:25], 0
	v_mov_b64_e32 v[26:27], 0
	v_mov_b64_e32 v[28:29], 0
	v_mov_b64_e32 v[30:31], 0
	v_mov_b64_e32 v[32:33], 0
	v_mov_b64_e32 v[34:35], 0
	v_mov_b64_e32 v[36:37], 0
	v_mov_b64_e32 v[38:39], 0
	v_mov_b64_e32 v[40:41], 0
	v_mov_b64_e32 v[42:43], 0
	v_mov_b64_e32 v[44:45], 0
	v_mov_b64_e32 v[46:47], 0
	v_mov_b64_e32 v[48:49], 0
	v_mov_b64_e32 v[50:51], 0
	v_mov_b64_e32 v[52:53], 0
	v_mov_b64_e32 v[54:55], 0
	v_mov_b64_e32 v[56:57], 0
	v_mov_b64_e32 v[58:59], 0
	v_mov_b64_e32 v[60:61], 0
	v_mov_b64_e32 v[62:63], 0
	v_mov_b64_e32 v[64:65], 0
	v_mov_b64_e32 v[66:67], 0
	v_mov_b64_e32 v[68:69], 0
	v_mov_b64_e32 v[70:71], 0
	v_mov_b64_e32 v[72:73], 0
	v_mov_b64_e32 v[74:75], 0
	v_mov_b64_e32 v[76:77], 0
	v_mov_b64_e32 v[78:79], 0
	v_mov_b64_e32 v[80:81], 0
	v_mov_b64_e32 v[82:83], 0
	v_mov_b64_e32 v[84:85], 0
	v_mov_b64_e32 v[86:87], 0
	v_mov_b64_e32 v[88:89], 0
	v_mov_b64_e32 v[90:91], 0
	v_mov_b64_e32 v[92:93], 0
	v_mov_b64_e32 v[94:95], 0
	v_mov_b64_e32 v[96:97], 0
	v_mov_b64_e32 v[98:99], 0
	v_mov_b64_e32 v[100:101], 0
	v_mov_b64_e32 v[102:103], 0
	v_mov_b64_e32 v[104:105], 0
	v_mov_b64_e32 v[106:107], 0
	v_mov_b64_e32 v[108:109], 0
	v_mov_b64_e32 v[110:111], 0
	v_mov_b64_e32 v[112:113], 0
	v_mov_b64_e32 v[114:115], 0
	v_mov_b64_e32 v[116:117], 0
	v_mov_b64_e32 v[118:119], 0
	v_mov_b64_e32 v[120:121], 0
	v_mov_b64_e32 v[122:123], 0
	v_mov_b64_e32 v[124:125], 0
	v_mov_b64_e32 v[126:127], 0
	s_cmp_eq_u64 s[20:21], 0
	s_cbranch_scc0 .Lprio_skip_148
	s_setprio 1
.Lprio_skip_148:
.LBB0_148:
	s_add_u32 s8, s6, 0xfff80080
	s_addc_u32 s9, s7, -1
	s_add_i32 s39, 0, 0x10000
	s_cmp_eq_u32 s38, 28
	s_cselect_b32 s31, s25, s9
	s_cselect_b32 s30, s34, s8
	s_cselect_b32 s9, s23, s37
	s_cselect_b32 s8, s35, s36
	s_add_i32 s58, 0, 0x14000
	v_add_u32_e32 v140, s39, v181
	v_add_u32_e32 v178, s58, v181
	ds_read_b128 v[128:131], v140
	ds_read_b128 v[132:135], v140 offset:1024
	ds_read_b128 v[136:139], v140 offset:2048
	ds_read_b128 v[140:143], v140 offset:3072
	ds_read_b128 v[174:177], v178
	ds_read_b128 v[184:187], v178 offset:1024
	ds_read_b128 v[198:201], v178 offset:2048
	ds_read_b128 v[202:205], v178 offset:3072
	v_lshl_add_u64 v[246:247], s[6:7], 0, v[154:155]
	s_add_i32 m0, s63, 0xc000
	ds_read_b128 v[206:209], v183
	ds_read_b128 v[210:213], v183 offset:1024
	ds_read_b128 v[214:217], v183 offset:2048
	ds_read_b128 v[218:221], v183 offset:3072
	ds_read_b128 v[222:225], v183 offset:4096
	ds_read_b128 v[226:229], v183 offset:5120
	ds_read_b128 v[238:241], v183 offset:6144
	ds_read_b128 v[242:245], v183 offset:7168
	global_load_lds_dwordx4 v[246:247], off
	v_lshl_add_u64 v[246:247], s[6:7], 0, v[156:157]
	s_add_i32 m0, s63, 0xe000
	s_nop 0
	global_load_lds_dwordx4 v[246:247], off
	s_waitcnt vmcnt(8)
	s_waitcnt lgkmcnt(0)
	s_barrier
	v_mfma_f32_16x16x32_bf16 v[124:127], v[128:131], v[206:209], v[124:127]
	v_mfma_f32_16x16x32_bf16 v[120:123], v[136:139], v[206:209], v[120:123]
	v_mfma_f32_16x16x32_bf16 v[108:111], v[128:131], v[214:217], v[108:111]
	v_mfma_f32_16x16x32_bf16 v[104:107], v[136:139], v[214:217], v[104:107]
	v_mfma_f32_16x16x32_bf16 v[92:95], v[128:131], v[222:225], v[92:95]
	v_mfma_f32_16x16x32_bf16 v[88:91], v[136:139], v[222:225], v[88:91]
	v_mfma_f32_16x16x32_bf16 v[76:79], v[128:131], v[238:241], v[76:79]
	v_mfma_f32_16x16x32_bf16 v[72:75], v[136:139], v[238:241], v[72:75]
	v_mfma_f32_16x16x32_bf16 v[124:127], v[132:135], v[210:213], v[124:127]
	v_mfma_f32_16x16x32_bf16 v[120:123], v[140:143], v[210:213], v[120:123]
	v_mfma_f32_16x16x32_bf16 v[108:111], v[132:135], v[218:221], v[108:111]
	v_mfma_f32_16x16x32_bf16 v[104:107], v[140:143], v[218:221], v[104:107]
	v_mfma_f32_16x16x32_bf16 v[92:95], v[132:135], v[226:229], v[92:95]
	v_mfma_f32_16x16x32_bf16 v[88:91], v[140:143], v[226:229], v[88:91]
	v_mfma_f32_16x16x32_bf16 v[76:79], v[132:135], v[242:245], v[76:79]
	v_mfma_f32_16x16x32_bf16 v[72:75], v[140:143], v[242:245], v[72:75]
	v_mfma_f32_16x16x32_bf16 v[116:119], v[174:177], v[206:209], v[116:119]
	v_mfma_f32_16x16x32_bf16 v[112:115], v[198:201], v[206:209], v[112:115]
	v_mfma_f32_16x16x32_bf16 v[100:103], v[174:177], v[214:217], v[100:103]
	v_mfma_f32_16x16x32_bf16 v[96:99], v[198:201], v[214:217], v[96:99]
	v_mfma_f32_16x16x32_bf16 v[84:87], v[174:177], v[222:225], v[84:87]
	v_mfma_f32_16x16x32_bf16 v[80:83], v[198:201], v[222:225], v[80:83]
	v_mfma_f32_16x16x32_bf16 v[68:71], v[174:177], v[238:241], v[68:71]
	v_mfma_f32_16x16x32_bf16 v[64:67], v[198:201], v[238:241], v[64:67]
	v_mfma_f32_16x16x32_bf16 v[116:119], v[184:187], v[210:213], v[116:119]
	v_mfma_f32_16x16x32_bf16 v[112:115], v[202:205], v[210:213], v[112:115]
	v_mfma_f32_16x16x32_bf16 v[100:103], v[184:187], v[218:221], v[100:103]
	v_mfma_f32_16x16x32_bf16 v[96:99], v[202:205], v[218:221], v[96:99]
	v_mfma_f32_16x16x32_bf16 v[84:87], v[184:187], v[226:229], v[84:87]
	v_mfma_f32_16x16x32_bf16 v[80:83], v[202:205], v[226:229], v[80:83]
	v_mfma_f32_16x16x32_bf16 v[68:71], v[184:187], v[242:245], v[68:71]
	v_mfma_f32_16x16x32_bf16 v[64:67], v[202:205], v[242:245], v[64:67]
	s_barrier
; #define PG8_STAGE(bufoff, gbase, voff) do { _Pragma("unroll") for (int _i = 0; _i < 2; ++_i) \
;         __builtin_amdgcn_global_load_lds((const unsigned*)((const char*)(gbase) + (voff)[_i]), (PG8_LAS unsigned*)(lds + (bufoff) + ldsw + _i * 8192), 16, 0, 0); } while (0)
; #define PG8_LDA(dst, b, h) do { _Pragma("unroll") for (int m = 0; m < 4; ++m) _Pragma("unroll") for (int k = 0; k < 2; ++k) dst[m][k] = *(const PG8_LAS bf16x8*)(lds + PG8_SA(b, h) + aoff + m * 2048 + k * 1024); } while (0)
; #define PG8_LDB(dst, b, h) do { _Pragma("unroll") for (int n = 0; n < 2; ++n) _Pragma("unroll") for (int k = 0; k < 2; ++k) dst[n][k] = *(const PG8_LAS bf16x8*)(lds + PG8_SB(b, h) + boff + n * 2048 + k * 1024); } while (0)
; #define PG8_MMA(ai, bj, At, Bt) do { __builtin_amdgcn_s_setprio(1); _Pragma("unroll") for (int m = 0; m < 4; ++m) _Pragma("unroll") for (int n = 0; n < 2; ++n) _Pragma("unroll") for (int k = 0; k < 2; ++k) \
;         acc[ai][bj][m][n] = __builtin_amdgcn_mfma_f32_16x16x32_bf16(Bt[n][k], At[m][k], acc[ai][bj][m][n], 0, 0, 0); __builtin_amdgcn_s_setprio(0); } while (0)
; #define PG8_WAIT_V(n) asm volatile("s_waitcnt vmcnt(" #n ")" ::: "memory")
; #define PG8_WAIT_L(n) asm volatile("s_waitcnt lgkmcnt(" #n ")" ::: "memory")
; #define PG8_BAR __builtin_amdgcn_s_barrier()
; #define PG8_SCHED __builtin_amdgcn_sched_barrier(0)
; template <class Epi, class Sched, bool ALIGN_EPI = false, bool SP2 = false>
; __device__ __forceinline__ void gemm_phase(PG8_LAS unsigned char* lds, const Gemm g, const Sched& S, const Epi& E) {
;     ...
;             PG8_LDA(At, 0, 1); PG8_STAGE(PG8_SB(0, 0), b2, voffB); PG8_STAGE(PG8_SB(0, 1), b2 + hstep, voffB); PG8_STAGE(PG8_SA(0, 0), a2, voffA);
;             PG8_WAIT_V(8); PG8_WAIT_L(0); PG8_BAR; PG8_MMA(1, 0, At, B0); PG8_MMA(1, 1, At, B1); PG8_BAR; PG8_SCHED;
;             PG8_LDB(B0, 1, 0); PG8_LDB(B1, 1, 1); PG8_SCHED; PG8_LDA(At, 1, 0); PG8_STAGE(PG8_SA(0, 1), a2 + hstep, voffA);
	s_add_i32 s39, s39, s45
	v_lshl_add_u64 v[246:247], s[8:9], 0, v[148:149]
	s_mov_b32 m0, s39
	ds_read_b128 v[206:209], v183 offset:16384
	ds_read_b128 v[210:213], v183 offset:17408
	ds_read_b128 v[214:217], v183 offset:18432
	ds_read_b128 v[218:221], v183 offset:19456
	ds_read_b128 v[222:225], v183 offset:20480
	ds_read_b128 v[226:229], v183 offset:21504
	ds_read_b128 v[238:241], v183 offset:22528
	ds_read_b128 v[242:245], v183 offset:23552
	global_load_lds_dwordx4 v[246:247], off
	s_add_i32 m0, s39, 0x2000
	s_add_u32 s88, s8, 0x80000
	v_lshl_add_u64 v[248:249], s[8:9], 0, v[144:145]
	s_addc_u32 s89, s9, 0
	s_add_i32 s39, s58, s45
	global_load_lds_dwordx4 v[248:249], off
	v_lshl_add_u64 v[250:251], s[88:89], 0, v[148:149]
	s_mov_b32 m0, s39
	v_lshl_add_u64 v[252:253], s[30:31], 0, v[146:147]
	global_load_lds_dwordx4 v[250:251], off
	v_lshl_add_u64 v[250:251], s[88:89], 0, v[144:145]
	s_add_i32 m0, s39, 0x2000
	s_nop 0
	global_load_lds_dwordx4 v[250:251], off
	v_lshl_add_u64 v[250:251], s[30:31], 0, v[150:151]
	s_mov_b32 m0, s63
	s_nop 0
	global_load_lds_dwordx4 v[250:251], off
	s_mov_b32 m0, s66
	s_nop 0
	global_load_lds_dwordx4 v[252:253], off
	s_waitcnt vmcnt(8)
	s_waitcnt lgkmcnt(0)
	s_barrier
	v_mfma_f32_16x16x32_bf16 v[60:63], v[128:131], v[206:209], v[60:63]
	v_mfma_f32_16x16x32_bf16 v[56:59], v[136:139], v[206:209], v[56:59]
	v_mfma_f32_16x16x32_bf16 v[44:47], v[128:131], v[214:217], v[44:47]
	v_mfma_f32_16x16x32_bf16 v[40:43], v[136:139], v[214:217], v[40:43]
	v_mfma_f32_16x16x32_bf16 v[28:31], v[128:131], v[222:225], v[28:31]
	v_mfma_f32_16x16x32_bf16 v[24:27], v[136:139], v[222:225], v[24:27]
	v_mfma_f32_16x16x32_bf16 v[12:15], v[128:131], v[238:241], v[12:15]
	v_mfma_f32_16x16x32_bf16 v[8:11], v[136:139], v[238:241], v[8:11]
	v_mfma_f32_16x16x32_bf16 v[60:63], v[132:135], v[210:213], v[60:63]
	v_mfma_f32_16x16x32_bf16 v[56:59], v[140:143], v[210:213], v[56:59]
	v_mfma_f32_16x16x32_bf16 v[44:47], v[132:135], v[218:221], v[44:47]
	v_mfma_f32_16x16x32_bf16 v[40:43], v[140:143], v[218:221], v[40:43]
	v_mfma_f32_16x16x32_bf16 v[28:31], v[132:135], v[226:229], v[28:31]
	v_mfma_f32_16x16x32_bf16 v[24:27], v[140:143], v[226:229], v[24:27]
	v_mfma_f32_16x16x32_bf16 v[12:15], v[132:135], v[242:245], v[12:15]
	v_mfma_f32_16x16x32_bf16 v[8:11], v[140:143], v[242:245], v[8:11]
	v_mfma_f32_16x16x32_bf16 v[52:55], v[174:177], v[206:209], v[52:55]
	v_mfma_f32_16x16x32_bf16 v[48:51], v[198:201], v[206:209], v[48:51]
	v_mfma_f32_16x16x32_bf16 v[36:39], v[174:177], v[214:217], v[36:39]
	v_mfma_f32_16x16x32_bf16 v[32:35], v[198:201], v[214:217], v[32:35]
	v_mfma_f32_16x16x32_bf16 v[20:23], v[174:177], v[222:225], v[20:23]
	v_mfma_f32_16x16x32_bf16 v[16:19], v[198:201], v[222:225], v[16:19]
	v_mfma_f32_16x16x32_bf16 v[4:7], v[174:177], v[238:241], v[4:7]
	v_mfma_f32_16x16x32_bf16 v[0:3], v[198:201], v[238:241], v[0:3]
	v_mfma_f32_16x16x32_bf16 v[52:55], v[184:187], v[210:213], v[52:55]
	v_mfma_f32_16x16x32_bf16 v[48:51], v[202:205], v[210:213], v[48:51]
	v_mfma_f32_16x16x32_bf16 v[36:39], v[184:187], v[218:221], v[36:39]
	v_mfma_f32_16x16x32_bf16 v[32:35], v[202:205], v[218:221], v[32:35]
	v_mfma_f32_16x16x32_bf16 v[20:23], v[184:187], v[226:229], v[20:23]
	v_mfma_f32_16x16x32_bf16 v[16:19], v[202:205], v[226:229], v[16:19]
	v_mfma_f32_16x16x32_bf16 v[4:7], v[184:187], v[242:245], v[4:7]
	v_mfma_f32_16x16x32_bf16 v[0:3], v[202:205], v[242:245], v[0:3]
	s_barrier
	s_add_i32 s39, 0, 0x18000
	s_add_i32 s58, 0, 0x1c000
	v_add_u32_e32 v140, s39, v181
	v_add_u32_e32 v178, s58, v181
	ds_read_b128 v[128:131], v140
	ds_read_b128 v[132:135], v140 offset:1024
	ds_read_b128 v[136:139], v140 offset:2048
	ds_read_b128 v[140:143], v140 offset:3072
	ds_read_b128 v[174:177], v178
	ds_read_b128 v[184:187], v178 offset:1024
	ds_read_b128 v[198:201], v178 offset:2048
	ds_read_b128 v[202:205], v178 offset:3072
	s_add_u32 s30, s30, 0x80000
	s_addc_u32 s31, s31, 0
	s_mov_b32 m0, s67
	v_lshl_add_u64 v[232:233], s[30:31], 0, v[150:151]
	ds_read_b128 v[206:209], v183 offset:32768
	ds_read_b128 v[210:213], v183 offset:33792
	ds_read_b128 v[214:217], v183 offset:34816
	ds_read_b128 v[218:221], v183 offset:35840
	ds_read_b128 v[222:225], v183 offset:36864
	ds_read_b128 v[226:229], v183 offset:37888
	ds_read_b128 v[238:241], v183 offset:38912
	ds_read_b128 v[242:245], v183 offset:39936
	global_load_lds_dwordx4 v[232:233], off
	v_lshl_add_u64 v[232:233], s[30:31], 0, v[146:147]
	s_mov_b32 m0, s72
	s_nop 0
	global_load_lds_dwordx4 v[232:233], off
	s_waitcnt vmcnt(8)
	s_waitcnt lgkmcnt(0)
	s_barrier
; #define PG8_STAGE(bufoff, gbase, voff) do { _Pragma("unroll") for (int _i = 0; _i < 2; ++_i) \
;         __builtin_amdgcn_global_load_lds((const unsigned*)((const char*)(gbase) + (voff)[_i]), (PG8_LAS unsigned*)(lds + (bufoff) + ldsw + _i * 8192), 16, 0, 0); } while (0)
; #define PG8_LDA(dst, b, h) do { _Pragma("unroll") for (int m = 0; m < 4; ++m) _Pragma("unroll") for (int k = 0; k < 2; ++k) dst[m][k] = *(const PG8_LAS bf16x8*)(lds + PG8_SA(b, h) + aoff + m * 2048 + k * 1024); } while (0)
; #define PG8_MMA(ai, bj, At, Bt) do { __builtin_amdgcn_s_setprio(1); _Pragma("unroll") for (int m = 0; m < 4; ++m) _Pragma("unroll") for (int n = 0; n < 2; ++n) _Pragma("unroll") for (int k = 0; k < 2; ++k) \
;         acc[ai][bj][m][n] = __builtin_amdgcn_mfma_f32_16x16x32_bf16(Bt[n][k], At[m][k], acc[ai][bj][m][n], 0, 0, 0); __builtin_amdgcn_s_setprio(0); } while (0)
; #define PG8_WAIT_V(n) asm volatile("s_waitcnt vmcnt(" #n ")" ::: "memory")
; #define PG8_WAIT_L(n) asm volatile("s_waitcnt lgkmcnt(" #n ")" ::: "memory")
; #define PG8_BAR __builtin_amdgcn_s_barrier()
; #define PG8_SCHED __builtin_amdgcn_sched_barrier(0)
; template <class Epi, class Sched, bool ALIGN_EPI = false, bool SP2 = false>
; __device__ __forceinline__ void gemm_phase(PG8_LAS unsigned char* lds, const Gemm g, const Sched& S, const Epi& E) {
;     ...
;             PG8_WAIT_V(8); PG8_WAIT_L(0); PG8_BAR; PG8_MMA(0, 0, At, B0); PG8_MMA(0, 1, At, B1); PG8_BAR; PG8_SCHED;
;             PG8_LDA(At, 1, 1); PG8_STAGE(PG8_SB(1, 0), b3, voffB); PG8_STAGE(PG8_SB(1, 1), b3 + hstep, voffB); PG8_STAGE(PG8_SA(1, 0), a3, voffA);
;             PG8_WAIT_V(8); PG8_WAIT_L(0); PG8_BAR; PG8_MMA(1, 0, At, B0); PG8_MMA(1, 1, At, B1); PG8_BAR; PG8_SCHED;
;     ...
;         if constexpr (ALIGN_EPI) { if (wr == 0) PG8_BAR; }
	v_mfma_f32_16x16x32_bf16 v[124:127], v[128:131], v[206:209], v[124:127]
	v_mfma_f32_16x16x32_bf16 v[120:123], v[136:139], v[206:209], v[120:123]
	v_mfma_f32_16x16x32_bf16 v[108:111], v[128:131], v[214:217], v[108:111]
	v_mfma_f32_16x16x32_bf16 v[104:107], v[136:139], v[214:217], v[104:107]
	v_mfma_f32_16x16x32_bf16 v[92:95], v[128:131], v[222:225], v[92:95]
	v_mfma_f32_16x16x32_bf16 v[88:91], v[136:139], v[222:225], v[88:91]
	v_mfma_f32_16x16x32_bf16 v[76:79], v[128:131], v[238:241], v[76:79]
	v_mfma_f32_16x16x32_bf16 v[72:75], v[136:139], v[238:241], v[72:75]
	v_mfma_f32_16x16x32_bf16 v[124:127], v[132:135], v[210:213], v[124:127]
	v_mfma_f32_16x16x32_bf16 v[120:123], v[140:143], v[210:213], v[120:123]
	v_mfma_f32_16x16x32_bf16 v[108:111], v[132:135], v[218:221], v[108:111]
	v_mfma_f32_16x16x32_bf16 v[104:107], v[140:143], v[218:221], v[104:107]
	v_mfma_f32_16x16x32_bf16 v[92:95], v[132:135], v[226:229], v[92:95]
	v_mfma_f32_16x16x32_bf16 v[88:91], v[140:143], v[226:229], v[88:91]
	v_mfma_f32_16x16x32_bf16 v[76:79], v[132:135], v[242:245], v[76:79]
	v_mfma_f32_16x16x32_bf16 v[72:75], v[140:143], v[242:245], v[72:75]
	v_mfma_f32_16x16x32_bf16 v[116:119], v[174:177], v[206:209], v[116:119]
	v_mfma_f32_16x16x32_bf16 v[112:115], v[198:201], v[206:209], v[112:115]
	v_mfma_f32_16x16x32_bf16 v[100:103], v[174:177], v[214:217], v[100:103]
	v_mfma_f32_16x16x32_bf16 v[96:99], v[198:201], v[214:217], v[96:99]
	v_mfma_f32_16x16x32_bf16 v[84:87], v[174:177], v[222:225], v[84:87]
	v_mfma_f32_16x16x32_bf16 v[80:83], v[198:201], v[222:225], v[80:83]
	v_mfma_f32_16x16x32_bf16 v[68:71], v[174:177], v[238:241], v[68:71]
	v_mfma_f32_16x16x32_bf16 v[64:67], v[198:201], v[238:241], v[64:67]
	v_mfma_f32_16x16x32_bf16 v[116:119], v[184:187], v[210:213], v[116:119]
	v_mfma_f32_16x16x32_bf16 v[112:115], v[202:205], v[210:213], v[112:115]
	v_mfma_f32_16x16x32_bf16 v[100:103], v[184:187], v[218:221], v[100:103]
	v_mfma_f32_16x16x32_bf16 v[96:99], v[202:205], v[218:221], v[96:99]
	v_mfma_f32_16x16x32_bf16 v[84:87], v[184:187], v[226:229], v[84:87]
	v_mfma_f32_16x16x32_bf16 v[80:83], v[202:205], v[226:229], v[80:83]
	v_mfma_f32_16x16x32_bf16 v[68:71], v[184:187], v[242:245], v[68:71]
	v_mfma_f32_16x16x32_bf16 v[64:67], v[202:205], v[242:245], v[64:67]
	s_barrier
	s_add_i32 s30, s39, s45
	v_lshl_add_u64 v[232:233], v[246:247], 0, s[78:79]
	s_mov_b32 m0, s30
	ds_read_b128 v[206:209], v183 offset:49152
	ds_read_b128 v[210:213], v183 offset:50176
	ds_read_b128 v[214:217], v183 offset:51200
	ds_read_b128 v[218:221], v183 offset:52224
	ds_read_b128 v[222:225], v183 offset:53248
	ds_read_b128 v[226:229], v183 offset:54272
	ds_read_b128 v[238:241], v183 offset:55296
	ds_read_b128 v[242:245], v183 offset:56320
	global_load_lds_dwordx4 v[232:233], off
	s_add_i32 m0, s30, 0x2000
	s_add_u32 s8, s8, 0x80080
	v_lshl_add_u64 v[232:233], v[248:249], 0, s[78:79]
	s_addc_u32 s9, s9, 0
	s_add_i32 s30, s58, s45
	global_load_lds_dwordx4 v[232:233], off
	v_lshl_add_u64 v[232:233], s[8:9], 0, v[148:149]
	s_mov_b32 m0, s30
	s_nop 0
	global_load_lds_dwordx4 v[232:233], off
	v_lshl_add_u64 v[232:233], s[8:9], 0, v[144:145]
	s_add_i32 m0, s30, 0x2000
	s_nop 0
	global_load_lds_dwordx4 v[232:233], off
	v_lshl_add_u64 v[232:233], v[250:251], 0, s[78:79]
	s_mov_b32 m0, s73
	s_nop 0
	global_load_lds_dwordx4 v[232:233], off
	v_lshl_add_u64 v[232:233], v[252:253], 0, s[78:79]
	s_mov_b32 m0, s74
	s_nop 0
	global_load_lds_dwordx4 v[232:233], off
	s_waitcnt vmcnt(8)
	s_waitcnt lgkmcnt(0)
	s_barrier
	v_mfma_f32_16x16x32_bf16 v[60:63], v[128:131], v[206:209], v[60:63]
	v_mfma_f32_16x16x32_bf16 v[56:59], v[136:139], v[206:209], v[56:59]
	v_mfma_f32_16x16x32_bf16 v[44:47], v[128:131], v[214:217], v[44:47]
	v_mfma_f32_16x16x32_bf16 v[40:43], v[136:139], v[214:217], v[40:43]
	v_mfma_f32_16x16x32_bf16 v[28:31], v[128:131], v[222:225], v[28:31]
	v_mfma_f32_16x16x32_bf16 v[24:27], v[136:139], v[222:225], v[24:27]
	v_mfma_f32_16x16x32_bf16 v[12:15], v[128:131], v[238:241], v[12:15]
	v_mfma_f32_16x16x32_bf16 v[8:11], v[136:139], v[238:241], v[8:11]
	v_mfma_f32_16x16x32_bf16 v[60:63], v[132:135], v[210:213], v[60:63]
	v_mfma_f32_16x16x32_bf16 v[56:59], v[140:143], v[210:213], v[56:59]
	v_mfma_f32_16x16x32_bf16 v[44:47], v[132:135], v[218:221], v[44:47]
	v_mfma_f32_16x16x32_bf16 v[40:43], v[140:143], v[218:221], v[40:43]
	v_mfma_f32_16x16x32_bf16 v[28:31], v[132:135], v[226:229], v[28:31]
	v_mfma_f32_16x16x32_bf16 v[24:27], v[140:143], v[226:229], v[24:27]
	v_mfma_f32_16x16x32_bf16 v[12:15], v[132:135], v[242:245], v[12:15]
	v_mfma_f32_16x16x32_bf16 v[8:11], v[140:143], v[242:245], v[8:11]
	v_mfma_f32_16x16x32_bf16 v[52:55], v[174:177], v[206:209], v[52:55]
	v_mfma_f32_16x16x32_bf16 v[48:51], v[198:201], v[206:209], v[48:51]
	v_mfma_f32_16x16x32_bf16 v[36:39], v[174:177], v[214:217], v[36:39]
	v_mfma_f32_16x16x32_bf16 v[32:35], v[198:201], v[214:217], v[32:35]
	v_mfma_f32_16x16x32_bf16 v[20:23], v[174:177], v[222:225], v[20:23]
	v_mfma_f32_16x16x32_bf16 v[16:19], v[198:201], v[222:225], v[16:19]
	v_mfma_f32_16x16x32_bf16 v[4:7], v[174:177], v[238:241], v[4:7]
	v_mfma_f32_16x16x32_bf16 v[0:3], v[198:201], v[238:241], v[0:3]
	v_mfma_f32_16x16x32_bf16 v[52:55], v[184:187], v[210:213], v[52:55]
	v_mfma_f32_16x16x32_bf16 v[48:51], v[202:205], v[210:213], v[48:51]
	v_mfma_f32_16x16x32_bf16 v[36:39], v[184:187], v[218:221], v[36:39]
	v_mfma_f32_16x16x32_bf16 v[32:35], v[202:205], v[218:221], v[32:35]
	v_mfma_f32_16x16x32_bf16 v[20:23], v[184:187], v[226:229], v[20:23]
	v_mfma_f32_16x16x32_bf16 v[16:19], v[202:205], v[226:229], v[16:19]
	v_mfma_f32_16x16x32_bf16 v[4:7], v[184:187], v[242:245], v[4:7]
	v_mfma_f32_16x16x32_bf16 v[0:3], v[202:205], v[242:245], v[0:3]
	s_barrier
	s_add_i32 s38, s38, 2
	s_add_u32 s6, s6, 0x100
	s_addc_u32 s7, s7, 0
	s_add_u32 s36, s36, 0x100
	s_addc_u32 s37, s37, 0
	s_cmp_gt_u32 s38, 29
	s_cbranch_scc0 .LBB0_148
	s_setprio 0
	s_and_b64 vcc, exec, s[20:21]
	s_cbranch_vccz .LBB0_151
	s_barrier

;     __device__ __forceinline__ bool next(int i, Unit& u) const { Unit t; if (!so.next(i / 3, t)) return false; const int br = i % 3; u.pm = t.pm + br * so.nM; u.pn = t.pn + br * so.nN; return true; }
; #define PG8_STAGE(bufoff, gbase, voff) do { _Pragma("unroll") for (int _i = 0; _i < 2; ++_i) \
;         __builtin_amdgcn_global_load_lds((const unsigned*)((const char*)(gbase) + (voff)[_i]), (PG8_LAS unsigned*)(lds + (bufoff) + ldsw + _i * 8192), 16, 0, 0); } while (0)
; #define PG8_LDA(dst, b, h) do { _Pragma("unroll") for (int m = 0; m < 4; ++m) _Pragma("unroll") for (int k = 0; k < 2; ++k) dst[m][k] = *(const PG8_LAS bf16x8*)(lds + PG8_SA(b, h) + aoff + m * 2048 + k * 1024); } while (0)
; #define PG8_LDB(dst, b, h) do { _Pragma("unroll") for (int n = 0; n < 2; ++n) _Pragma("unroll") for (int k = 0; k < 2; ++k) dst[n][k] = *(const PG8_LAS bf16x8*)(lds + PG8_SB(b, h) + boff + n * 2048 + k * 1024); } while (0)
; #define PG8_WAIT_V(n) asm volatile("s_waitcnt vmcnt(" #n ")" ::: "memory")
; template <class Epi, class Sched, bool ALIGN_EPI = false, bool SP2 = false>
; __device__ __forceinline__ void gemm_phase(PG8_LAS unsigned char* lds, const Gemm g, const Sched& S, const Epi& E) {
;     ...
;         const bool has_next = S.next(ui + 1, nxt);
;         const char* nA = has_next ? (const char*)g.A + (size_t)nxt.pm * tstep : cA; const char* nB = has_next ? (const char*)g.Bt + (size_t)nxt.pn * tstep : cB;
;         for (int t = 0; t < nt; t += 2) {
;             const bool last = (t == nt - 2);
;             const char* a1 = cA + (size_t)(t + 1) * kstep;
;             const char* a2 = last ? nA : cA + (size_t)(t + 2) * kstep; const char* b2 = last ? nB : cB + (size_t)(t + 2) * kstep;
;             const char* a3 = a2 + kstep; const char* b3 = b2 + kstep;
;             if (last && has_next) S.a_ready(nxt);
;             if constexpr (SP2) {
;             PG8_LDB(B0, 0, 0); PG8_LDB(B1, 0, 1); PG8_SCHED; PG8_LDA(At, 0, 0); PG8_STAGE(PG8_SA(1, 1), a1 + hstep, voffA);
;             PG8_WAIT_V(8); PG8_WAIT_L(0); PG8_BAR; PG8_MMA(0, 0, At, B0); PG8_MMA(0, 1, At, B1); PG8_BAR; PG8_SCHED;
;             PG8_LDA(At, 0, 1); PG8_STAGE(PG8_SB(0, 0), b2, voffB); PG8_STAGE(PG8_SB(0, 1), b2 + hstep, voffB); PG8_STAGE(PG8_SA(0, 0), a2, voffA);
;             PG8_WAIT_V(8); PG8_WAIT_L(0); PG8_BAR; PG8_MMA(1, 0, At, B0); PG8_MMA(1, 1, At, B1); PG8_BAR; PG8_SCHED;
.LBB0_423:
	s_ashr_i32 s17, s16, 31
	s_lshl_b64 s[20:21], s[16:17], 19
	s_add_u32 s20, s26, s20
	s_addc_u32 s21, s27, s21
	s_and_b64 s[22:23], s[4:5], exec
	s_cselect_b32 s17, s21, s7
	s_cselect_b32 s38, s20, s6
	s_ashr_i32 s19, s18, 31
	s_lshl_b64 s[22:23], s[18:19], 19
	s_add_u32 s22, s28, s22
	s_addc_u32 s23, s29, s23
	s_and_b64 s[24:25], s[4:5], exec
	s_cselect_b32 s19, s23, s9
	s_cselect_b32 s39, s22, s8
	s_add_u32 s6, s6, 0x40080
	s_addc_u32 s7, s7, 0
	s_add_u32 s45, s8, 0x100
	s_addc_u32 s52, s9, 0
	s_mov_b32 s58, -2
	s_cmp_eq_u64 s[14:15], 0
	s_cbranch_scc0 .Lprio_skip_424
	s_setprio 1
.Lprio_skip_424:
.LBB0_424:
	s_add_u32 s8, s6, 0xfffc0080
	s_addc_u32 s9, s7, -1
	s_add_i32 s60, 0, 0x10000
	s_cmp_eq_u32 s58, 12
	s_cselect_b32 s25, s17, s9
	s_cselect_b32 s24, s38, s8
	s_cselect_b32 s9, s19, s52
	s_cselect_b32 s8, s39, s45
	s_add_i32 s62, 0, 0x14000
	v_add_u32_e32 v140, s60, v201
	v_add_u32_e32 v156, s62, v201
	ds_read_b128 v[128:131], v140
	ds_read_b128 v[132:135], v140 offset:1024
	ds_read_b128 v[136:139], v140 offset:2048
	ds_read_b128 v[140:143], v140 offset:3072
	ds_read_b128 v[144:147], v156
	ds_read_b128 v[148:151], v156 offset:1024
	ds_read_b128 v[152:155], v156 offset:2048
	ds_read_b128 v[156:159], v156 offset:3072
	v_lshl_add_u64 v[198:199], s[6:7], 0, v[168:169]
	s_add_i32 m0, s31, 0xc000
	ds_read_b128 v[172:175], v203
	ds_read_b128 v[176:179], v203 offset:1024
	ds_read_b128 v[180:183], v203 offset:2048
	ds_read_b128 v[184:187], v203 offset:3072
	ds_read_b128 v[204:207], v203 offset:4096
	ds_read_b128 v[208:211], v203 offset:5120
	ds_read_b128 v[212:215], v203 offset:6144
	ds_read_b128 v[216:219], v203 offset:7168
	global_load_lds_dwordx4 v[198:199], off
	v_lshl_add_u64 v[198:199], s[6:7], 0, v[170:171]
	s_add_i32 m0, s31, 0xe000
	s_nop 0
	global_load_lds_dwordx4 v[198:199], off
	s_waitcnt vmcnt(8)
	s_waitcnt lgkmcnt(0)
	s_barrier
	v_mfma_f32_16x16x32_bf16 v[124:127], v[128:131], v[172:175], v[124:127]
	v_mfma_f32_16x16x32_bf16 v[120:123], v[136:139], v[172:175], v[120:123]
	v_mfma_f32_16x16x32_bf16 v[116:119], v[128:131], v[180:183], v[116:119]
	v_mfma_f32_16x16x32_bf16 v[112:115], v[136:139], v[180:183], v[112:115]
	v_mfma_f32_16x16x32_bf16 v[108:111], v[128:131], v[204:207], v[108:111]
	v_mfma_f32_16x16x32_bf16 v[104:107], v[136:139], v[204:207], v[104:107]
	v_mfma_f32_16x16x32_bf16 v[100:103], v[128:131], v[212:215], v[100:103]
	v_mfma_f32_16x16x32_bf16 v[96:99], v[136:139], v[212:215], v[96:99]
	v_mfma_f32_16x16x32_bf16 v[124:127], v[132:135], v[176:179], v[124:127]
	v_mfma_f32_16x16x32_bf16 v[120:123], v[140:143], v[176:179], v[120:123]
	v_mfma_f32_16x16x32_bf16 v[116:119], v[132:135], v[184:187], v[116:119]
	v_mfma_f32_16x16x32_bf16 v[112:115], v[140:143], v[184:187], v[112:115]
	v_mfma_f32_16x16x32_bf16 v[108:111], v[132:135], v[208:211], v[108:111]
	v_mfma_f32_16x16x32_bf16 v[104:107], v[140:143], v[208:211], v[104:107]
	v_mfma_f32_16x16x32_bf16 v[100:103], v[132:135], v[216:219], v[100:103]
	v_mfma_f32_16x16x32_bf16 v[96:99], v[140:143], v[216:219], v[96:99]
	v_mfma_f32_16x16x32_bf16 v[92:95], v[144:147], v[172:175], v[92:95]
	v_mfma_f32_16x16x32_bf16 v[88:91], v[152:155], v[172:175], v[88:91]
	v_mfma_f32_16x16x32_bf16 v[84:87], v[144:147], v[180:183], v[84:87]
	v_mfma_f32_16x16x32_bf16 v[80:83], v[152:155], v[180:183], v[80:83]
	v_mfma_f32_16x16x32_bf16 v[76:79], v[144:147], v[204:207], v[76:79]
	v_mfma_f32_16x16x32_bf16 v[72:75], v[152:155], v[204:207], v[72:75]
	v_mfma_f32_16x16x32_bf16 v[68:71], v[144:147], v[212:215], v[68:71]
	v_mfma_f32_16x16x32_bf16 v[64:67], v[152:155], v[212:215], v[64:67]
	v_mfma_f32_16x16x32_bf16 v[92:95], v[148:151], v[176:179], v[92:95]
	v_mfma_f32_16x16x32_bf16 v[88:91], v[156:159], v[176:179], v[88:91]
	v_mfma_f32_16x16x32_bf16 v[84:87], v[148:151], v[184:187], v[84:87]
	v_mfma_f32_16x16x32_bf16 v[80:83], v[156:159], v[184:187], v[80:83]
	v_mfma_f32_16x16x32_bf16 v[76:79], v[148:151], v[208:211], v[76:79]
	v_mfma_f32_16x16x32_bf16 v[72:75], v[156:159], v[208:211], v[72:75]
	v_mfma_f32_16x16x32_bf16 v[68:71], v[148:151], v[216:219], v[68:71]
	v_mfma_f32_16x16x32_bf16 v[64:67], v[156:159], v[216:219], v[64:67]
	s_barrier
	s_add_i32 s60, s60, s30
	v_lshl_add_u64 v[198:199], s[8:9], 0, v[164:165]
	s_mov_b32 m0, s60
	ds_read_b128 v[172:175], v203 offset:16384
	ds_read_b128 v[176:179], v203 offset:17408
	ds_read_b128 v[180:183], v203 offset:18432
	ds_read_b128 v[184:187], v203 offset:19456
	ds_read_b128 v[204:207], v203 offset:20480
	ds_read_b128 v[208:211], v203 offset:21504
	ds_read_b128 v[212:215], v203 offset:22528
	ds_read_b128 v[216:219], v203 offset:23552
	global_load_lds_dwordx4 v[198:199], off
	s_add_i32 m0, s60, 0x2000
	s_add_u32 s60, s8, 0x40000
	v_lshl_add_u64 v[220:221], s[8:9], 0, v[160:161]
	s_addc_u32 s61, s9, 0
	s_add_i32 s62, s62, s30
	global_load_lds_dwordx4 v[220:221], off
	v_lshl_add_u64 v[222:223], s[60:61], 0, v[164:165]
	s_mov_b32 m0, s62
	v_lshl_add_u64 v[224:225], s[24:25], 0, v[162:163]
	global_load_lds_dwordx4 v[222:223], off
	v_lshl_add_u64 v[222:223], s[60:61], 0, v[160:161]
	s_add_i32 m0, s62, 0x2000
	s_nop 0
	global_load_lds_dwordx4 v[222:223], off
	v_lshl_add_u64 v[222:223], s[24:25], 0, v[166:167]
	s_mov_b32 m0, s31
	s_nop 0
	global_load_lds_dwordx4 v[222:223], off
	s_mov_b32 m0, s34
	s_nop 0
	global_load_lds_dwordx4 v[224:225], off
	s_waitcnt vmcnt(8)
	s_waitcnt lgkmcnt(0)
	s_barrier
; #define PG8_STAGE(bufoff, gbase, voff) do { _Pragma("unroll") for (int _i = 0; _i < 2; ++_i) \
;         __builtin_amdgcn_global_load_lds((const unsigned*)((const char*)(gbase) + (voff)[_i]), (PG8_LAS unsigned*)(lds + (bufoff) + ldsw + _i * 8192), 16, 0, 0); } while (0)
; #define PG8_LDA(dst, b, h) do { _Pragma("unroll") for (int m = 0; m < 4; ++m) _Pragma("unroll") for (int k = 0; k < 2; ++k) dst[m][k] = *(const PG8_LAS bf16x8*)(lds + PG8_SA(b, h) + aoff + m * 2048 + k * 1024); } while (0)
; #define PG8_LDB(dst, b, h) do { _Pragma("unroll") for (int n = 0; n < 2; ++n) _Pragma("unroll") for (int k = 0; k < 2; ++k) dst[n][k] = *(const PG8_LAS bf16x8*)(lds + PG8_SB(b, h) + boff + n * 2048 + k * 1024); } while (0)
; #define PG8_MMA(ai, bj, At, Bt) do { __builtin_amdgcn_s_setprio(1); _Pragma("unroll") for (int m = 0; m < 4; ++m) _Pragma("unroll") for (int n = 0; n < 2; ++n) _Pragma("unroll") for (int k = 0; k < 2; ++k) \
;         acc[ai][bj][m][n] = __builtin_amdgcn_mfma_f32_16x16x32_bf16(Bt[n][k], At[m][k], acc[ai][bj][m][n], 0, 0, 0); __builtin_amdgcn_s_setprio(0); } while (0)
; #define PG8_WAIT_V(n) asm volatile("s_waitcnt vmcnt(" #n ")" ::: "memory")
; #define PG8_WAIT_L(n) asm volatile("s_waitcnt lgkmcnt(" #n ")" ::: "memory")
; #define PG8_BAR __builtin_amdgcn_s_barrier()
; #define PG8_SCHED __builtin_amdgcn_sched_barrier(0)
; template <class Epi, class Sched, bool ALIGN_EPI = false, bool SP2 = false>
; __device__ __forceinline__ void gemm_phase(PG8_LAS unsigned char* lds, const Gemm g, const Sched& S, const Epi& E) {
;     ...
;             PG8_WAIT_V(8); PG8_WAIT_L(0); PG8_BAR; PG8_MMA(1, 0, At, B0); PG8_MMA(1, 1, At, B1); PG8_BAR; PG8_SCHED;
;             PG8_LDB(B0, 1, 0); PG8_LDB(B1, 1, 1); PG8_SCHED; PG8_LDA(At, 1, 0); PG8_STAGE(PG8_SA(0, 1), a2 + hstep, voffA);
;             PG8_WAIT_V(8); PG8_WAIT_L(0); PG8_BAR; PG8_MMA(0, 0, At, B0); PG8_MMA(0, 1, At, B1); PG8_BAR; PG8_SCHED;
	v_mfma_f32_16x16x32_bf16 v[60:63], v[128:131], v[172:175], v[60:63]
	v_mfma_f32_16x16x32_bf16 v[56:59], v[136:139], v[172:175], v[56:59]
	v_mfma_f32_16x16x32_bf16 v[52:55], v[128:131], v[180:183], v[52:55]
	v_mfma_f32_16x16x32_bf16 v[48:51], v[136:139], v[180:183], v[48:51]
	v_mfma_f32_16x16x32_bf16 v[44:47], v[128:131], v[204:207], v[44:47]
	v_mfma_f32_16x16x32_bf16 v[40:43], v[136:139], v[204:207], v[40:43]
	v_mfma_f32_16x16x32_bf16 v[36:39], v[128:131], v[212:215], v[36:39]
	v_mfma_f32_16x16x32_bf16 v[32:35], v[136:139], v[212:215], v[32:35]
	v_mfma_f32_16x16x32_bf16 v[60:63], v[132:135], v[176:179], v[60:63]
	v_mfma_f32_16x16x32_bf16 v[56:59], v[140:143], v[176:179], v[56:59]
	v_mfma_f32_16x16x32_bf16 v[52:55], v[132:135], v[184:187], v[52:55]
	v_mfma_f32_16x16x32_bf16 v[48:51], v[140:143], v[184:187], v[48:51]
	v_mfma_f32_16x16x32_bf16 v[44:47], v[132:135], v[208:211], v[44:47]
	v_mfma_f32_16x16x32_bf16 v[40:43], v[140:143], v[208:211], v[40:43]
	v_mfma_f32_16x16x32_bf16 v[36:39], v[132:135], v[216:219], v[36:39]
	v_mfma_f32_16x16x32_bf16 v[32:35], v[140:143], v[216:219], v[32:35]
	v_mfma_f32_16x16x32_bf16 v[28:31], v[144:147], v[172:175], v[28:31]
	v_mfma_f32_16x16x32_bf16 v[24:27], v[152:155], v[172:175], v[24:27]
	v_mfma_f32_16x16x32_bf16 v[20:23], v[144:147], v[180:183], v[20:23]
	v_mfma_f32_16x16x32_bf16 v[16:19], v[152:155], v[180:183], v[16:19]
	v_mfma_f32_16x16x32_bf16 v[12:15], v[144:147], v[204:207], v[12:15]
	v_mfma_f32_16x16x32_bf16 v[8:11], v[152:155], v[204:207], v[8:11]
	v_mfma_f32_16x16x32_bf16 v[4:7], v[144:147], v[212:215], v[4:7]
	v_mfma_f32_16x16x32_bf16 v[0:3], v[152:155], v[212:215], v[0:3]
	v_mfma_f32_16x16x32_bf16 v[28:31], v[148:151], v[176:179], v[28:31]
	v_mfma_f32_16x16x32_bf16 v[24:27], v[156:159], v[176:179], v[24:27]
	v_mfma_f32_16x16x32_bf16 v[20:23], v[148:151], v[184:187], v[20:23]
	v_mfma_f32_16x16x32_bf16 v[16:19], v[156:159], v[184:187], v[16:19]
	v_mfma_f32_16x16x32_bf16 v[12:15], v[148:151], v[208:211], v[12:15]
	v_mfma_f32_16x16x32_bf16 v[8:11], v[156:159], v[208:211], v[8:11]
	v_mfma_f32_16x16x32_bf16 v[4:7], v[148:151], v[216:219], v[4:7]
	v_mfma_f32_16x16x32_bf16 v[0:3], v[156:159], v[216:219], v[0:3]
	s_barrier
	s_add_i32 s60, 0, 0x18000
	s_add_i32 s61, 0, 0x1c000
	v_add_u32_e32 v140, s60, v201
	v_add_u32_e32 v156, s61, v201
	ds_read_b128 v[128:131], v140
	ds_read_b128 v[132:135], v140 offset:1024
	ds_read_b128 v[136:139], v140 offset:2048
	ds_read_b128 v[140:143], v140 offset:3072
	ds_read_b128 v[144:147], v156
	ds_read_b128 v[148:151], v156 offset:1024
	ds_read_b128 v[152:155], v156 offset:2048
	ds_read_b128 v[156:159], v156 offset:3072
	s_add_u32 s24, s24, 0x40000
	s_addc_u32 s25, s25, 0
	s_mov_b32 m0, s35
	v_lshl_add_u64 v[226:227], s[24:25], 0, v[166:167]
	ds_read_b128 v[172:175], v203 offset:32768
	ds_read_b128 v[176:179], v203 offset:33792
	ds_read_b128 v[180:183], v203 offset:34816
	ds_read_b128 v[184:187], v203 offset:35840
	ds_read_b128 v[204:207], v203 offset:36864
	ds_read_b128 v[208:211], v203 offset:37888
	ds_read_b128 v[212:215], v203 offset:38912
	ds_read_b128 v[216:219], v203 offset:39936
	global_load_lds_dwordx4 v[226:227], off
	v_lshl_add_u64 v[226:227], s[24:25], 0, v[162:163]
	s_mov_b32 m0, s36
	s_nop 0
	global_load_lds_dwordx4 v[226:227], off
	s_waitcnt vmcnt(8)
	s_waitcnt lgkmcnt(0)
	s_barrier
	v_mfma_f32_16x16x32_bf16 v[124:127], v[128:131], v[172:175], v[124:127]
	v_mfma_f32_16x16x32_bf16 v[120:123], v[136:139], v[172:175], v[120:123]
	v_mfma_f32_16x16x32_bf16 v[116:119], v[128:131], v[180:183], v[116:119]
	v_mfma_f32_16x16x32_bf16 v[112:115], v[136:139], v[180:183], v[112:115]
	v_mfma_f32_16x16x32_bf16 v[108:111], v[128:131], v[204:207], v[108:111]
	v_mfma_f32_16x16x32_bf16 v[104:107], v[136:139], v[204:207], v[104:107]
	v_mfma_f32_16x16x32_bf16 v[100:103], v[128:131], v[212:215], v[100:103]
	v_mfma_f32_16x16x32_bf16 v[96:99], v[136:139], v[212:215], v[96:99]
	v_mfma_f32_16x16x32_bf16 v[124:127], v[132:135], v[176:179], v[124:127]
	v_mfma_f32_16x16x32_bf16 v[120:123], v[140:143], v[176:179], v[120:123]
	v_mfma_f32_16x16x32_bf16 v[116:119], v[132:135], v[184:187], v[116:119]
	v_mfma_f32_16x16x32_bf16 v[112:115], v[140:143], v[184:187], v[112:115]
	v_mfma_f32_16x16x32_bf16 v[108:111], v[132:135], v[208:211], v[108:111]
	v_mfma_f32_16x16x32_bf16 v[104:107], v[140:143], v[208:211], v[104:107]
	v_mfma_f32_16x16x32_bf16 v[100:103], v[132:135], v[216:219], v[100:103]
	v_mfma_f32_16x16x32_bf16 v[96:99], v[140:143], v[216:219], v[96:99]
	v_mfma_f32_16x16x32_bf16 v[92:95], v[144:147], v[172:175], v[92:95]
	v_mfma_f32_16x16x32_bf16 v[88:91], v[152:155], v[172:175], v[88:91]
	v_mfma_f32_16x16x32_bf16 v[84:87], v[144:147], v[180:183], v[84:87]
	v_mfma_f32_16x16x32_bf16 v[80:83], v[152:155], v[180:183], v[80:83]
	v_mfma_f32_16x16x32_bf16 v[76:79], v[144:147], v[204:207], v[76:79]
	v_mfma_f32_16x16x32_bf16 v[72:75], v[152:155], v[204:207], v[72:75]
	v_mfma_f32_16x16x32_bf16 v[68:71], v[144:147], v[212:215], v[68:71]
	v_mfma_f32_16x16x32_bf16 v[64:67], v[152:155], v[212:215], v[64:67]
	v_mfma_f32_16x16x32_bf16 v[92:95], v[148:151], v[176:179], v[92:95]
	v_mfma_f32_16x16x32_bf16 v[88:91], v[156:159], v[176:179], v[88:91]
	v_mfma_f32_16x16x32_bf16 v[84:87], v[148:151], v[184:187], v[84:87]
	v_mfma_f32_16x16x32_bf16 v[80:83], v[156:159], v[184:187], v[80:83]
	v_mfma_f32_16x16x32_bf16 v[76:79], v[148:151], v[208:211], v[76:79]
	v_mfma_f32_16x16x32_bf16 v[72:75], v[156:159], v[208:211], v[72:75]
	v_mfma_f32_16x16x32_bf16 v[68:71], v[148:151], v[216:219], v[68:71]
	v_mfma_f32_16x16x32_bf16 v[64:67], v[156:159], v[216:219], v[64:67]
	s_barrier
; #define PG8_STAGE(bufoff, gbase, voff) do { _Pragma("unroll") for (int _i = 0; _i < 2; ++_i) \
;         __builtin_amdgcn_global_load_lds((const unsigned*)((const char*)(gbase) + (voff)[_i]), (PG8_LAS unsigned*)(lds + (bufoff) + ldsw + _i * 8192), 16, 0, 0); } while (0)
; #define PG8_LDA(dst, b, h) do { _Pragma("unroll") for (int m = 0; m < 4; ++m) _Pragma("unroll") for (int k = 0; k < 2; ++k) dst[m][k] = *(const PG8_LAS bf16x8*)(lds + PG8_SA(b, h) + aoff + m * 2048 + k * 1024); } while (0)
; #define PG8_MMA(ai, bj, At, Bt) do { __builtin_amdgcn_s_setprio(1); _Pragma("unroll") for (int m = 0; m < 4; ++m) _Pragma("unroll") for (int n = 0; n < 2; ++n) _Pragma("unroll") for (int k = 0; k < 2; ++k) \
;         acc[ai][bj][m][n] = __builtin_amdgcn_mfma_f32_16x16x32_bf16(Bt[n][k], At[m][k], acc[ai][bj][m][n], 0, 0, 0); __builtin_amdgcn_s_setprio(0); } while (0)
; #define PG8_WAIT_V(n) asm volatile("s_waitcnt vmcnt(" #n ")" ::: "memory")
; #define PG8_WAIT_L(n) asm volatile("s_waitcnt lgkmcnt(" #n ")" ::: "memory")
; #define PG8_BAR __builtin_amdgcn_s_barrier()
; #define PG8_SCHED __builtin_amdgcn_sched_barrier(0)
; template <class Epi, class Sched, bool ALIGN_EPI = false, bool SP2 = false>
; __device__ __forceinline__ void gemm_phase(PG8_LAS unsigned char* lds, const Gemm g, const Sched& S, const Epi& E) {
;     ...
;             PG8_LDA(At, 1, 1); PG8_STAGE(PG8_SB(1, 0), b3, voffB); PG8_STAGE(PG8_SB(1, 1), b3 + hstep, voffB); PG8_STAGE(PG8_SA(1, 0), a3, voffA);
;             PG8_WAIT_V(8); PG8_WAIT_L(0); PG8_BAR; PG8_MMA(1, 0, At, B0); PG8_MMA(1, 1, At, B1); PG8_BAR; PG8_SCHED;
;     ...
;         if constexpr (ALIGN_EPI) { if (wr == 0) PG8_BAR; }
	s_add_i32 s24, s60, s30
	v_lshl_add_u64 v[198:199], v[198:199], 0, s[78:79]
	s_mov_b32 m0, s24
	ds_read_b128 v[172:175], v203 offset:49152
	ds_read_b128 v[176:179], v203 offset:50176
	ds_read_b128 v[180:183], v203 offset:51200
	ds_read_b128 v[184:187], v203 offset:52224
	ds_read_b128 v[204:207], v203 offset:53248
	ds_read_b128 v[208:211], v203 offset:54272
	ds_read_b128 v[212:215], v203 offset:55296
	ds_read_b128 v[216:219], v203 offset:56320
	global_load_lds_dwordx4 v[198:199], off
	s_add_i32 m0, s24, 0x2000
	s_add_u32 s8, s8, 0x40080
	v_lshl_add_u64 v[198:199], v[220:221], 0, s[78:79]
	s_addc_u32 s9, s9, 0
	s_add_i32 s24, s61, s30
	global_load_lds_dwordx4 v[198:199], off
	v_lshl_add_u64 v[198:199], s[8:9], 0, v[164:165]
	s_mov_b32 m0, s24
	s_nop 0
	global_load_lds_dwordx4 v[198:199], off
	v_lshl_add_u64 v[198:199], s[8:9], 0, v[160:161]
	s_add_i32 m0, s24, 0x2000
	s_nop 0
	global_load_lds_dwordx4 v[198:199], off
	v_lshl_add_u64 v[198:199], v[222:223], 0, s[78:79]
	s_mov_b32 m0, s37
	s_nop 0
	global_load_lds_dwordx4 v[198:199], off
	v_lshl_add_u64 v[198:199], v[224:225], 0, s[78:79]
	s_mov_b32 m0, s40
	s_nop 0
	global_load_lds_dwordx4 v[198:199], off
	s_waitcnt vmcnt(8)
	s_waitcnt lgkmcnt(0)
	s_barrier
	v_mfma_f32_16x16x32_bf16 v[60:63], v[128:131], v[172:175], v[60:63]
	v_mfma_f32_16x16x32_bf16 v[56:59], v[136:139], v[172:175], v[56:59]
	v_mfma_f32_16x16x32_bf16 v[52:55], v[128:131], v[180:183], v[52:55]
	v_mfma_f32_16x16x32_bf16 v[48:51], v[136:139], v[180:183], v[48:51]
	v_mfma_f32_16x16x32_bf16 v[44:47], v[128:131], v[204:207], v[44:47]
	v_mfma_f32_16x16x32_bf16 v[40:43], v[136:139], v[204:207], v[40:43]
	v_mfma_f32_16x16x32_bf16 v[36:39], v[128:131], v[212:215], v[36:39]
	v_mfma_f32_16x16x32_bf16 v[32:35], v[136:139], v[212:215], v[32:35]
	v_mfma_f32_16x16x32_bf16 v[60:63], v[132:135], v[176:179], v[60:63]
	v_mfma_f32_16x16x32_bf16 v[56:59], v[140:143], v[176:179], v[56:59]
	v_mfma_f32_16x16x32_bf16 v[52:55], v[132:135], v[184:187], v[52:55]
	v_mfma_f32_16x16x32_bf16 v[48:51], v[140:143], v[184:187], v[48:51]
	v_mfma_f32_16x16x32_bf16 v[44:47], v[132:135], v[208:211], v[44:47]
	v_mfma_f32_16x16x32_bf16 v[40:43], v[140:143], v[208:211], v[40:43]
	v_mfma_f32_16x16x32_bf16 v[36:39], v[132:135], v[216:219], v[36:39]
	v_mfma_f32_16x16x32_bf16 v[32:35], v[140:143], v[216:219], v[32:35]
	v_mfma_f32_16x16x32_bf16 v[28:31], v[144:147], v[172:175], v[28:31]
	v_mfma_f32_16x16x32_bf16 v[24:27], v[152:155], v[172:175], v[24:27]
	v_mfma_f32_16x16x32_bf16 v[20:23], v[144:147], v[180:183], v[20:23]
	v_mfma_f32_16x16x32_bf16 v[16:19], v[152:155], v[180:183], v[16:19]
	v_mfma_f32_16x16x32_bf16 v[12:15], v[144:147], v[204:207], v[12:15]
	v_mfma_f32_16x16x32_bf16 v[8:11], v[152:155], v[204:207], v[8:11]
	v_mfma_f32_16x16x32_bf16 v[4:7], v[144:147], v[212:215], v[4:7]
	v_mfma_f32_16x16x32_bf16 v[0:3], v[152:155], v[212:215], v[0:3]
	v_mfma_f32_16x16x32_bf16 v[28:31], v[148:151], v[176:179], v[28:31]
	v_mfma_f32_16x16x32_bf16 v[24:27], v[156:159], v[176:179], v[24:27]
	v_mfma_f32_16x16x32_bf16 v[20:23], v[148:151], v[184:187], v[20:23]
	v_mfma_f32_16x16x32_bf16 v[16:19], v[156:159], v[184:187], v[16:19]
	v_mfma_f32_16x16x32_bf16 v[12:15], v[148:151], v[208:211], v[12:15]
	v_mfma_f32_16x16x32_bf16 v[8:11], v[156:159], v[208:211], v[8:11]
	v_mfma_f32_16x16x32_bf16 v[4:7], v[148:151], v[216:219], v[4:7]
	v_mfma_f32_16x16x32_bf16 v[0:3], v[156:159], v[216:219], v[0:3]
	s_barrier
	s_add_i32 s58, s58, 2
	s_add_u32 s6, s6, 0x100
	s_addc_u32 s7, s7, 0
	s_add_u32 s45, s45, 0x100
	s_addc_u32 s52, s52, 0
	s_cmp_gt_u32 s58, 13
	s_cbranch_scc0 .LBB0_424
	s_setprio 0
	s_and_b64 vcc, exec, s[14:15]
	s_cbranch_vccz .LBB0_427
	s_barrier

;     __device__ __forceinline__ bool next(int i, Unit& u) const { Unit t; if (!so.next(i / 3, t)) return false; const int br = i % 3; u.pm = t.pm + br * so.nM; u.pn = t.pn + br * so.nN; return true; }
;     __device__ __forceinline__ bool zero_after(const Unit& u) const { return (u.pn / nN) == 2; }
; #define PG8_STAGE(bufoff, gbase, voff) do { _Pragma("unroll") for (int _i = 0; _i < 2; ++_i) \
;         __builtin_amdgcn_global_load_lds((const unsigned*)((const char*)(gbase) + (voff)[_i]), (PG8_LAS unsigned*)(lds + (bufoff) + ldsw + _i * 8192), 16, 0, 0); } while (0)
; #define PG8_LDA(dst, b, h) do { _Pragma("unroll") for (int m = 0; m < 4; ++m) _Pragma("unroll") for (int k = 0; k < 2; ++k) dst[m][k] = *(const PG8_LAS bf16x8*)(lds + PG8_SA(b, h) + aoff + m * 2048 + k * 1024); } while (0)
; #define PG8_LDB(dst, b, h) do { _Pragma("unroll") for (int n = 0; n < 2; ++n) _Pragma("unroll") for (int k = 0; k < 2; ++k) dst[n][k] = *(const PG8_LAS bf16x8*)(lds + PG8_SB(b, h) + boff + n * 2048 + k * 1024); } while (0)
; template <class Epi, class Sched, bool ALIGN_EPI = false, bool SP2 = false>
; __device__ __forceinline__ void gemm_phase(PG8_LAS unsigned char* lds, const Gemm g, const Sched& S, const Epi& E) {
;     ...
;         const bool has_next = S.next(ui + 1, nxt);
;         const char* nA = has_next ? (const char*)g.A + (size_t)nxt.pm * tstep : cA; const char* nB = has_next ? (const char*)g.Bt + (size_t)nxt.pn * tstep : cB;
;         for (int t = 0; t < nt; t += 2) {
;             const bool last = (t == nt - 2);
;             const char* a1 = cA + (size_t)(t + 1) * kstep;
;             const char* a2 = last ? nA : cA + (size_t)(t + 2) * kstep; const char* b2 = last ? nB : cB + (size_t)(t + 2) * kstep;
;             const char* a3 = a2 + kstep; const char* b3 = b2 + kstep;
;             if (last && has_next) S.a_ready(nxt);
;             if constexpr (SP2) {
;             PG8_LDB(B0, 0, 0); PG8_LDB(B1, 0, 1); PG8_SCHED; PG8_LDA(At, 0, 0); PG8_STAGE(PG8_SA(1, 1), a1 + hstep, voffA);
;     ...
;         if (E.zero_after(cur)) {
; #pragma unroll
;         for (int a = 0; a < 2; ++a)
; #pragma unroll
;             for (int b = 0; b < 2; ++b)
; #pragma unroll
;                 for (int m = 0; m < 4; ++m)
; #pragma unroll
;                     for (int n = 0; n < 2; ++n) acc[a][b][m][n] = (f32x4){0.f, 0.f, 0.f, 0.f};
;         }
;         cur = nxt; cA = nA; cB = nB; ++ui;
.LBB0_595:
	s_ashr_i32 s19, s18, 31
	s_lshl_b64 s[20:21], s[18:19], 20
	s_add_u32 s20, s2, s20
	s_addc_u32 s21, s30, s21
	s_and_b64 s[22:23], s[8:9], exec
	s_cselect_b32 s19, s21, s25
	s_cselect_b32 s58, s20, s24
	s_ashr_i32 s17, s16, 31
	s_lshl_b64 s[22:23], s[16:17], 20
	s_add_u32 s22, s31, s22
	s_addc_u32 s23, s34, s23
	s_and_b64 s[28:29], s[8:9], exec
	s_cselect_b32 s17, s23, s27
	s_cselect_b32 s62, s22, s26
	s_add_u32 s24, s24, 0x80080
	s_addc_u32 s25, s25, 0
	s_add_u32 s63, s26, 0x100
	v_mov_b32_e32 v0, 0
	s_addc_u32 s66, s27, 0
	s_mov_b32 s67, -2
	v_mov_b32_e32 v1, v0
	v_mov_b32_e32 v2, v0
	v_mov_b32_e32 v3, v0
	v_mov_b32_e32 v4, v0
	v_mov_b32_e32 v5, v0
	v_mov_b32_e32 v6, v0
	v_mov_b32_e32 v7, v0
	v_mov_b32_e32 v16, v0
	v_mov_b32_e32 v17, v0
	v_mov_b32_e32 v18, v0
	v_mov_b32_e32 v19, v0
	v_mov_b32_e32 v20, v0
	v_mov_b32_e32 v21, v0
	v_mov_b32_e32 v22, v0
	v_mov_b32_e32 v23, v0
	v_mov_b32_e32 v32, v0
	v_mov_b32_e32 v33, v0
	v_mov_b32_e32 v34, v0
	v_mov_b32_e32 v35, v0
	v_mov_b32_e32 v36, v0
	v_mov_b32_e32 v37, v0
	v_mov_b32_e32 v38, v0
	v_mov_b32_e32 v39, v0
	v_mov_b32_e32 v48, v0
	v_mov_b32_e32 v49, v0
	v_mov_b32_e32 v50, v0
	v_mov_b32_e32 v51, v0
	v_mov_b32_e32 v52, v0
	v_mov_b32_e32 v53, v0
	v_mov_b32_e32 v54, v0
	v_mov_b32_e32 v55, v0
	v_mov_b32_e32 v8, v0
	v_mov_b32_e32 v9, v0
	v_mov_b32_e32 v10, v0
	v_mov_b32_e32 v11, v0
	v_mov_b32_e32 v12, v0
	v_mov_b32_e32 v13, v0
	v_mov_b32_e32 v14, v0
	v_mov_b32_e32 v15, v0
	v_mov_b32_e32 v24, v0
	v_mov_b32_e32 v25, v0
	v_mov_b32_e32 v26, v0
	v_mov_b32_e32 v27, v0
	v_mov_b32_e32 v28, v0
	v_mov_b32_e32 v29, v0
	v_mov_b32_e32 v30, v0
	v_mov_b32_e32 v31, v0
	v_mov_b32_e32 v40, v0
	v_mov_b32_e32 v41, v0
	v_mov_b32_e32 v42, v0
	v_mov_b32_e32 v43, v0
	v_mov_b32_e32 v44, v0
	v_mov_b32_e32 v45, v0
	v_mov_b32_e32 v46, v0
	v_mov_b32_e32 v47, v0
	v_mov_b32_e32 v56, v0
	v_mov_b32_e32 v57, v0
	v_mov_b32_e32 v58, v0
	v_mov_b32_e32 v59, v0
	v_mov_b32_e32 v60, v0
	v_mov_b32_e32 v61, v0
	v_mov_b32_e32 v62, v0
	v_mov_b32_e32 v63, v0
	v_mov_b32_e32 v64, v0
	v_mov_b32_e32 v65, v0
	v_mov_b32_e32 v66, v0
	v_mov_b32_e32 v67, v0
	v_mov_b32_e32 v68, v0
	v_mov_b32_e32 v69, v0
	v_mov_b32_e32 v70, v0
	v_mov_b32_e32 v71, v0
	v_mov_b32_e32 v80, v0
	v_mov_b32_e32 v81, v0
	v_mov_b32_e32 v82, v0
	v_mov_b32_e32 v83, v0
	v_mov_b32_e32 v84, v0
	v_mov_b32_e32 v85, v0
	v_mov_b32_e32 v86, v0
	v_mov_b32_e32 v87, v0
	v_mov_b32_e32 v96, v0
	v_mov_b32_e32 v97, v0
	v_mov_b32_e32 v98, v0
	v_mov_b32_e32 v99, v0
	v_mov_b32_e32 v100, v0
	v_mov_b32_e32 v101, v0
	v_mov_b32_e32 v102, v0
	v_mov_b32_e32 v103, v0
	v_mov_b32_e32 v128, v0
	v_mov_b32_e32 v129, v0
	v_mov_b32_e32 v130, v0
	v_mov_b32_e32 v131, v0
	v_mov_b32_e32 v136, v0
	v_mov_b32_e32 v137, v0
	v_mov_b32_e32 v138, v0
	v_mov_b32_e32 v139, v0
	v_mov_b32_e32 v72, v0
	v_mov_b32_e32 v73, v0
	v_mov_b32_e32 v74, v0
	v_mov_b32_e32 v75, v0
	v_mov_b32_e32 v76, v0
	v_mov_b32_e32 v77, v0
	v_mov_b32_e32 v78, v0
	v_mov_b32_e32 v79, v0
	v_mov_b32_e32 v88, v0
	v_mov_b32_e32 v89, v0
	v_mov_b32_e32 v90, v0
	v_mov_b32_e32 v91, v0
	v_mov_b32_e32 v92, v0
	v_mov_b32_e32 v93, v0
	v_mov_b32_e32 v94, v0
	v_mov_b32_e32 v95, v0
	v_mov_b32_e32 v104, v0
	v_mov_b32_e32 v105, v0
	v_mov_b32_e32 v106, v0
	v_mov_b32_e32 v107, v0
	v_mov_b32_e32 v108, v0
	v_mov_b32_e32 v109, v0
	v_mov_b32_e32 v110, v0
	v_mov_b32_e32 v111, v0
	v_mov_b32_e32 v152, v0
	v_mov_b32_e32 v153, v0
	v_mov_b32_e32 v154, v0
	v_mov_b32_e32 v155, v0
	v_mov_b32_e32 v160, v0
	v_mov_b32_e32 v161, v0
	v_mov_b32_e32 v162, v0
	v_mov_b32_e32 v163, v0
	s_cmp_eq_u64 s[14:15], 0
	s_cbranch_scc0 .Lprio_skip_596
	s_setprio 1
.Lprio_skip_596:
.LBB0_596:
	s_add_u32 s26, s24, 0xfff80080
	s_addc_u32 s27, s25, -1
	s_add_i32 s60, 0, 0x10000
	s_cmp_eq_u32 s67, 28
	s_cselect_b32 s29, s19, s27
	s_cselect_b32 s28, s58, s26
	s_cselect_b32 s27, s17, s66
	s_cselect_b32 s26, s62, s63
	s_add_i32 s68, 0, 0x14000
	v_add_u32_e32 v124, s60, v239
	v_add_u32_e32 v148, s68, v239
	ds_read_b128 v[112:115], v124
	ds_read_b128 v[116:119], v124 offset:1024
	ds_read_b128 v[120:123], v124 offset:2048
	ds_read_b128 v[124:127], v124 offset:3072
	ds_read_b128 v[132:135], v148
	ds_read_b128 v[140:143], v148 offset:1024
	ds_read_b128 v[144:147], v148 offset:2048
	ds_read_b128 v[148:151], v148 offset:3072
	v_lshl_add_u64 v[212:213], s[24:25], 0, v[204:205]
	s_add_i32 m0, s36, 0xc000
	ds_read_b128 v[156:159], v241
	ds_read_b128 v[164:167], v241 offset:1024
	ds_read_b128 v[168:171], v241 offset:2048
	ds_read_b128 v[172:175], v241 offset:3072
	ds_read_b128 v[176:179], v241 offset:4096
	ds_read_b128 v[180:183], v241 offset:5120
	ds_read_b128 v[184:187], v241 offset:6144
	ds_read_b128 v[208:211], v241 offset:7168
	global_load_lds_dwordx4 v[212:213], off
	v_lshl_add_u64 v[212:213], s[24:25], 0, v[206:207]
	s_add_i32 m0, s36, 0xe000
	s_nop 0
	global_load_lds_dwordx4 v[212:213], off
	s_waitcnt vmcnt(8)
	s_waitcnt lgkmcnt(0)
	s_barrier
; #define PG8_STAGE(bufoff, gbase, voff) do { _Pragma("unroll") for (int _i = 0; _i < 2; ++_i) \
;         __builtin_amdgcn_global_load_lds((const unsigned*)((const char*)(gbase) + (voff)[_i]), (PG8_LAS unsigned*)(lds + (bufoff) + ldsw + _i * 8192), 16, 0, 0); } while (0)
; #define PG8_LDA(dst, b, h) do { _Pragma("unroll") for (int m = 0; m < 4; ++m) _Pragma("unroll") for (int k = 0; k < 2; ++k) dst[m][k] = *(const PG8_LAS bf16x8*)(lds + PG8_SA(b, h) + aoff + m * 2048 + k * 1024); } while (0)
; #define PG8_MMA(ai, bj, At, Bt) do { __builtin_amdgcn_s_setprio(1); _Pragma("unroll") for (int m = 0; m < 4; ++m) _Pragma("unroll") for (int n = 0; n < 2; ++n) _Pragma("unroll") for (int k = 0; k < 2; ++k) \
;         acc[ai][bj][m][n] = __builtin_amdgcn_mfma_f32_16x16x32_bf16(Bt[n][k], At[m][k], acc[ai][bj][m][n], 0, 0, 0); __builtin_amdgcn_s_setprio(0); } while (0)
; #define PG8_WAIT_V(n) asm volatile("s_waitcnt vmcnt(" #n ")" ::: "memory")
; #define PG8_WAIT_L(n) asm volatile("s_waitcnt lgkmcnt(" #n ")" ::: "memory")
; #define PG8_BAR __builtin_amdgcn_s_barrier()
; #define PG8_SCHED __builtin_amdgcn_sched_barrier(0)
; template <class Epi, class Sched, bool ALIGN_EPI = false, bool SP2 = false>
; __device__ __forceinline__ void gemm_phase(PG8_LAS unsigned char* lds, const Gemm g, const Sched& S, const Epi& E) {
;     ...
;             PG8_WAIT_V(8); PG8_WAIT_L(0); PG8_BAR; PG8_MMA(0, 0, At, B0); PG8_MMA(0, 1, At, B1); PG8_BAR; PG8_SCHED;
;             PG8_LDA(At, 0, 1); PG8_STAGE(PG8_SB(0, 0), b2, voffB); PG8_STAGE(PG8_SB(0, 1), b2 + hstep, voffB); PG8_STAGE(PG8_SA(0, 0), a2, voffA);
;             PG8_WAIT_V(8); PG8_WAIT_L(0); PG8_BAR; PG8_MMA(1, 0, At, B0); PG8_MMA(1, 1, At, B1); PG8_BAR; PG8_SCHED;
	v_mfma_f32_16x16x32_bf16 v[160:163], v[112:115], v[156:159], v[160:163]
	v_mfma_f32_16x16x32_bf16 v[152:155], v[120:123], v[156:159], v[152:155]
	v_mfma_f32_16x16x32_bf16 v[108:111], v[112:115], v[168:171], v[108:111]
	v_mfma_f32_16x16x32_bf16 v[104:107], v[120:123], v[168:171], v[104:107]
	v_mfma_f32_16x16x32_bf16 v[92:95], v[112:115], v[176:179], v[92:95]
	v_mfma_f32_16x16x32_bf16 v[88:91], v[120:123], v[176:179], v[88:91]
	v_mfma_f32_16x16x32_bf16 v[76:79], v[112:115], v[184:187], v[76:79]
	v_mfma_f32_16x16x32_bf16 v[72:75], v[120:123], v[184:187], v[72:75]
	v_mfma_f32_16x16x32_bf16 v[160:163], v[116:119], v[164:167], v[160:163]
	v_mfma_f32_16x16x32_bf16 v[152:155], v[124:127], v[164:167], v[152:155]
	v_mfma_f32_16x16x32_bf16 v[108:111], v[116:119], v[172:175], v[108:111]
	v_mfma_f32_16x16x32_bf16 v[104:107], v[124:127], v[172:175], v[104:107]
	v_mfma_f32_16x16x32_bf16 v[92:95], v[116:119], v[180:183], v[92:95]
	v_mfma_f32_16x16x32_bf16 v[88:91], v[124:127], v[180:183], v[88:91]
	v_mfma_f32_16x16x32_bf16 v[76:79], v[116:119], v[208:211], v[76:79]
	v_mfma_f32_16x16x32_bf16 v[72:75], v[124:127], v[208:211], v[72:75]
	v_mfma_f32_16x16x32_bf16 v[136:139], v[132:135], v[156:159], v[136:139]
	v_mfma_f32_16x16x32_bf16 v[128:131], v[144:147], v[156:159], v[128:131]
	v_mfma_f32_16x16x32_bf16 v[100:103], v[132:135], v[168:171], v[100:103]
	v_mfma_f32_16x16x32_bf16 v[96:99], v[144:147], v[168:171], v[96:99]
	v_mfma_f32_16x16x32_bf16 v[84:87], v[132:135], v[176:179], v[84:87]
	v_mfma_f32_16x16x32_bf16 v[80:83], v[144:147], v[176:179], v[80:83]
	v_mfma_f32_16x16x32_bf16 v[68:71], v[132:135], v[184:187], v[68:71]
	v_mfma_f32_16x16x32_bf16 v[64:67], v[144:147], v[184:187], v[64:67]
	v_mfma_f32_16x16x32_bf16 v[136:139], v[140:143], v[164:167], v[136:139]
	v_mfma_f32_16x16x32_bf16 v[128:131], v[148:151], v[164:167], v[128:131]
	v_mfma_f32_16x16x32_bf16 v[100:103], v[140:143], v[172:175], v[100:103]
	v_mfma_f32_16x16x32_bf16 v[96:99], v[148:151], v[172:175], v[96:99]
	v_mfma_f32_16x16x32_bf16 v[84:87], v[140:143], v[180:183], v[84:87]
	v_mfma_f32_16x16x32_bf16 v[80:83], v[148:151], v[180:183], v[80:83]
	v_mfma_f32_16x16x32_bf16 v[68:71], v[140:143], v[208:211], v[68:71]
	v_mfma_f32_16x16x32_bf16 v[64:67], v[148:151], v[208:211], v[64:67]
	s_barrier
	s_add_i32 s60, s60, s35
	v_lshl_add_u64 v[212:213], s[26:27], 0, v[188:189]
	s_mov_b32 m0, s60
	ds_read_b128 v[156:159], v241 offset:16384
	ds_read_b128 v[164:167], v241 offset:17408
	ds_read_b128 v[168:171], v241 offset:18432
	ds_read_b128 v[172:175], v241 offset:19456
	ds_read_b128 v[176:179], v241 offset:20480
	ds_read_b128 v[180:183], v241 offset:21504
	ds_read_b128 v[184:187], v241 offset:22528
	ds_read_b128 v[208:211], v241 offset:23552
	global_load_lds_dwordx4 v[212:213], off
	s_add_i32 m0, s60, 0x2000
	s_add_u32 s60, s26, 0x80000
	v_lshl_add_u64 v[214:215], s[26:27], 0, v[198:199]
	s_addc_u32 s61, s27, 0
	s_add_i32 s68, s68, s35
	global_load_lds_dwordx4 v[214:215], off
	v_lshl_add_u64 v[216:217], s[60:61], 0, v[188:189]
	s_mov_b32 m0, s68
	v_lshl_add_u64 v[218:219], s[28:29], 0, v[200:201]
	global_load_lds_dwordx4 v[216:217], off
	v_lshl_add_u64 v[216:217], s[60:61], 0, v[198:199]
	s_add_i32 m0, s68, 0x2000
	s_nop 0
	global_load_lds_dwordx4 v[216:217], off
	v_lshl_add_u64 v[216:217], s[28:29], 0, v[202:203]
	s_mov_b32 m0, s36
	s_nop 0
	global_load_lds_dwordx4 v[216:217], off
	s_mov_b32 m0, s37
	s_nop 0
	global_load_lds_dwordx4 v[218:219], off
	s_waitcnt vmcnt(8)
	s_waitcnt lgkmcnt(0)
	s_barrier
	v_mfma_f32_16x16x32_bf16 v[60:63], v[112:115], v[156:159], v[60:63]
	v_mfma_f32_16x16x32_bf16 v[56:59], v[120:123], v[156:159], v[56:59]
	v_mfma_f32_16x16x32_bf16 v[44:47], v[112:115], v[168:171], v[44:47]
	v_mfma_f32_16x16x32_bf16 v[40:43], v[120:123], v[168:171], v[40:43]
	v_mfma_f32_16x16x32_bf16 v[28:31], v[112:115], v[176:179], v[28:31]
	v_mfma_f32_16x16x32_bf16 v[24:27], v[120:123], v[176:179], v[24:27]
	v_mfma_f32_16x16x32_bf16 v[12:15], v[112:115], v[184:187], v[12:15]
	v_mfma_f32_16x16x32_bf16 v[8:11], v[120:123], v[184:187], v[8:11]
	v_mfma_f32_16x16x32_bf16 v[60:63], v[116:119], v[164:167], v[60:63]
	v_mfma_f32_16x16x32_bf16 v[56:59], v[124:127], v[164:167], v[56:59]
	v_mfma_f32_16x16x32_bf16 v[44:47], v[116:119], v[172:175], v[44:47]
	v_mfma_f32_16x16x32_bf16 v[40:43], v[124:127], v[172:175], v[40:43]
	v_mfma_f32_16x16x32_bf16 v[28:31], v[116:119], v[180:183], v[28:31]
	v_mfma_f32_16x16x32_bf16 v[24:27], v[124:127], v[180:183], v[24:27]
	v_mfma_f32_16x16x32_bf16 v[12:15], v[116:119], v[208:211], v[12:15]
	v_mfma_f32_16x16x32_bf16 v[8:11], v[124:127], v[208:211], v[8:11]
	v_mfma_f32_16x16x32_bf16 v[52:55], v[132:135], v[156:159], v[52:55]
	v_mfma_f32_16x16x32_bf16 v[48:51], v[144:147], v[156:159], v[48:51]
	v_mfma_f32_16x16x32_bf16 v[36:39], v[132:135], v[168:171], v[36:39]
	v_mfma_f32_16x16x32_bf16 v[32:35], v[144:147], v[168:171], v[32:35]
	v_mfma_f32_16x16x32_bf16 v[20:23], v[132:135], v[176:179], v[20:23]
	v_mfma_f32_16x16x32_bf16 v[16:19], v[144:147], v[176:179], v[16:19]
	v_mfma_f32_16x16x32_bf16 v[4:7], v[132:135], v[184:187], v[4:7]
	v_mfma_f32_16x16x32_bf16 v[0:3], v[144:147], v[184:187], v[0:3]
	v_mfma_f32_16x16x32_bf16 v[52:55], v[140:143], v[164:167], v[52:55]
	v_mfma_f32_16x16x32_bf16 v[48:51], v[148:151], v[164:167], v[48:51]
	v_mfma_f32_16x16x32_bf16 v[36:39], v[140:143], v[172:175], v[36:39]
	v_mfma_f32_16x16x32_bf16 v[32:35], v[148:151], v[172:175], v[32:35]
	v_mfma_f32_16x16x32_bf16 v[20:23], v[140:143], v[180:183], v[20:23]
	v_mfma_f32_16x16x32_bf16 v[16:19], v[148:151], v[180:183], v[16:19]
	v_mfma_f32_16x16x32_bf16 v[4:7], v[140:143], v[208:211], v[4:7]
	v_mfma_f32_16x16x32_bf16 v[0:3], v[148:151], v[208:211], v[0:3]
	s_barrier
; #define PG8_STAGE(bufoff, gbase, voff) do { _Pragma("unroll") for (int _i = 0; _i < 2; ++_i) \
;         __builtin_amdgcn_global_load_lds((const unsigned*)((const char*)(gbase) + (voff)[_i]), (PG8_LAS unsigned*)(lds + (bufoff) + ldsw + _i * 8192), 16, 0, 0); } while (0)
; #define PG8_LDA(dst, b, h) do { _Pragma("unroll") for (int m = 0; m < 4; ++m) _Pragma("unroll") for (int k = 0; k < 2; ++k) dst[m][k] = *(const PG8_LAS bf16x8*)(lds + PG8_SA(b, h) + aoff + m * 2048 + k * 1024); } while (0)
; #define PG8_LDB(dst, b, h) do { _Pragma("unroll") for (int n = 0; n < 2; ++n) _Pragma("unroll") for (int k = 0; k < 2; ++k) dst[n][k] = *(const PG8_LAS bf16x8*)(lds + PG8_SB(b, h) + boff + n * 2048 + k * 1024); } while (0)
; #define PG8_MMA(ai, bj, At, Bt) do { __builtin_amdgcn_s_setprio(1); _Pragma("unroll") for (int m = 0; m < 4; ++m) _Pragma("unroll") for (int n = 0; n < 2; ++n) _Pragma("unroll") for (int k = 0; k < 2; ++k) \
;         acc[ai][bj][m][n] = __builtin_amdgcn_mfma_f32_16x16x32_bf16(Bt[n][k], At[m][k], acc[ai][bj][m][n], 0, 0, 0); __builtin_amdgcn_s_setprio(0); } while (0)
; #define PG8_WAIT_V(n) asm volatile("s_waitcnt vmcnt(" #n ")" ::: "memory")
; #define PG8_WAIT_L(n) asm volatile("s_waitcnt lgkmcnt(" #n ")" ::: "memory")
; #define PG8_BAR __builtin_amdgcn_s_barrier()
; #define PG8_SCHED __builtin_amdgcn_sched_barrier(0)
; template <class Epi, class Sched, bool ALIGN_EPI = false, bool SP2 = false>
; __device__ __forceinline__ void gemm_phase(PG8_LAS unsigned char* lds, const Gemm g, const Sched& S, const Epi& E) {
;     ...
;             PG8_LDB(B0, 1, 0); PG8_LDB(B1, 1, 1); PG8_SCHED; PG8_LDA(At, 1, 0); PG8_STAGE(PG8_SA(0, 1), a2 + hstep, voffA);
;             PG8_WAIT_V(8); PG8_WAIT_L(0); PG8_BAR; PG8_MMA(0, 0, At, B0); PG8_MMA(0, 1, At, B1); PG8_BAR; PG8_SCHED;
	s_add_i32 s60, 0, 0x18000
	s_add_i32 s61, 0, 0x1c000
	v_add_u32_e32 v124, s60, v239
	v_add_u32_e32 v148, s61, v239
	ds_read_b128 v[112:115], v124
	ds_read_b128 v[116:119], v124 offset:1024
	ds_read_b128 v[120:123], v124 offset:2048
	ds_read_b128 v[124:127], v124 offset:3072
	ds_read_b128 v[132:135], v148
	ds_read_b128 v[140:143], v148 offset:1024
	ds_read_b128 v[144:147], v148 offset:2048
	ds_read_b128 v[148:151], v148 offset:3072
	s_add_u32 s28, s28, 0x80000
	s_addc_u32 s29, s29, 0
	s_mov_b32 m0, s38
	v_lshl_add_u64 v[220:221], s[28:29], 0, v[202:203]
	ds_read_b128 v[156:159], v241 offset:32768
	ds_read_b128 v[164:167], v241 offset:33792
	ds_read_b128 v[168:171], v241 offset:34816
	ds_read_b128 v[172:175], v241 offset:35840
	ds_read_b128 v[176:179], v241 offset:36864
	ds_read_b128 v[180:183], v241 offset:37888
	ds_read_b128 v[184:187], v241 offset:38912
	ds_read_b128 v[208:211], v241 offset:39936
	global_load_lds_dwordx4 v[220:221], off
	v_lshl_add_u64 v[220:221], s[28:29], 0, v[200:201]
	s_mov_b32 m0, s39
	s_nop 0
	global_load_lds_dwordx4 v[220:221], off
	s_waitcnt vmcnt(8)
	s_waitcnt lgkmcnt(0)
	s_barrier
	v_mfma_f32_16x16x32_bf16 v[160:163], v[112:115], v[156:159], v[160:163]
	v_mfma_f32_16x16x32_bf16 v[152:155], v[120:123], v[156:159], v[152:155]
	v_mfma_f32_16x16x32_bf16 v[108:111], v[112:115], v[168:171], v[108:111]
	v_mfma_f32_16x16x32_bf16 v[104:107], v[120:123], v[168:171], v[104:107]
	v_mfma_f32_16x16x32_bf16 v[92:95], v[112:115], v[176:179], v[92:95]
	v_mfma_f32_16x16x32_bf16 v[88:91], v[120:123], v[176:179], v[88:91]
	v_mfma_f32_16x16x32_bf16 v[76:79], v[112:115], v[184:187], v[76:79]
	v_mfma_f32_16x16x32_bf16 v[72:75], v[120:123], v[184:187], v[72:75]
	v_mfma_f32_16x16x32_bf16 v[160:163], v[116:119], v[164:167], v[160:163]
	v_mfma_f32_16x16x32_bf16 v[152:155], v[124:127], v[164:167], v[152:155]
	v_mfma_f32_16x16x32_bf16 v[108:111], v[116:119], v[172:175], v[108:111]
	v_mfma_f32_16x16x32_bf16 v[104:107], v[124:127], v[172:175], v[104:107]
	v_mfma_f32_16x16x32_bf16 v[92:95], v[116:119], v[180:183], v[92:95]
	v_mfma_f32_16x16x32_bf16 v[88:91], v[124:127], v[180:183], v[88:91]
	v_mfma_f32_16x16x32_bf16 v[76:79], v[116:119], v[208:211], v[76:79]
	v_mfma_f32_16x16x32_bf16 v[72:75], v[124:127], v[208:211], v[72:75]
	v_mfma_f32_16x16x32_bf16 v[136:139], v[132:135], v[156:159], v[136:139]
	v_mfma_f32_16x16x32_bf16 v[128:131], v[144:147], v[156:159], v[128:131]
	v_mfma_f32_16x16x32_bf16 v[100:103], v[132:135], v[168:171], v[100:103]
	v_mfma_f32_16x16x32_bf16 v[96:99], v[144:147], v[168:171], v[96:99]
	v_mfma_f32_16x16x32_bf16 v[84:87], v[132:135], v[176:179], v[84:87]
	v_mfma_f32_16x16x32_bf16 v[80:83], v[144:147], v[176:179], v[80:83]
	v_mfma_f32_16x16x32_bf16 v[68:71], v[132:135], v[184:187], v[68:71]
	v_mfma_f32_16x16x32_bf16 v[64:67], v[144:147], v[184:187], v[64:67]
	v_mfma_f32_16x16x32_bf16 v[136:139], v[140:143], v[164:167], v[136:139]
	v_mfma_f32_16x16x32_bf16 v[128:131], v[148:151], v[164:167], v[128:131]
	v_mfma_f32_16x16x32_bf16 v[100:103], v[140:143], v[172:175], v[100:103]
	v_mfma_f32_16x16x32_bf16 v[96:99], v[148:151], v[172:175], v[96:99]
	v_mfma_f32_16x16x32_bf16 v[84:87], v[140:143], v[180:183], v[84:87]
	v_mfma_f32_16x16x32_bf16 v[80:83], v[148:151], v[180:183], v[80:83]
	v_mfma_f32_16x16x32_bf16 v[68:71], v[140:143], v[208:211], v[68:71]
	v_mfma_f32_16x16x32_bf16 v[64:67], v[148:151], v[208:211], v[64:67]
	s_barrier
; #define PG8_STAGE(bufoff, gbase, voff) do { _Pragma("unroll") for (int _i = 0; _i < 2; ++_i) \
;         __builtin_amdgcn_global_load_lds((const unsigned*)((const char*)(gbase) + (voff)[_i]), (PG8_LAS unsigned*)(lds + (bufoff) + ldsw + _i * 8192), 16, 0, 0); } while (0)
; #define PG8_LDA(dst, b, h) do { _Pragma("unroll") for (int m = 0; m < 4; ++m) _Pragma("unroll") for (int k = 0; k < 2; ++k) dst[m][k] = *(const PG8_LAS bf16x8*)(lds + PG8_SA(b, h) + aoff + m * 2048 + k * 1024); } while (0)
; #define PG8_MMA(ai, bj, At, Bt) do { __builtin_amdgcn_s_setprio(1); _Pragma("unroll") for (int m = 0; m < 4; ++m) _Pragma("unroll") for (int n = 0; n < 2; ++n) _Pragma("unroll") for (int k = 0; k < 2; ++k) \
;         acc[ai][bj][m][n] = __builtin_amdgcn_mfma_f32_16x16x32_bf16(Bt[n][k], At[m][k], acc[ai][bj][m][n], 0, 0, 0); __builtin_amdgcn_s_setprio(0); } while (0)
; #define PG8_WAIT_V(n) asm volatile("s_waitcnt vmcnt(" #n ")" ::: "memory")
; #define PG8_WAIT_L(n) asm volatile("s_waitcnt lgkmcnt(" #n ")" ::: "memory")
; #define PG8_BAR __builtin_amdgcn_s_barrier()
; #define PG8_SCHED __builtin_amdgcn_sched_barrier(0)
; template <class Epi, class Sched, bool ALIGN_EPI = false, bool SP2 = false>
; __device__ __forceinline__ void gemm_phase(PG8_LAS unsigned char* lds, const Gemm g, const Sched& S, const Epi& E) {
;     ...
;             PG8_LDA(At, 1, 1); PG8_STAGE(PG8_SB(1, 0), b3, voffB); PG8_STAGE(PG8_SB(1, 1), b3 + hstep, voffB); PG8_STAGE(PG8_SA(1, 0), a3, voffA);
;             PG8_WAIT_V(8); PG8_WAIT_L(0); PG8_BAR; PG8_MMA(1, 0, At, B0); PG8_MMA(1, 1, At, B1); PG8_BAR; PG8_SCHED;
;     ...
;         if constexpr (ALIGN_EPI) { if (wr == 0) PG8_BAR; }
	s_add_i32 s28, s60, s35
	v_lshl_add_u64 v[212:213], v[212:213], 0, s[78:79]
	s_mov_b32 m0, s28
	ds_read_b128 v[156:159], v241 offset:49152
	ds_read_b128 v[164:167], v241 offset:50176
	ds_read_b128 v[168:171], v241 offset:51200
	ds_read_b128 v[172:175], v241 offset:52224
	ds_read_b128 v[176:179], v241 offset:53248
	ds_read_b128 v[180:183], v241 offset:54272
	ds_read_b128 v[184:187], v241 offset:55296
	ds_read_b128 v[208:211], v241 offset:56320
	global_load_lds_dwordx4 v[212:213], off
	s_add_i32 m0, s28, 0x2000
	s_add_u32 s26, s26, 0x80080
	v_lshl_add_u64 v[212:213], v[214:215], 0, s[78:79]
	s_addc_u32 s27, s27, 0
	s_add_i32 s28, s61, s35
	global_load_lds_dwordx4 v[212:213], off
	v_lshl_add_u64 v[212:213], s[26:27], 0, v[188:189]
	s_mov_b32 m0, s28
	s_nop 0
	global_load_lds_dwordx4 v[212:213], off
	v_lshl_add_u64 v[212:213], s[26:27], 0, v[198:199]
	s_add_i32 m0, s28, 0x2000
	s_nop 0
	global_load_lds_dwordx4 v[212:213], off
	v_lshl_add_u64 v[212:213], v[216:217], 0, s[78:79]
	s_mov_b32 m0, s40
	s_nop 0
	global_load_lds_dwordx4 v[212:213], off
	v_lshl_add_u64 v[212:213], v[218:219], 0, s[78:79]
	s_mov_b32 m0, s41
	s_nop 0
	global_load_lds_dwordx4 v[212:213], off
	s_waitcnt vmcnt(8)
	s_waitcnt lgkmcnt(0)
	s_barrier
	v_mfma_f32_16x16x32_bf16 v[60:63], v[112:115], v[156:159], v[60:63]
	v_mfma_f32_16x16x32_bf16 v[56:59], v[120:123], v[156:159], v[56:59]
	v_mfma_f32_16x16x32_bf16 v[44:47], v[112:115], v[168:171], v[44:47]
	v_mfma_f32_16x16x32_bf16 v[40:43], v[120:123], v[168:171], v[40:43]
	v_mfma_f32_16x16x32_bf16 v[28:31], v[112:115], v[176:179], v[28:31]
	v_mfma_f32_16x16x32_bf16 v[24:27], v[120:123], v[176:179], v[24:27]
	v_mfma_f32_16x16x32_bf16 v[12:15], v[112:115], v[184:187], v[12:15]
	v_mfma_f32_16x16x32_bf16 v[8:11], v[120:123], v[184:187], v[8:11]
	v_mfma_f32_16x16x32_bf16 v[60:63], v[116:119], v[164:167], v[60:63]
	v_mfma_f32_16x16x32_bf16 v[56:59], v[124:127], v[164:167], v[56:59]
	v_mfma_f32_16x16x32_bf16 v[44:47], v[116:119], v[172:175], v[44:47]
	v_mfma_f32_16x16x32_bf16 v[40:43], v[124:127], v[172:175], v[40:43]
	v_mfma_f32_16x16x32_bf16 v[28:31], v[116:119], v[180:183], v[28:31]
	v_mfma_f32_16x16x32_bf16 v[24:27], v[124:127], v[180:183], v[24:27]
	v_mfma_f32_16x16x32_bf16 v[12:15], v[116:119], v[208:211], v[12:15]
	v_mfma_f32_16x16x32_bf16 v[8:11], v[124:127], v[208:211], v[8:11]
	v_mfma_f32_16x16x32_bf16 v[52:55], v[132:135], v[156:159], v[52:55]
	v_mfma_f32_16x16x32_bf16 v[48:51], v[144:147], v[156:159], v[48:51]
	v_mfma_f32_16x16x32_bf16 v[36:39], v[132:135], v[168:171], v[36:39]
	v_mfma_f32_16x16x32_bf16 v[32:35], v[144:147], v[168:171], v[32:35]
	v_mfma_f32_16x16x32_bf16 v[20:23], v[132:135], v[176:179], v[20:23]
	v_mfma_f32_16x16x32_bf16 v[16:19], v[144:147], v[176:179], v[16:19]
	v_mfma_f32_16x16x32_bf16 v[4:7], v[132:135], v[184:187], v[4:7]
	v_mfma_f32_16x16x32_bf16 v[0:3], v[144:147], v[184:187], v[0:3]
	v_mfma_f32_16x16x32_bf16 v[52:55], v[140:143], v[164:167], v[52:55]
	v_mfma_f32_16x16x32_bf16 v[48:51], v[148:151], v[164:167], v[48:51]
	v_mfma_f32_16x16x32_bf16 v[36:39], v[140:143], v[172:175], v[36:39]
	v_mfma_f32_16x16x32_bf16 v[32:35], v[148:151], v[172:175], v[32:35]
	v_mfma_f32_16x16x32_bf16 v[20:23], v[140:143], v[180:183], v[20:23]
	v_mfma_f32_16x16x32_bf16 v[16:19], v[148:151], v[180:183], v[16:19]
	v_mfma_f32_16x16x32_bf16 v[4:7], v[140:143], v[208:211], v[4:7]
	v_mfma_f32_16x16x32_bf16 v[0:3], v[148:151], v[208:211], v[0:3]
	s_barrier
	s_add_i32 s67, s67, 2
	s_add_u32 s24, s24, 0x100
	s_addc_u32 s25, s25, 0
	s_add_u32 s63, s63, 0x100
	s_addc_u32 s66, s66, 0
	s_cmp_gt_u32 s67, 29
	s_cbranch_scc0 .LBB0_596
	s_setprio 0
	s_and_b64 vcc, exec, s[14:15]
	s_cbranch_vccz .LBB0_599
	s_barrier

;     __device__ __forceinline__ bool next(int i, Unit& u) const { Unit t; if (!so.next(i / 3, t)) return false; const int br = i % 3; u.pm = t.pm + br * so.nM; u.pn = t.pn + br * so.nN; return true; }
;     __device__ __forceinline__ bool zero_after(const Unit& u) const { return (u.pn / nN) == 2; }
; #define PG8_STAGE(bufoff, gbase, voff) do { _Pragma("unroll") for (int _i = 0; _i < 2; ++_i) \
;         __builtin_amdgcn_global_load_lds((const unsigned*)((const char*)(gbase) + (voff)[_i]), (PG8_LAS unsigned*)(lds + (bufoff) + ldsw + _i * 8192), 16, 0, 0); } while (0)
; #define PG8_LDA(dst, b, h) do { _Pragma("unroll") for (int m = 0; m < 4; ++m) _Pragma("unroll") for (int k = 0; k < 2; ++k) dst[m][k] = *(const PG8_LAS bf16x8*)(lds + PG8_SA(b, h) + aoff + m * 2048 + k * 1024); } while (0)
; #define PG8_WAIT_V(n) asm volatile("s_waitcnt vmcnt(" #n ")" ::: "memory")
; #define PG8_WAIT_L(n) asm volatile("s_waitcnt lgkmcnt(" #n ")" ::: "memory")
; template <class Epi, class Sched, bool ALIGN_EPI = false, bool SP2 = false>
; __device__ __forceinline__ void gemm_phase(PG8_LAS unsigned char* lds, const Gemm g, const Sched& S, const Epi& E) {
;     ...
;         const bool has_next = S.next(ui + 1, nxt);
;         const char* nA = has_next ? (const char*)g.A + (size_t)nxt.pm * tstep : cA; const char* nB = has_next ? (const char*)g.Bt + (size_t)nxt.pn * tstep : cB;
;         for (int t = 0; t < nt; t += 2) {
;             const bool last = (t == nt - 2);
;             const char* a1 = cA + (size_t)(t + 1) * kstep;
;             const char* a2 = last ? nA : cA + (size_t)(t + 2) * kstep; const char* b2 = last ? nB : cB + (size_t)(t + 2) * kstep;
;             const char* a3 = a2 + kstep; const char* b3 = b2 + kstep;
;             if (last && has_next) S.a_ready(nxt);
;             if constexpr (SP2) {
;             PG8_LDB(B0, 0, 0); PG8_LDB(B1, 0, 1); PG8_SCHED; PG8_LDA(At, 0, 0); PG8_STAGE(PG8_SA(1, 1), a1 + hstep, voffA);
;             PG8_WAIT_V(8); PG8_WAIT_L(0); PG8_BAR; PG8_MMA(0, 0, At, B0); PG8_MMA(0, 1, At, B1); PG8_BAR; PG8_SCHED;
;     ...
;         if (E.zero_after(cur)) {
; #pragma unroll
;         for (int a = 0; a < 2; ++a)
; #pragma unroll
;             for (int b = 0; b < 2; ++b)
; #pragma unroll
;                 for (int m = 0; m < 4; ++m)
; #pragma unroll
;                     for (int n = 0; n < 2; ++n) acc[a][b][m][n] = (f32x4){0.f, 0.f, 0.f, 0.f};
.LBB0_683:
	s_ashr_i32 s19, s18, 31
	s_lshl_b64 s[20:21], s[18:19], 20
	s_add_u32 s20, s2, s20
	s_addc_u32 s21, s28, s21
	s_and_b64 s[22:23], s[6:7], exec
	s_cselect_b32 s19, s21, s9
	s_cselect_b32 s45, s20, s8
	s_ashr_i32 s17, s16, 31
	s_lshl_b64 s[22:23], s[16:17], 20
	s_add_u32 s22, s29, s22
	s_addc_u32 s23, s30, s23
	s_and_b64 s[26:27], s[6:7], exec
	s_cselect_b32 s17, s23, s25
	s_cselect_b32 s52, s22, s24
	s_add_u32 s8, s8, 0x80080
	s_addc_u32 s9, s9, 0
	s_add_u32 s58, s24, 0x100
	s_addc_u32 s62, s25, 0
	s_mov_b32 s63, -2
	v_mov_b64_e32 v[0:1], 0
	v_mov_b64_e32 v[2:3], 0
	v_mov_b64_e32 v[4:5], 0
	v_mov_b64_e32 v[6:7], 0
	v_mov_b64_e32 v[8:9], 0
	v_mov_b64_e32 v[10:11], 0
	v_mov_b64_e32 v[12:13], 0
	v_mov_b64_e32 v[14:15], 0
	v_mov_b64_e32 v[16:17], 0
	v_mov_b64_e32 v[18:19], 0
	v_mov_b64_e32 v[20:21], 0
	v_mov_b64_e32 v[22:23], 0
	v_mov_b64_e32 v[24:25], 0
	v_mov_b64_e32 v[26:27], 0
	v_mov_b64_e32 v[28:29], 0
	v_mov_b64_e32 v[30:31], 0
	v_mov_b64_e32 v[32:33], 0
	v_mov_b64_e32 v[34:35], 0
	v_mov_b64_e32 v[36:37], 0
	v_mov_b64_e32 v[38:39], 0
	v_mov_b64_e32 v[40:41], 0
	v_mov_b64_e32 v[42:43], 0
	v_mov_b64_e32 v[44:45], 0
	v_mov_b64_e32 v[46:47], 0
	v_mov_b64_e32 v[48:49], 0
	v_mov_b64_e32 v[50:51], 0
	v_mov_b64_e32 v[52:53], 0
	v_mov_b64_e32 v[54:55], 0
	v_mov_b64_e32 v[56:57], 0
	v_mov_b64_e32 v[58:59], 0
	v_mov_b64_e32 v[60:61], 0
	v_mov_b64_e32 v[62:63], 0
	v_mov_b64_e32 v[64:65], 0
	v_mov_b64_e32 v[66:67], 0
	v_mov_b64_e32 v[68:69], 0
	v_mov_b64_e32 v[70:71], 0
	v_mov_b64_e32 v[72:73], 0
	v_mov_b64_e32 v[74:75], 0
	v_mov_b64_e32 v[76:77], 0
	v_mov_b64_e32 v[78:79], 0
	v_mov_b64_e32 v[80:81], 0
	v_mov_b64_e32 v[82:83], 0
	v_mov_b64_e32 v[84:85], 0
	v_mov_b64_e32 v[86:87], 0
	v_mov_b64_e32 v[88:89], 0
	v_mov_b64_e32 v[90:91], 0
	v_mov_b64_e32 v[92:93], 0
	v_mov_b64_e32 v[94:95], 0
	v_mov_b64_e32 v[96:97], 0
	v_mov_b64_e32 v[98:99], 0
	v_mov_b64_e32 v[100:101], 0
	v_mov_b64_e32 v[102:103], 0
	v_mov_b64_e32 v[104:105], 0
	v_mov_b64_e32 v[106:107], 0
	v_mov_b64_e32 v[108:109], 0
	v_mov_b64_e32 v[110:111], 0
	v_mov_b64_e32 v[112:113], 0
	v_mov_b64_e32 v[114:115], 0
	v_mov_b64_e32 v[116:117], 0
	v_mov_b64_e32 v[118:119], 0
	v_mov_b64_e32 v[120:121], 0
	v_mov_b64_e32 v[122:123], 0
	v_mov_b64_e32 v[124:125], 0
	v_mov_b64_e32 v[126:127], 0
	s_cmp_eq_u64 s[14:15], 0
	s_cbranch_scc0 .Lprio_skip_684
	s_setprio 1
.Lprio_skip_684:
.LBB0_684:
	s_add_u32 s24, s8, 0xfff80080
	s_addc_u32 s25, s9, -1
	s_add_i32 s60, 0, 0x10000
	s_cmp_eq_u32 s63, 28
	s_cselect_b32 s27, s19, s25
	s_cselect_b32 s26, s45, s24
	v_add_u32_e32 v154, s60, v157
	s_cselect_b32 s25, s17, s62
	s_cselect_b32 s24, s52, s58
	s_add_i32 s66, 0, 0x14000
	ds_read_b128 v[160:163], v154
	ds_read_b128 v[164:167], v154 offset:1024
	ds_read_b128 v[168:171], v154 offset:2048
	ds_read_b128 v[172:175], v154 offset:3072
	v_add_u32_e32 v154, s66, v157
	ds_read_b128 v[176:179], v154
	ds_read_b128 v[180:183], v154 offset:1024
	ds_read_b128 v[184:187], v154 offset:2048
	ds_read_b128 v[198:201], v154 offset:3072
	v_lshl_add_u64 v[154:155], s[8:9], 0, v[134:135]
	s_add_i32 m0, s34, 0xc000
	ds_read_b128 v[202:205], v159
	ds_read_b128 v[206:209], v159 offset:1024
	ds_read_b128 v[210:213], v159 offset:2048
	ds_read_b128 v[214:217], v159 offset:3072
	ds_read_b128 v[218:221], v159 offset:4096
	ds_read_b128 v[222:225], v159 offset:5120
	ds_read_b128 v[226:229], v159 offset:6144
	ds_read_b128 v[238:241], v159 offset:7168
	global_load_lds_dwordx4 v[154:155], off
	v_lshl_add_u64 v[154:155], s[8:9], 0, v[136:137]
	s_add_i32 m0, s34, 0xe000
	s_nop 0
	global_load_lds_dwordx4 v[154:155], off
	s_waitcnt vmcnt(8)
	s_waitcnt lgkmcnt(0)
	s_barrier
	v_mfma_f32_16x16x32_bf16 v[124:127], v[160:163], v[202:205], v[124:127]
	v_mfma_f32_16x16x32_bf16 v[120:123], v[168:171], v[202:205], v[120:123]
	v_mfma_f32_16x16x32_bf16 v[108:111], v[160:163], v[210:213], v[108:111]
	v_mfma_f32_16x16x32_bf16 v[104:107], v[168:171], v[210:213], v[104:107]
	v_mfma_f32_16x16x32_bf16 v[92:95], v[160:163], v[218:221], v[92:95]
	v_mfma_f32_16x16x32_bf16 v[88:91], v[168:171], v[218:221], v[88:91]
	v_mfma_f32_16x16x32_bf16 v[76:79], v[160:163], v[226:229], v[76:79]
	v_mfma_f32_16x16x32_bf16 v[72:75], v[168:171], v[226:229], v[72:75]
	v_mfma_f32_16x16x32_bf16 v[124:127], v[164:167], v[206:209], v[124:127]
	v_mfma_f32_16x16x32_bf16 v[120:123], v[172:175], v[206:209], v[120:123]
	v_mfma_f32_16x16x32_bf16 v[108:111], v[164:167], v[214:217], v[108:111]
	v_mfma_f32_16x16x32_bf16 v[104:107], v[172:175], v[214:217], v[104:107]
	v_mfma_f32_16x16x32_bf16 v[92:95], v[164:167], v[222:225], v[92:95]
	v_mfma_f32_16x16x32_bf16 v[88:91], v[172:175], v[222:225], v[88:91]
	v_mfma_f32_16x16x32_bf16 v[76:79], v[164:167], v[238:241], v[76:79]
	v_mfma_f32_16x16x32_bf16 v[72:75], v[172:175], v[238:241], v[72:75]
	v_mfma_f32_16x16x32_bf16 v[116:119], v[176:179], v[202:205], v[116:119]
	v_mfma_f32_16x16x32_bf16 v[112:115], v[184:187], v[202:205], v[112:115]
	v_mfma_f32_16x16x32_bf16 v[100:103], v[176:179], v[210:213], v[100:103]
	v_mfma_f32_16x16x32_bf16 v[96:99], v[184:187], v[210:213], v[96:99]
	v_mfma_f32_16x16x32_bf16 v[84:87], v[176:179], v[218:221], v[84:87]
	v_mfma_f32_16x16x32_bf16 v[80:83], v[184:187], v[218:221], v[80:83]
	v_mfma_f32_16x16x32_bf16 v[68:71], v[176:179], v[226:229], v[68:71]
	v_mfma_f32_16x16x32_bf16 v[64:67], v[184:187], v[226:229], v[64:67]
	v_mfma_f32_16x16x32_bf16 v[116:119], v[180:183], v[206:209], v[116:119]
	v_mfma_f32_16x16x32_bf16 v[112:115], v[198:201], v[206:209], v[112:115]
	v_mfma_f32_16x16x32_bf16 v[100:103], v[180:183], v[214:217], v[100:103]
	v_mfma_f32_16x16x32_bf16 v[96:99], v[198:201], v[214:217], v[96:99]
	v_mfma_f32_16x16x32_bf16 v[84:87], v[180:183], v[222:225], v[84:87]
	v_mfma_f32_16x16x32_bf16 v[80:83], v[198:201], v[222:225], v[80:83]
	v_mfma_f32_16x16x32_bf16 v[68:71], v[180:183], v[238:241], v[68:71]
	v_mfma_f32_16x16x32_bf16 v[64:67], v[198:201], v[238:241], v[64:67]
	s_barrier
; #define PG8_STAGE(bufoff, gbase, voff) do { _Pragma("unroll") for (int _i = 0; _i < 2; ++_i) \
;         __builtin_amdgcn_global_load_lds((const unsigned*)((const char*)(gbase) + (voff)[_i]), (PG8_LAS unsigned*)(lds + (bufoff) + ldsw + _i * 8192), 16, 0, 0); } while (0)
; #define PG8_LDA(dst, b, h) do { _Pragma("unroll") for (int m = 0; m < 4; ++m) _Pragma("unroll") for (int k = 0; k < 2; ++k) dst[m][k] = *(const PG8_LAS bf16x8*)(lds + PG8_SA(b, h) + aoff + m * 2048 + k * 1024); } while (0)
; #define PG8_LDB(dst, b, h) do { _Pragma("unroll") for (int n = 0; n < 2; ++n) _Pragma("unroll") for (int k = 0; k < 2; ++k) dst[n][k] = *(const PG8_LAS bf16x8*)(lds + PG8_SB(b, h) + boff + n * 2048 + k * 1024); } while (0)
; #define PG8_MMA(ai, bj, At, Bt) do { __builtin_amdgcn_s_setprio(1); _Pragma("unroll") for (int m = 0; m < 4; ++m) _Pragma("unroll") for (int n = 0; n < 2; ++n) _Pragma("unroll") for (int k = 0; k < 2; ++k) \
;         acc[ai][bj][m][n] = __builtin_amdgcn_mfma_f32_16x16x32_bf16(Bt[n][k], At[m][k], acc[ai][bj][m][n], 0, 0, 0); __builtin_amdgcn_s_setprio(0); } while (0)
; #define PG8_WAIT_V(n) asm volatile("s_waitcnt vmcnt(" #n ")" ::: "memory")
; #define PG8_WAIT_L(n) asm volatile("s_waitcnt lgkmcnt(" #n ")" ::: "memory")
; #define PG8_BAR __builtin_amdgcn_s_barrier()
; #define PG8_SCHED __builtin_amdgcn_sched_barrier(0)
; template <class Epi, class Sched, bool ALIGN_EPI = false, bool SP2 = false>
; __device__ __forceinline__ void gemm_phase(PG8_LAS unsigned char* lds, const Gemm g, const Sched& S, const Epi& E) {
;     ...
;             PG8_LDA(At, 0, 1); PG8_STAGE(PG8_SB(0, 0), b2, voffB); PG8_STAGE(PG8_SB(0, 1), b2 + hstep, voffB); PG8_STAGE(PG8_SA(0, 0), a2, voffA);
;             PG8_WAIT_V(8); PG8_WAIT_L(0); PG8_BAR; PG8_MMA(1, 0, At, B0); PG8_MMA(1, 1, At, B1); PG8_BAR; PG8_SCHED;
;             PG8_LDB(B0, 1, 0); PG8_LDB(B1, 1, 1); PG8_SCHED; PG8_LDA(At, 1, 0); PG8_STAGE(PG8_SA(0, 1), a2 + hstep, voffA);
	s_add_i32 s60, s60, s31
	v_lshl_add_u64 v[154:155], s[24:25], 0, v[188:189]
	s_mov_b32 m0, s60
	ds_read_b128 v[202:205], v159 offset:16384
	ds_read_b128 v[206:209], v159 offset:17408
	ds_read_b128 v[210:213], v159 offset:18432
	ds_read_b128 v[214:217], v159 offset:19456
	ds_read_b128 v[218:221], v159 offset:20480
	ds_read_b128 v[222:225], v159 offset:21504
	ds_read_b128 v[226:229], v159 offset:22528
	ds_read_b128 v[238:241], v159 offset:23552
	global_load_lds_dwordx4 v[154:155], off
	s_add_i32 m0, s60, 0x2000
	s_add_u32 s60, s24, 0x80000
	v_lshl_add_u64 v[232:233], s[24:25], 0, v[128:129]
	s_addc_u32 s61, s25, 0
	s_add_i32 s66, s66, s31
	global_load_lds_dwordx4 v[232:233], off
	v_lshl_add_u64 v[242:243], s[60:61], 0, v[188:189]
	s_mov_b32 m0, s66
	v_lshl_add_u64 v[244:245], s[26:27], 0, v[130:131]
	global_load_lds_dwordx4 v[242:243], off
	v_lshl_add_u64 v[242:243], s[60:61], 0, v[128:129]
	s_add_i32 m0, s66, 0x2000
	s_nop 0
	global_load_lds_dwordx4 v[242:243], off
	v_lshl_add_u64 v[242:243], s[26:27], 0, v[132:133]
	s_mov_b32 m0, s34
	s_nop 0
	global_load_lds_dwordx4 v[242:243], off
	s_mov_b32 m0, s35
	s_nop 0
	global_load_lds_dwordx4 v[244:245], off
	s_waitcnt vmcnt(8)
	s_waitcnt lgkmcnt(0)
	s_barrier
	v_mfma_f32_16x16x32_bf16 v[60:63], v[160:163], v[202:205], v[60:63]
	v_mfma_f32_16x16x32_bf16 v[56:59], v[168:171], v[202:205], v[56:59]
	v_mfma_f32_16x16x32_bf16 v[44:47], v[160:163], v[210:213], v[44:47]
	v_mfma_f32_16x16x32_bf16 v[40:43], v[168:171], v[210:213], v[40:43]
	v_mfma_f32_16x16x32_bf16 v[28:31], v[160:163], v[218:221], v[28:31]
	v_mfma_f32_16x16x32_bf16 v[24:27], v[168:171], v[218:221], v[24:27]
	v_mfma_f32_16x16x32_bf16 v[12:15], v[160:163], v[226:229], v[12:15]
	v_mfma_f32_16x16x32_bf16 v[8:11], v[168:171], v[226:229], v[8:11]
	v_mfma_f32_16x16x32_bf16 v[60:63], v[164:167], v[206:209], v[60:63]
	v_mfma_f32_16x16x32_bf16 v[56:59], v[172:175], v[206:209], v[56:59]
	v_mfma_f32_16x16x32_bf16 v[44:47], v[164:167], v[214:217], v[44:47]
	v_mfma_f32_16x16x32_bf16 v[40:43], v[172:175], v[214:217], v[40:43]
	v_mfma_f32_16x16x32_bf16 v[28:31], v[164:167], v[222:225], v[28:31]
	v_mfma_f32_16x16x32_bf16 v[24:27], v[172:175], v[222:225], v[24:27]
	v_mfma_f32_16x16x32_bf16 v[12:15], v[164:167], v[238:241], v[12:15]
	v_mfma_f32_16x16x32_bf16 v[8:11], v[172:175], v[238:241], v[8:11]
	v_mfma_f32_16x16x32_bf16 v[52:55], v[176:179], v[202:205], v[52:55]
	v_mfma_f32_16x16x32_bf16 v[48:51], v[184:187], v[202:205], v[48:51]
	v_mfma_f32_16x16x32_bf16 v[36:39], v[176:179], v[210:213], v[36:39]
	v_mfma_f32_16x16x32_bf16 v[32:35], v[184:187], v[210:213], v[32:35]
	v_mfma_f32_16x16x32_bf16 v[20:23], v[176:179], v[218:221], v[20:23]
	v_mfma_f32_16x16x32_bf16 v[16:19], v[184:187], v[218:221], v[16:19]
	v_mfma_f32_16x16x32_bf16 v[4:7], v[176:179], v[226:229], v[4:7]
	v_mfma_f32_16x16x32_bf16 v[0:3], v[184:187], v[226:229], v[0:3]
	v_mfma_f32_16x16x32_bf16 v[52:55], v[180:183], v[206:209], v[52:55]
	v_mfma_f32_16x16x32_bf16 v[48:51], v[198:201], v[206:209], v[48:51]
	v_mfma_f32_16x16x32_bf16 v[36:39], v[180:183], v[214:217], v[36:39]
	v_mfma_f32_16x16x32_bf16 v[32:35], v[198:201], v[214:217], v[32:35]
	v_mfma_f32_16x16x32_bf16 v[20:23], v[180:183], v[222:225], v[20:23]
	v_mfma_f32_16x16x32_bf16 v[16:19], v[198:201], v[222:225], v[16:19]
	v_mfma_f32_16x16x32_bf16 v[4:7], v[180:183], v[238:241], v[4:7]
	v_mfma_f32_16x16x32_bf16 v[0:3], v[198:201], v[238:241], v[0:3]
	s_barrier
	s_add_i32 s60, 0, 0x18000
	s_add_i32 s61, 0, 0x1c000
	v_add_u32_e32 v172, s60, v157
	v_add_u32_e32 v194, s61, v157
	ds_read_b128 v[160:163], v172
	ds_read_b128 v[164:167], v172 offset:1024
	ds_read_b128 v[168:171], v172 offset:2048
	ds_read_b128 v[172:175], v172 offset:3072
	ds_read_b128 v[176:179], v194
	ds_read_b128 v[180:183], v194 offset:1024
	ds_read_b128 v[184:187], v194 offset:2048
	ds_read_b128 v[198:201], v194 offset:3072
	s_add_u32 s26, s26, 0x80000
	s_addc_u32 s27, s27, 0
	s_mov_b32 m0, s36
	v_lshl_add_u64 v[246:247], s[26:27], 0, v[132:133]
	ds_read_b128 v[202:205], v159 offset:32768
	ds_read_b128 v[206:209], v159 offset:33792
	ds_read_b128 v[210:213], v159 offset:34816
	ds_read_b128 v[214:217], v159 offset:35840
	ds_read_b128 v[218:221], v159 offset:36864
	ds_read_b128 v[222:225], v159 offset:37888
	ds_read_b128 v[226:229], v159 offset:38912
	ds_read_b128 v[238:241], v159 offset:39936
	global_load_lds_dwordx4 v[246:247], off
	v_lshl_add_u64 v[246:247], s[26:27], 0, v[130:131]
	s_mov_b32 m0, s37
	s_nop 0
	global_load_lds_dwordx4 v[246:247], off
	s_waitcnt vmcnt(8)
	s_waitcnt lgkmcnt(0)
	s_barrier
; #define PG8_STAGE(bufoff, gbase, voff) do { _Pragma("unroll") for (int _i = 0; _i < 2; ++_i) \
;         __builtin_amdgcn_global_load_lds((const unsigned*)((const char*)(gbase) + (voff)[_i]), (PG8_LAS unsigned*)(lds + (bufoff) + ldsw + _i * 8192), 16, 0, 0); } while (0)
; #define PG8_LDA(dst, b, h) do { _Pragma("unroll") for (int m = 0; m < 4; ++m) _Pragma("unroll") for (int k = 0; k < 2; ++k) dst[m][k] = *(const PG8_LAS bf16x8*)(lds + PG8_SA(b, h) + aoff + m * 2048 + k * 1024); } while (0)
; #define PG8_MMA(ai, bj, At, Bt) do { __builtin_amdgcn_s_setprio(1); _Pragma("unroll") for (int m = 0; m < 4; ++m) _Pragma("unroll") for (int n = 0; n < 2; ++n) _Pragma("unroll") for (int k = 0; k < 2; ++k) \
;         acc[ai][bj][m][n] = __builtin_amdgcn_mfma_f32_16x16x32_bf16(Bt[n][k], At[m][k], acc[ai][bj][m][n], 0, 0, 0); __builtin_amdgcn_s_setprio(0); } while (0)
; #define PG8_WAIT_V(n) asm volatile("s_waitcnt vmcnt(" #n ")" ::: "memory")
; #define PG8_WAIT_L(n) asm volatile("s_waitcnt lgkmcnt(" #n ")" ::: "memory")
; #define PG8_BAR __builtin_amdgcn_s_barrier()
; #define PG8_SCHED __builtin_amdgcn_sched_barrier(0)
; template <class Epi, class Sched, bool ALIGN_EPI = false, bool SP2 = false>
; __device__ __forceinline__ void gemm_phase(PG8_LAS unsigned char* lds, const Gemm g, const Sched& S, const Epi& E) {
;     ...
;             PG8_WAIT_V(8); PG8_WAIT_L(0); PG8_BAR; PG8_MMA(0, 0, At, B0); PG8_MMA(0, 1, At, B1); PG8_BAR; PG8_SCHED;
;             PG8_LDA(At, 1, 1); PG8_STAGE(PG8_SB(1, 0), b3, voffB); PG8_STAGE(PG8_SB(1, 1), b3 + hstep, voffB); PG8_STAGE(PG8_SA(1, 0), a3, voffA);
;             PG8_WAIT_V(8); PG8_WAIT_L(0); PG8_BAR; PG8_MMA(1, 0, At, B0); PG8_MMA(1, 1, At, B1); PG8_BAR; PG8_SCHED;
;     ...
;         if constexpr (ALIGN_EPI) { if (wr == 0) PG8_BAR; }
	v_mfma_f32_16x16x32_bf16 v[124:127], v[160:163], v[202:205], v[124:127]
	v_mfma_f32_16x16x32_bf16 v[120:123], v[168:171], v[202:205], v[120:123]
	v_mfma_f32_16x16x32_bf16 v[108:111], v[160:163], v[210:213], v[108:111]
	v_mfma_f32_16x16x32_bf16 v[104:107], v[168:171], v[210:213], v[104:107]
	v_mfma_f32_16x16x32_bf16 v[92:95], v[160:163], v[218:221], v[92:95]
	v_mfma_f32_16x16x32_bf16 v[88:91], v[168:171], v[218:221], v[88:91]
	v_mfma_f32_16x16x32_bf16 v[76:79], v[160:163], v[226:229], v[76:79]
	v_mfma_f32_16x16x32_bf16 v[72:75], v[168:171], v[226:229], v[72:75]
	v_mfma_f32_16x16x32_bf16 v[124:127], v[164:167], v[206:209], v[124:127]
	v_mfma_f32_16x16x32_bf16 v[120:123], v[172:175], v[206:209], v[120:123]
	v_mfma_f32_16x16x32_bf16 v[108:111], v[164:167], v[214:217], v[108:111]
	v_mfma_f32_16x16x32_bf16 v[104:107], v[172:175], v[214:217], v[104:107]
	v_mfma_f32_16x16x32_bf16 v[92:95], v[164:167], v[222:225], v[92:95]
	v_mfma_f32_16x16x32_bf16 v[88:91], v[172:175], v[222:225], v[88:91]
	v_mfma_f32_16x16x32_bf16 v[76:79], v[164:167], v[238:241], v[76:79]
	v_mfma_f32_16x16x32_bf16 v[72:75], v[172:175], v[238:241], v[72:75]
	v_mfma_f32_16x16x32_bf16 v[116:119], v[176:179], v[202:205], v[116:119]
	v_mfma_f32_16x16x32_bf16 v[112:115], v[184:187], v[202:205], v[112:115]
	v_mfma_f32_16x16x32_bf16 v[100:103], v[176:179], v[210:213], v[100:103]
	v_mfma_f32_16x16x32_bf16 v[96:99], v[184:187], v[210:213], v[96:99]
	v_mfma_f32_16x16x32_bf16 v[84:87], v[176:179], v[218:221], v[84:87]
	v_mfma_f32_16x16x32_bf16 v[80:83], v[184:187], v[218:221], v[80:83]
	v_mfma_f32_16x16x32_bf16 v[68:71], v[176:179], v[226:229], v[68:71]
	v_mfma_f32_16x16x32_bf16 v[64:67], v[184:187], v[226:229], v[64:67]
	v_mfma_f32_16x16x32_bf16 v[116:119], v[180:183], v[206:209], v[116:119]
	v_mfma_f32_16x16x32_bf16 v[112:115], v[198:201], v[206:209], v[112:115]
	v_mfma_f32_16x16x32_bf16 v[100:103], v[180:183], v[214:217], v[100:103]
	v_mfma_f32_16x16x32_bf16 v[96:99], v[198:201], v[214:217], v[96:99]
	v_mfma_f32_16x16x32_bf16 v[84:87], v[180:183], v[222:225], v[84:87]
	v_mfma_f32_16x16x32_bf16 v[80:83], v[198:201], v[222:225], v[80:83]
	v_mfma_f32_16x16x32_bf16 v[68:71], v[180:183], v[238:241], v[68:71]
	v_mfma_f32_16x16x32_bf16 v[64:67], v[198:201], v[238:241], v[64:67]
	s_barrier
	s_add_i32 s26, s60, s31
	v_lshl_add_u64 v[154:155], v[154:155], 0, s[78:79]
	s_mov_b32 m0, s26
	ds_read_b128 v[202:205], v159 offset:49152
	ds_read_b128 v[206:209], v159 offset:50176
	ds_read_b128 v[210:213], v159 offset:51200
	ds_read_b128 v[214:217], v159 offset:52224
	ds_read_b128 v[218:221], v159 offset:53248
	ds_read_b128 v[222:225], v159 offset:54272
	ds_read_b128 v[226:229], v159 offset:55296
	ds_read_b128 v[238:241], v159 offset:56320
	global_load_lds_dwordx4 v[154:155], off
	s_add_i32 m0, s26, 0x2000
	s_add_u32 s24, s24, 0x80080
	v_lshl_add_u64 v[154:155], v[232:233], 0, s[78:79]
	s_addc_u32 s25, s25, 0
	s_add_i32 s26, s61, s31
	global_load_lds_dwordx4 v[154:155], off
	v_lshl_add_u64 v[154:155], s[24:25], 0, v[188:189]
	s_mov_b32 m0, s26
	s_nop 0
	global_load_lds_dwordx4 v[154:155], off
	v_lshl_add_u64 v[154:155], s[24:25], 0, v[128:129]
	s_add_i32 m0, s26, 0x2000
	s_nop 0
	global_load_lds_dwordx4 v[154:155], off
	v_lshl_add_u64 v[154:155], v[242:243], 0, s[78:79]
	s_mov_b32 m0, s38
	s_nop 0
	global_load_lds_dwordx4 v[154:155], off
	v_lshl_add_u64 v[154:155], v[244:245], 0, s[78:79]
	s_mov_b32 m0, s39
	s_nop 0
	global_load_lds_dwordx4 v[154:155], off
	s_waitcnt vmcnt(8)
	s_waitcnt lgkmcnt(0)
	s_barrier
	v_mfma_f32_16x16x32_bf16 v[60:63], v[160:163], v[202:205], v[60:63]
	v_mfma_f32_16x16x32_bf16 v[56:59], v[168:171], v[202:205], v[56:59]
	v_mfma_f32_16x16x32_bf16 v[44:47], v[160:163], v[210:213], v[44:47]
	v_mfma_f32_16x16x32_bf16 v[40:43], v[168:171], v[210:213], v[40:43]
	v_mfma_f32_16x16x32_bf16 v[28:31], v[160:163], v[218:221], v[28:31]
	v_mfma_f32_16x16x32_bf16 v[24:27], v[168:171], v[218:221], v[24:27]
	v_mfma_f32_16x16x32_bf16 v[12:15], v[160:163], v[226:229], v[12:15]
	v_mfma_f32_16x16x32_bf16 v[8:11], v[168:171], v[226:229], v[8:11]
	v_mfma_f32_16x16x32_bf16 v[60:63], v[164:167], v[206:209], v[60:63]
	v_mfma_f32_16x16x32_bf16 v[56:59], v[172:175], v[206:209], v[56:59]
	v_mfma_f32_16x16x32_bf16 v[44:47], v[164:167], v[214:217], v[44:47]
	v_mfma_f32_16x16x32_bf16 v[40:43], v[172:175], v[214:217], v[40:43]
	v_mfma_f32_16x16x32_bf16 v[28:31], v[164:167], v[222:225], v[28:31]
	v_mfma_f32_16x16x32_bf16 v[24:27], v[172:175], v[222:225], v[24:27]
	v_mfma_f32_16x16x32_bf16 v[12:15], v[164:167], v[238:241], v[12:15]
	v_mfma_f32_16x16x32_bf16 v[8:11], v[172:175], v[238:241], v[8:11]
	v_mfma_f32_16x16x32_bf16 v[52:55], v[176:179], v[202:205], v[52:55]
	v_mfma_f32_16x16x32_bf16 v[48:51], v[184:187], v[202:205], v[48:51]
	v_mfma_f32_16x16x32_bf16 v[36:39], v[176:179], v[210:213], v[36:39]
	v_mfma_f32_16x16x32_bf16 v[32:35], v[184:187], v[210:213], v[32:35]
	v_mfma_f32_16x16x32_bf16 v[20:23], v[176:179], v[218:221], v[20:23]
	v_mfma_f32_16x16x32_bf16 v[16:19], v[184:187], v[218:221], v[16:19]
	v_mfma_f32_16x16x32_bf16 v[4:7], v[176:179], v[226:229], v[4:7]
	v_mfma_f32_16x16x32_bf16 v[0:3], v[184:187], v[226:229], v[0:3]
	v_mfma_f32_16x16x32_bf16 v[52:55], v[180:183], v[206:209], v[52:55]
	v_mfma_f32_16x16x32_bf16 v[48:51], v[198:201], v[206:209], v[48:51]
	v_mfma_f32_16x16x32_bf16 v[36:39], v[180:183], v[214:217], v[36:39]
	v_mfma_f32_16x16x32_bf16 v[32:35], v[198:201], v[214:217], v[32:35]
	v_mfma_f32_16x16x32_bf16 v[20:23], v[180:183], v[222:225], v[20:23]
	v_mfma_f32_16x16x32_bf16 v[16:19], v[198:201], v[222:225], v[16:19]
	v_mfma_f32_16x16x32_bf16 v[4:7], v[180:183], v[238:241], v[4:7]
	v_mfma_f32_16x16x32_bf16 v[0:3], v[198:201], v[238:241], v[0:3]
	s_barrier
	s_add_i32 s63, s63, 2
	s_add_u32 s8, s8, 0x100
	s_addc_u32 s9, s9, 0
	s_add_u32 s58, s58, 0x100
	s_addc_u32 s62, s62, 0
	s_cmp_gt_u32 s63, 29
	s_cbranch_scc0 .LBB0_684
	s_setprio 0
	s_and_b64 vcc, exec, s[14:15]
	s_cbranch_vccz .LBB0_687
	s_barrier

;     __device__ __forceinline__ bool next(int i, Unit& u) const { Unit t; if (!so.next(i / 3, t)) return false; const int br = i % 3; u.pm = t.pm + br * so.nM; u.pn = t.pn + br * so.nN; return true; }
;     __device__ __forceinline__ bool zero_after(const Unit& u) const { return (u.pn / nN) == 2; }
; #define PG8_STAGE(bufoff, gbase, voff) do { _Pragma("unroll") for (int _i = 0; _i < 2; ++_i) \
;         __builtin_amdgcn_global_load_lds((const unsigned*)((const char*)(gbase) + (voff)[_i]), (PG8_LAS unsigned*)(lds + (bufoff) + ldsw + _i * 8192), 16, 0, 0); } while (0)
; #define PG8_LDA(dst, b, h) do { _Pragma("unroll") for (int m = 0; m < 4; ++m) _Pragma("unroll") for (int k = 0; k < 2; ++k) dst[m][k] = *(const PG8_LAS bf16x8*)(lds + PG8_SA(b, h) + aoff + m * 2048 + k * 1024); } while (0)
; #define PG8_WAIT_V(n) asm volatile("s_waitcnt vmcnt(" #n ")" ::: "memory")
; #define PG8_WAIT_L(n) asm volatile("s_waitcnt lgkmcnt(" #n ")" ::: "memory")
; template <class Epi, class Sched, bool ALIGN_EPI = false, bool SP2 = false>
; __device__ __forceinline__ void gemm_phase(PG8_LAS unsigned char* lds, const Gemm g, const Sched& S, const Epi& E) {
;     ...
;         const bool has_next = S.next(ui + 1, nxt);
;         const char* nA = has_next ? (const char*)g.A + (size_t)nxt.pm * tstep : cA; const char* nB = has_next ? (const char*)g.Bt + (size_t)nxt.pn * tstep : cB;
;         for (int t = 0; t < nt; t += 2) {
;             const bool last = (t == nt - 2);
;             const char* a1 = cA + (size_t)(t + 1) * kstep;
;             const char* a2 = last ? nA : cA + (size_t)(t + 2) * kstep; const char* b2 = last ? nB : cB + (size_t)(t + 2) * kstep;
;             const char* a3 = a2 + kstep; const char* b3 = b2 + kstep;
;             if (last && has_next) S.a_ready(nxt);
;             if constexpr (SP2) {
;             PG8_LDB(B0, 0, 0); PG8_LDB(B1, 0, 1); PG8_SCHED; PG8_LDA(At, 0, 0); PG8_STAGE(PG8_SA(1, 1), a1 + hstep, voffA);
;             PG8_WAIT_V(8); PG8_WAIT_L(0); PG8_BAR; PG8_MMA(0, 0, At, B0); PG8_MMA(0, 1, At, B1); PG8_BAR; PG8_SCHED;
;     ...
;         if (E.zero_after(cur)) {
; #pragma unroll
;         for (int a = 0; a < 2; ++a)
; #pragma unroll
;             for (int b = 0; b < 2; ++b)
; #pragma unroll
;                 for (int m = 0; m < 4; ++m)
; #pragma unroll
;                     for (int n = 0; n < 2; ++n) acc[a][b][m][n] = (f32x4){0.f, 0.f, 0.f, 0.f};
.LBB0_756:
	s_ashr_i32 s21, s20, 31
	s_lshl_b64 s[22:23], s[20:21], 22
	s_add_u32 s22, s2, s22
	s_addc_u32 s23, s34, s23
	s_and_b64 s[24:25], s[6:7], exec
	s_cselect_b32 s21, s23, s27
	s_cselect_b32 s63, s22, s26
	s_ashr_i32 s19, s18, 31
	s_lshl_b64 s[24:25], s[18:19], 22
	s_add_u32 s24, s35, s24
	s_addc_u32 s25, s36, s25
	s_and_b64 s[30:31], s[6:7], exec
	s_cselect_b32 s19, s25, s29
	s_cselect_b32 s66, s24, s28
	s_add_u32 s26, s26, 0x200080
	s_addc_u32 s27, s27, 0
	s_add_u32 s67, s28, 0x100
	v_mov_b32_e32 v0, 0
	s_addc_u32 s68, s29, 0
	s_mov_b32 s72, -2
	v_mov_b32_e32 v1, v0
	v_mov_b32_e32 v2, v0
	v_mov_b32_e32 v3, v0
	v_mov_b32_e32 v4, v0
	v_mov_b32_e32 v5, v0
	v_mov_b32_e32 v6, v0
	v_mov_b32_e32 v7, v0
	v_mov_b32_e32 v16, v0
	v_mov_b32_e32 v17, v0
	v_mov_b32_e32 v18, v0
	v_mov_b32_e32 v19, v0
	v_mov_b32_e32 v20, v0
	v_mov_b32_e32 v21, v0
	v_mov_b32_e32 v22, v0
	v_mov_b32_e32 v23, v0
	v_mov_b32_e32 v32, v0
	v_mov_b32_e32 v33, v0
	v_mov_b32_e32 v34, v0
	v_mov_b32_e32 v35, v0
	v_mov_b32_e32 v36, v0
	v_mov_b32_e32 v37, v0
	v_mov_b32_e32 v38, v0
	v_mov_b32_e32 v39, v0
	v_mov_b32_e32 v48, v0
	v_mov_b32_e32 v49, v0
	v_mov_b32_e32 v50, v0
	v_mov_b32_e32 v51, v0
	v_mov_b32_e32 v52, v0
	v_mov_b32_e32 v53, v0
	v_mov_b32_e32 v54, v0
	v_mov_b32_e32 v55, v0
	v_mov_b32_e32 v8, v0
	v_mov_b32_e32 v9, v0
	v_mov_b32_e32 v10, v0
	v_mov_b32_e32 v11, v0
	v_mov_b32_e32 v12, v0
	v_mov_b32_e32 v13, v0
	v_mov_b32_e32 v14, v0
	v_mov_b32_e32 v15, v0
	v_mov_b32_e32 v24, v0
	v_mov_b32_e32 v25, v0
	v_mov_b32_e32 v26, v0
	v_mov_b32_e32 v27, v0
	v_mov_b32_e32 v28, v0
	v_mov_b32_e32 v29, v0
	v_mov_b32_e32 v30, v0
	v_mov_b32_e32 v31, v0
	v_mov_b32_e32 v40, v0
	v_mov_b32_e32 v41, v0
	v_mov_b32_e32 v42, v0
	v_mov_b32_e32 v43, v0
	v_mov_b32_e32 v44, v0
	v_mov_b32_e32 v45, v0
	v_mov_b32_e32 v46, v0
	v_mov_b32_e32 v47, v0
	v_mov_b32_e32 v56, v0
	v_mov_b32_e32 v57, v0
	v_mov_b32_e32 v58, v0
	v_mov_b32_e32 v59, v0
	v_mov_b32_e32 v60, v0
	v_mov_b32_e32 v61, v0
	v_mov_b32_e32 v62, v0
	v_mov_b32_e32 v63, v0
	v_mov_b32_e32 v64, v0
	v_mov_b32_e32 v65, v0
	v_mov_b32_e32 v66, v0
	v_mov_b32_e32 v67, v0
	v_mov_b32_e32 v68, v0
	v_mov_b32_e32 v69, v0
	v_mov_b32_e32 v70, v0
	v_mov_b32_e32 v71, v0
	v_mov_b32_e32 v80, v0
	v_mov_b32_e32 v81, v0
	v_mov_b32_e32 v82, v0
	v_mov_b32_e32 v83, v0
	v_mov_b32_e32 v84, v0
	v_mov_b32_e32 v85, v0
	v_mov_b32_e32 v86, v0
	v_mov_b32_e32 v87, v0
	v_mov_b32_e32 v96, v0
	v_mov_b32_e32 v97, v0
	v_mov_b32_e32 v98, v0
	v_mov_b32_e32 v99, v0
	v_mov_b32_e32 v100, v0
	v_mov_b32_e32 v101, v0
	v_mov_b32_e32 v102, v0
	v_mov_b32_e32 v103, v0
	v_mov_b32_e32 v128, v0
	v_mov_b32_e32 v129, v0
	v_mov_b32_e32 v130, v0
	v_mov_b32_e32 v131, v0
	v_mov_b32_e32 v136, v0
	v_mov_b32_e32 v137, v0
	v_mov_b32_e32 v138, v0
	v_mov_b32_e32 v139, v0
	v_mov_b32_e32 v72, v0
	v_mov_b32_e32 v73, v0
	v_mov_b32_e32 v74, v0
	v_mov_b32_e32 v75, v0
	v_mov_b32_e32 v76, v0
	v_mov_b32_e32 v77, v0
	v_mov_b32_e32 v78, v0
	v_mov_b32_e32 v79, v0
	v_mov_b32_e32 v88, v0
	v_mov_b32_e32 v89, v0
	v_mov_b32_e32 v90, v0
	v_mov_b32_e32 v91, v0
	v_mov_b32_e32 v92, v0
	v_mov_b32_e32 v93, v0
	v_mov_b32_e32 v94, v0
	v_mov_b32_e32 v95, v0
	v_mov_b32_e32 v104, v0
	v_mov_b32_e32 v105, v0
	v_mov_b32_e32 v106, v0
	v_mov_b32_e32 v107, v0
	v_mov_b32_e32 v108, v0
	v_mov_b32_e32 v109, v0
	v_mov_b32_e32 v110, v0
	v_mov_b32_e32 v111, v0
	v_mov_b32_e32 v156, v0
	v_mov_b32_e32 v157, v0
	v_mov_b32_e32 v158, v0
	v_mov_b32_e32 v159, v0
	v_mov_b32_e32 v160, v0
	v_mov_b32_e32 v161, v0
	v_mov_b32_e32 v162, v0
	v_mov_b32_e32 v163, v0
	s_cmp_eq_u64 s[16:17], 0
	s_cbranch_scc0 .Lprio_skip_757
	s_setprio 1
.Lprio_skip_757:
.LBB0_757:
	s_add_u32 s28, s26, 0xffe00080
	s_addc_u32 s29, s27, -1
	s_add_i32 s60, 0, 0x10000
	s_cmpk_eq_i32 s72, 0x7c
	s_cselect_b32 s31, s21, s29
	s_cselect_b32 s30, s63, s28
	s_cselect_b32 s29, s19, s68
	s_cselect_b32 s28, s66, s67
	s_add_i32 s73, 0, 0x14000
	v_add_u32_e32 v124, s60, v239
	v_add_u32_e32 v148, s73, v239
	ds_read_b128 v[112:115], v124
	ds_read_b128 v[116:119], v124 offset:1024
	ds_read_b128 v[120:123], v124 offset:2048
	ds_read_b128 v[124:127], v124 offset:3072
	ds_read_b128 v[132:135], v148
	ds_read_b128 v[140:143], v148 offset:1024
	ds_read_b128 v[144:147], v148 offset:2048
	ds_read_b128 v[148:151], v148 offset:3072
	v_lshl_add_u64 v[212:213], s[26:27], 0, v[204:205]
	s_add_i32 m0, s38, 0xc000
	ds_read_b128 v[152:155], v241
	ds_read_b128 v[164:167], v241 offset:1024
	ds_read_b128 v[168:171], v241 offset:2048
	ds_read_b128 v[172:175], v241 offset:3072
	ds_read_b128 v[176:179], v241 offset:4096
	ds_read_b128 v[180:183], v241 offset:5120
	ds_read_b128 v[184:187], v241 offset:6144
	ds_read_b128 v[208:211], v241 offset:7168
	global_load_lds_dwordx4 v[212:213], off
	v_lshl_add_u64 v[212:213], s[26:27], 0, v[206:207]
	s_add_i32 m0, s38, 0xe000
	s_nop 0
	global_load_lds_dwordx4 v[212:213], off
	s_waitcnt vmcnt(8)
	s_waitcnt lgkmcnt(0)
	s_barrier
; #define PG8_STAGE(bufoff, gbase, voff) do { _Pragma("unroll") for (int _i = 0; _i < 2; ++_i) \
;         __builtin_amdgcn_global_load_lds((const unsigned*)((const char*)(gbase) + (voff)[_i]), (PG8_LAS unsigned*)(lds + (bufoff) + ldsw + _i * 8192), 16, 0, 0); } while (0)
; #define PG8_LDA(dst, b, h) do { _Pragma("unroll") for (int m = 0; m < 4; ++m) _Pragma("unroll") for (int k = 0; k < 2; ++k) dst[m][k] = *(const PG8_LAS bf16x8*)(lds + PG8_SA(b, h) + aoff + m * 2048 + k * 1024); } while (0)
; #define PG8_MMA(ai, bj, At, Bt) do { __builtin_amdgcn_s_setprio(1); _Pragma("unroll") for (int m = 0; m < 4; ++m) _Pragma("unroll") for (int n = 0; n < 2; ++n) _Pragma("unroll") for (int k = 0; k < 2; ++k) \
;         acc[ai][bj][m][n] = __builtin_amdgcn_mfma_f32_16x16x32_bf16(Bt[n][k], At[m][k], acc[ai][bj][m][n], 0, 0, 0); __builtin_amdgcn_s_setprio(0); } while (0)
; #define PG8_WAIT_V(n) asm volatile("s_waitcnt vmcnt(" #n ")" ::: "memory")
; #define PG8_WAIT_L(n) asm volatile("s_waitcnt lgkmcnt(" #n ")" ::: "memory")
; #define PG8_BAR __builtin_amdgcn_s_barrier()
; #define PG8_SCHED __builtin_amdgcn_sched_barrier(0)
; template <class Epi, class Sched, bool ALIGN_EPI = false, bool SP2 = false>
; __device__ __forceinline__ void gemm_phase(PG8_LAS unsigned char* lds, const Gemm g, const Sched& S, const Epi& E) {
;     ...
;             PG8_WAIT_V(8); PG8_WAIT_L(0); PG8_BAR; PG8_MMA(0, 0, At, B0); PG8_MMA(0, 1, At, B1); PG8_BAR; PG8_SCHED;
;             PG8_LDA(At, 0, 1); PG8_STAGE(PG8_SB(0, 0), b2, voffB); PG8_STAGE(PG8_SB(0, 1), b2 + hstep, voffB); PG8_STAGE(PG8_SA(0, 0), a2, voffA);
;             PG8_WAIT_V(8); PG8_WAIT_L(0); PG8_BAR; PG8_MMA(1, 0, At, B0); PG8_MMA(1, 1, At, B1); PG8_BAR; PG8_SCHED;
	v_mfma_f32_16x16x32_bf16 v[160:163], v[112:115], v[152:155], v[160:163]
	v_mfma_f32_16x16x32_bf16 v[156:159], v[120:123], v[152:155], v[156:159]
	v_mfma_f32_16x16x32_bf16 v[108:111], v[112:115], v[168:171], v[108:111]
	v_mfma_f32_16x16x32_bf16 v[104:107], v[120:123], v[168:171], v[104:107]
	v_mfma_f32_16x16x32_bf16 v[92:95], v[112:115], v[176:179], v[92:95]
	v_mfma_f32_16x16x32_bf16 v[88:91], v[120:123], v[176:179], v[88:91]
	v_mfma_f32_16x16x32_bf16 v[76:79], v[112:115], v[184:187], v[76:79]
	v_mfma_f32_16x16x32_bf16 v[72:75], v[120:123], v[184:187], v[72:75]
	v_mfma_f32_16x16x32_bf16 v[160:163], v[116:119], v[164:167], v[160:163]
	v_mfma_f32_16x16x32_bf16 v[156:159], v[124:127], v[164:167], v[156:159]
	v_mfma_f32_16x16x32_bf16 v[108:111], v[116:119], v[172:175], v[108:111]
	v_mfma_f32_16x16x32_bf16 v[104:107], v[124:127], v[172:175], v[104:107]
	v_mfma_f32_16x16x32_bf16 v[92:95], v[116:119], v[180:183], v[92:95]
	v_mfma_f32_16x16x32_bf16 v[88:91], v[124:127], v[180:183], v[88:91]
	v_mfma_f32_16x16x32_bf16 v[76:79], v[116:119], v[208:211], v[76:79]
	v_mfma_f32_16x16x32_bf16 v[72:75], v[124:127], v[208:211], v[72:75]
	v_mfma_f32_16x16x32_bf16 v[136:139], v[132:135], v[152:155], v[136:139]
	v_mfma_f32_16x16x32_bf16 v[128:131], v[144:147], v[152:155], v[128:131]
	v_mfma_f32_16x16x32_bf16 v[100:103], v[132:135], v[168:171], v[100:103]
	v_mfma_f32_16x16x32_bf16 v[96:99], v[144:147], v[168:171], v[96:99]
	v_mfma_f32_16x16x32_bf16 v[84:87], v[132:135], v[176:179], v[84:87]
	v_mfma_f32_16x16x32_bf16 v[80:83], v[144:147], v[176:179], v[80:83]
	v_mfma_f32_16x16x32_bf16 v[68:71], v[132:135], v[184:187], v[68:71]
	v_mfma_f32_16x16x32_bf16 v[64:67], v[144:147], v[184:187], v[64:67]
	v_mfma_f32_16x16x32_bf16 v[136:139], v[140:143], v[164:167], v[136:139]
	v_mfma_f32_16x16x32_bf16 v[128:131], v[148:151], v[164:167], v[128:131]
	v_mfma_f32_16x16x32_bf16 v[100:103], v[140:143], v[172:175], v[100:103]
	v_mfma_f32_16x16x32_bf16 v[96:99], v[148:151], v[172:175], v[96:99]
	v_mfma_f32_16x16x32_bf16 v[84:87], v[140:143], v[180:183], v[84:87]
	v_mfma_f32_16x16x32_bf16 v[80:83], v[148:151], v[180:183], v[80:83]
	v_mfma_f32_16x16x32_bf16 v[68:71], v[140:143], v[208:211], v[68:71]
	v_mfma_f32_16x16x32_bf16 v[64:67], v[148:151], v[208:211], v[64:67]
	s_barrier
	s_add_i32 s60, s60, s37
	v_lshl_add_u64 v[212:213], s[28:29], 0, v[188:189]
	s_mov_b32 m0, s60
	ds_read_b128 v[152:155], v241 offset:16384
	ds_read_b128 v[164:167], v241 offset:17408
	ds_read_b128 v[168:171], v241 offset:18432
	ds_read_b128 v[172:175], v241 offset:19456
	ds_read_b128 v[176:179], v241 offset:20480
	ds_read_b128 v[180:183], v241 offset:21504
	ds_read_b128 v[184:187], v241 offset:22528
	ds_read_b128 v[208:211], v241 offset:23552
	global_load_lds_dwordx4 v[212:213], off
	s_add_i32 m0, s60, 0x2000
	s_add_u32 s60, s28, 0x200000
	v_lshl_add_u64 v[214:215], s[28:29], 0, v[198:199]
	s_addc_u32 s61, s29, 0
	s_add_i32 s73, s73, s37
	global_load_lds_dwordx4 v[214:215], off
	v_lshl_add_u64 v[216:217], s[60:61], 0, v[188:189]
	s_mov_b32 m0, s73
	v_lshl_add_u64 v[218:219], s[30:31], 0, v[200:201]
	global_load_lds_dwordx4 v[216:217], off
	v_lshl_add_u64 v[216:217], s[60:61], 0, v[198:199]
	s_add_i32 m0, s73, 0x2000
	s_nop 0
	global_load_lds_dwordx4 v[216:217], off
	v_lshl_add_u64 v[216:217], s[30:31], 0, v[202:203]
	s_mov_b32 m0, s38
	s_nop 0
	global_load_lds_dwordx4 v[216:217], off
	s_mov_b32 m0, s39
	s_nop 0
	global_load_lds_dwordx4 v[218:219], off
	s_waitcnt vmcnt(8)
	s_waitcnt lgkmcnt(0)
	s_barrier
	v_mfma_f32_16x16x32_bf16 v[60:63], v[112:115], v[152:155], v[60:63]
	v_mfma_f32_16x16x32_bf16 v[56:59], v[120:123], v[152:155], v[56:59]
	v_mfma_f32_16x16x32_bf16 v[44:47], v[112:115], v[168:171], v[44:47]
	v_mfma_f32_16x16x32_bf16 v[40:43], v[120:123], v[168:171], v[40:43]
	v_mfma_f32_16x16x32_bf16 v[28:31], v[112:115], v[176:179], v[28:31]
	v_mfma_f32_16x16x32_bf16 v[24:27], v[120:123], v[176:179], v[24:27]
	v_mfma_f32_16x16x32_bf16 v[12:15], v[112:115], v[184:187], v[12:15]
	v_mfma_f32_16x16x32_bf16 v[8:11], v[120:123], v[184:187], v[8:11]
	v_mfma_f32_16x16x32_bf16 v[60:63], v[116:119], v[164:167], v[60:63]
	v_mfma_f32_16x16x32_bf16 v[56:59], v[124:127], v[164:167], v[56:59]
	v_mfma_f32_16x16x32_bf16 v[44:47], v[116:119], v[172:175], v[44:47]
	v_mfma_f32_16x16x32_bf16 v[40:43], v[124:127], v[172:175], v[40:43]
	v_mfma_f32_16x16x32_bf16 v[28:31], v[116:119], v[180:183], v[28:31]
	v_mfma_f32_16x16x32_bf16 v[24:27], v[124:127], v[180:183], v[24:27]
	v_mfma_f32_16x16x32_bf16 v[12:15], v[116:119], v[208:211], v[12:15]
	v_mfma_f32_16x16x32_bf16 v[8:11], v[124:127], v[208:211], v[8:11]
	v_mfma_f32_16x16x32_bf16 v[52:55], v[132:135], v[152:155], v[52:55]
	v_mfma_f32_16x16x32_bf16 v[48:51], v[144:147], v[152:155], v[48:51]
	v_mfma_f32_16x16x32_bf16 v[36:39], v[132:135], v[168:171], v[36:39]
	v_mfma_f32_16x16x32_bf16 v[32:35], v[144:147], v[168:171], v[32:35]
	v_mfma_f32_16x16x32_bf16 v[20:23], v[132:135], v[176:179], v[20:23]
	v_mfma_f32_16x16x32_bf16 v[16:19], v[144:147], v[176:179], v[16:19]
	v_mfma_f32_16x16x32_bf16 v[4:7], v[132:135], v[184:187], v[4:7]
	v_mfma_f32_16x16x32_bf16 v[0:3], v[144:147], v[184:187], v[0:3]
	v_mfma_f32_16x16x32_bf16 v[52:55], v[140:143], v[164:167], v[52:55]
	v_mfma_f32_16x16x32_bf16 v[48:51], v[148:151], v[164:167], v[48:51]
	v_mfma_f32_16x16x32_bf16 v[36:39], v[140:143], v[172:175], v[36:39]
	v_mfma_f32_16x16x32_bf16 v[32:35], v[148:151], v[172:175], v[32:35]
	v_mfma_f32_16x16x32_bf16 v[20:23], v[140:143], v[180:183], v[20:23]
	v_mfma_f32_16x16x32_bf16 v[16:19], v[148:151], v[180:183], v[16:19]
	v_mfma_f32_16x16x32_bf16 v[4:7], v[140:143], v[208:211], v[4:7]
	v_mfma_f32_16x16x32_bf16 v[0:3], v[148:151], v[208:211], v[0:3]
	s_barrier
; #define PG8_STAGE(bufoff, gbase, voff) do { _Pragma("unroll") for (int _i = 0; _i < 2; ++_i) \
;         __builtin_amdgcn_global_load_lds((const unsigned*)((const char*)(gbase) + (voff)[_i]), (PG8_LAS unsigned*)(lds + (bufoff) + ldsw + _i * 8192), 16, 0, 0); } while (0)
; #define PG8_LDA(dst, b, h) do { _Pragma("unroll") for (int m = 0; m < 4; ++m) _Pragma("unroll") for (int k = 0; k < 2; ++k) dst[m][k] = *(const PG8_LAS bf16x8*)(lds + PG8_SA(b, h) + aoff + m * 2048 + k * 1024); } while (0)
; #define PG8_LDB(dst, b, h) do { _Pragma("unroll") for (int n = 0; n < 2; ++n) _Pragma("unroll") for (int k = 0; k < 2; ++k) dst[n][k] = *(const PG8_LAS bf16x8*)(lds + PG8_SB(b, h) + boff + n * 2048 + k * 1024); } while (0)
; #define PG8_MMA(ai, bj, At, Bt) do { __builtin_amdgcn_s_setprio(1); _Pragma("unroll") for (int m = 0; m < 4; ++m) _Pragma("unroll") for (int n = 0; n < 2; ++n) _Pragma("unroll") for (int k = 0; k < 2; ++k) \
;         acc[ai][bj][m][n] = __builtin_amdgcn_mfma_f32_16x16x32_bf16(Bt[n][k], At[m][k], acc[ai][bj][m][n], 0, 0, 0); __builtin_amdgcn_s_setprio(0); } while (0)
; #define PG8_WAIT_V(n) asm volatile("s_waitcnt vmcnt(" #n ")" ::: "memory")
; #define PG8_WAIT_L(n) asm volatile("s_waitcnt lgkmcnt(" #n ")" ::: "memory")
; #define PG8_BAR __builtin_amdgcn_s_barrier()
; #define PG8_SCHED __builtin_amdgcn_sched_barrier(0)
; template <class Epi, class Sched, bool ALIGN_EPI = false, bool SP2 = false>
; __device__ __forceinline__ void gemm_phase(PG8_LAS unsigned char* lds, const Gemm g, const Sched& S, const Epi& E) {
;     ...
;             PG8_LDB(B0, 1, 0); PG8_LDB(B1, 1, 1); PG8_SCHED; PG8_LDA(At, 1, 0); PG8_STAGE(PG8_SA(0, 1), a2 + hstep, voffA);
;             PG8_WAIT_V(8); PG8_WAIT_L(0); PG8_BAR; PG8_MMA(0, 0, At, B0); PG8_MMA(0, 1, At, B1); PG8_BAR; PG8_SCHED;
	s_add_i32 s60, 0, 0x18000
	s_add_i32 s61, 0, 0x1c000
	v_add_u32_e32 v124, s60, v239
	v_add_u32_e32 v148, s61, v239
	ds_read_b128 v[112:115], v124
	ds_read_b128 v[116:119], v124 offset:1024
	ds_read_b128 v[120:123], v124 offset:2048
	ds_read_b128 v[124:127], v124 offset:3072
	ds_read_b128 v[132:135], v148
	ds_read_b128 v[140:143], v148 offset:1024
	ds_read_b128 v[144:147], v148 offset:2048
	ds_read_b128 v[148:151], v148 offset:3072
	s_add_u32 s30, s30, 0x200000
	s_addc_u32 s31, s31, 0
	s_mov_b32 m0, s40
	v_lshl_add_u64 v[220:221], s[30:31], 0, v[202:203]
	ds_read_b128 v[152:155], v241 offset:32768
	ds_read_b128 v[164:167], v241 offset:33792
	ds_read_b128 v[168:171], v241 offset:34816
	ds_read_b128 v[172:175], v241 offset:35840
	ds_read_b128 v[176:179], v241 offset:36864
	ds_read_b128 v[180:183], v241 offset:37888
	ds_read_b128 v[184:187], v241 offset:38912
	ds_read_b128 v[208:211], v241 offset:39936
	global_load_lds_dwordx4 v[220:221], off
	v_lshl_add_u64 v[220:221], s[30:31], 0, v[200:201]
	s_mov_b32 m0, s41
	s_nop 0
	global_load_lds_dwordx4 v[220:221], off
	s_waitcnt vmcnt(8)
	s_waitcnt lgkmcnt(0)
	s_barrier
	v_mfma_f32_16x16x32_bf16 v[160:163], v[112:115], v[152:155], v[160:163]
	v_mfma_f32_16x16x32_bf16 v[156:159], v[120:123], v[152:155], v[156:159]
	v_mfma_f32_16x16x32_bf16 v[108:111], v[112:115], v[168:171], v[108:111]
	v_mfma_f32_16x16x32_bf16 v[104:107], v[120:123], v[168:171], v[104:107]
	v_mfma_f32_16x16x32_bf16 v[92:95], v[112:115], v[176:179], v[92:95]
	v_mfma_f32_16x16x32_bf16 v[88:91], v[120:123], v[176:179], v[88:91]
	v_mfma_f32_16x16x32_bf16 v[76:79], v[112:115], v[184:187], v[76:79]
	v_mfma_f32_16x16x32_bf16 v[72:75], v[120:123], v[184:187], v[72:75]
	v_mfma_f32_16x16x32_bf16 v[160:163], v[116:119], v[164:167], v[160:163]
	v_mfma_f32_16x16x32_bf16 v[156:159], v[124:127], v[164:167], v[156:159]
	v_mfma_f32_16x16x32_bf16 v[108:111], v[116:119], v[172:175], v[108:111]
	v_mfma_f32_16x16x32_bf16 v[104:107], v[124:127], v[172:175], v[104:107]
	v_mfma_f32_16x16x32_bf16 v[92:95], v[116:119], v[180:183], v[92:95]
	v_mfma_f32_16x16x32_bf16 v[88:91], v[124:127], v[180:183], v[88:91]
	v_mfma_f32_16x16x32_bf16 v[76:79], v[116:119], v[208:211], v[76:79]
	v_mfma_f32_16x16x32_bf16 v[72:75], v[124:127], v[208:211], v[72:75]
	v_mfma_f32_16x16x32_bf16 v[136:139], v[132:135], v[152:155], v[136:139]
	v_mfma_f32_16x16x32_bf16 v[128:131], v[144:147], v[152:155], v[128:131]
	v_mfma_f32_16x16x32_bf16 v[100:103], v[132:135], v[168:171], v[100:103]
	v_mfma_f32_16x16x32_bf16 v[96:99], v[144:147], v[168:171], v[96:99]
	v_mfma_f32_16x16x32_bf16 v[84:87], v[132:135], v[176:179], v[84:87]
	v_mfma_f32_16x16x32_bf16 v[80:83], v[144:147], v[176:179], v[80:83]
	v_mfma_f32_16x16x32_bf16 v[68:71], v[132:135], v[184:187], v[68:71]
	v_mfma_f32_16x16x32_bf16 v[64:67], v[144:147], v[184:187], v[64:67]
	v_mfma_f32_16x16x32_bf16 v[136:139], v[140:143], v[164:167], v[136:139]
	v_mfma_f32_16x16x32_bf16 v[128:131], v[148:151], v[164:167], v[128:131]
	v_mfma_f32_16x16x32_bf16 v[100:103], v[140:143], v[172:175], v[100:103]
	v_mfma_f32_16x16x32_bf16 v[96:99], v[148:151], v[172:175], v[96:99]
	v_mfma_f32_16x16x32_bf16 v[84:87], v[140:143], v[180:183], v[84:87]
	v_mfma_f32_16x16x32_bf16 v[80:83], v[148:151], v[180:183], v[80:83]
	v_mfma_f32_16x16x32_bf16 v[68:71], v[140:143], v[208:211], v[68:71]
	v_mfma_f32_16x16x32_bf16 v[64:67], v[148:151], v[208:211], v[64:67]
	s_barrier
; #define PG8_STAGE(bufoff, gbase, voff) do { _Pragma("unroll") for (int _i = 0; _i < 2; ++_i) \
;         __builtin_amdgcn_global_load_lds((const unsigned*)((const char*)(gbase) + (voff)[_i]), (PG8_LAS unsigned*)(lds + (bufoff) + ldsw + _i * 8192), 16, 0, 0); } while (0)
; #define PG8_LDA(dst, b, h) do { _Pragma("unroll") for (int m = 0; m < 4; ++m) _Pragma("unroll") for (int k = 0; k < 2; ++k) dst[m][k] = *(const PG8_LAS bf16x8*)(lds + PG8_SA(b, h) + aoff + m * 2048 + k * 1024); } while (0)
; #define PG8_MMA(ai, bj, At, Bt) do { __builtin_amdgcn_s_setprio(1); _Pragma("unroll") for (int m = 0; m < 4; ++m) _Pragma("unroll") for (int n = 0; n < 2; ++n) _Pragma("unroll") for (int k = 0; k < 2; ++k) \
;         acc[ai][bj][m][n] = __builtin_amdgcn_mfma_f32_16x16x32_bf16(Bt[n][k], At[m][k], acc[ai][bj][m][n], 0, 0, 0); __builtin_amdgcn_s_setprio(0); } while (0)
; #define PG8_WAIT_V(n) asm volatile("s_waitcnt vmcnt(" #n ")" ::: "memory")
; #define PG8_WAIT_L(n) asm volatile("s_waitcnt lgkmcnt(" #n ")" ::: "memory")
; #define PG8_BAR __builtin_amdgcn_s_barrier()
; #define PG8_SCHED __builtin_amdgcn_sched_barrier(0)
; template <class Epi, class Sched, bool ALIGN_EPI = false, bool SP2 = false>
; __device__ __forceinline__ void gemm_phase(PG8_LAS unsigned char* lds, const Gemm g, const Sched& S, const Epi& E) {
;     ...
;             PG8_LDA(At, 1, 1); PG8_STAGE(PG8_SB(1, 0), b3, voffB); PG8_STAGE(PG8_SB(1, 1), b3 + hstep, voffB); PG8_STAGE(PG8_SA(1, 0), a3, voffA);
;             PG8_WAIT_V(8); PG8_WAIT_L(0); PG8_BAR; PG8_MMA(1, 0, At, B0); PG8_MMA(1, 1, At, B1); PG8_BAR; PG8_SCHED;
;     ...
;         if constexpr (ALIGN_EPI) { if (wr == 0) PG8_BAR; }
	s_add_i32 s30, s60, s37
	v_lshl_add_u64 v[212:213], v[212:213], 0, s[78:79]
	s_mov_b32 m0, s30
	ds_read_b128 v[152:155], v241 offset:49152
	ds_read_b128 v[164:167], v241 offset:50176
	ds_read_b128 v[168:171], v241 offset:51200
	ds_read_b128 v[172:175], v241 offset:52224
	ds_read_b128 v[176:179], v241 offset:53248
	ds_read_b128 v[180:183], v241 offset:54272
	ds_read_b128 v[184:187], v241 offset:55296
	ds_read_b128 v[208:211], v241 offset:56320
	global_load_lds_dwordx4 v[212:213], off
	s_add_i32 m0, s30, 0x2000
	s_add_u32 s28, s28, 0x200080
	v_lshl_add_u64 v[212:213], v[214:215], 0, s[78:79]
	s_addc_u32 s29, s29, 0
	s_add_i32 s30, s61, s37
	global_load_lds_dwordx4 v[212:213], off
	v_lshl_add_u64 v[212:213], s[28:29], 0, v[188:189]
	s_mov_b32 m0, s30
	s_nop 0
	global_load_lds_dwordx4 v[212:213], off
	v_lshl_add_u64 v[212:213], s[28:29], 0, v[198:199]
	s_add_i32 m0, s30, 0x2000
	s_nop 0
	global_load_lds_dwordx4 v[212:213], off
	v_lshl_add_u64 v[212:213], v[216:217], 0, s[78:79]
	s_mov_b32 m0, s44
	s_nop 0
	global_load_lds_dwordx4 v[212:213], off
	v_lshl_add_u64 v[212:213], v[218:219], 0, s[78:79]
	s_mov_b32 m0, s45
	s_nop 0
	global_load_lds_dwordx4 v[212:213], off
	s_waitcnt vmcnt(8)
	s_waitcnt lgkmcnt(0)
	s_barrier
	v_mfma_f32_16x16x32_bf16 v[60:63], v[112:115], v[152:155], v[60:63]
	v_mfma_f32_16x16x32_bf16 v[56:59], v[120:123], v[152:155], v[56:59]
	v_mfma_f32_16x16x32_bf16 v[44:47], v[112:115], v[168:171], v[44:47]
	v_mfma_f32_16x16x32_bf16 v[40:43], v[120:123], v[168:171], v[40:43]
	v_mfma_f32_16x16x32_bf16 v[28:31], v[112:115], v[176:179], v[28:31]
	v_mfma_f32_16x16x32_bf16 v[24:27], v[120:123], v[176:179], v[24:27]
	v_mfma_f32_16x16x32_bf16 v[12:15], v[112:115], v[184:187], v[12:15]
	v_mfma_f32_16x16x32_bf16 v[8:11], v[120:123], v[184:187], v[8:11]
	v_mfma_f32_16x16x32_bf16 v[60:63], v[116:119], v[164:167], v[60:63]
	v_mfma_f32_16x16x32_bf16 v[56:59], v[124:127], v[164:167], v[56:59]
	v_mfma_f32_16x16x32_bf16 v[44:47], v[116:119], v[172:175], v[44:47]
	v_mfma_f32_16x16x32_bf16 v[40:43], v[124:127], v[172:175], v[40:43]
	v_mfma_f32_16x16x32_bf16 v[28:31], v[116:119], v[180:183], v[28:31]
	v_mfma_f32_16x16x32_bf16 v[24:27], v[124:127], v[180:183], v[24:27]
	v_mfma_f32_16x16x32_bf16 v[12:15], v[116:119], v[208:211], v[12:15]
	v_mfma_f32_16x16x32_bf16 v[8:11], v[124:127], v[208:211], v[8:11]
	v_mfma_f32_16x16x32_bf16 v[52:55], v[132:135], v[152:155], v[52:55]
	v_mfma_f32_16x16x32_bf16 v[48:51], v[144:147], v[152:155], v[48:51]
	v_mfma_f32_16x16x32_bf16 v[36:39], v[132:135], v[168:171], v[36:39]
	v_mfma_f32_16x16x32_bf16 v[32:35], v[144:147], v[168:171], v[32:35]
	v_mfma_f32_16x16x32_bf16 v[20:23], v[132:135], v[176:179], v[20:23]
	v_mfma_f32_16x16x32_bf16 v[16:19], v[144:147], v[176:179], v[16:19]
	v_mfma_f32_16x16x32_bf16 v[4:7], v[132:135], v[184:187], v[4:7]
	v_mfma_f32_16x16x32_bf16 v[0:3], v[144:147], v[184:187], v[0:3]
	v_mfma_f32_16x16x32_bf16 v[52:55], v[140:143], v[164:167], v[52:55]
	v_mfma_f32_16x16x32_bf16 v[48:51], v[148:151], v[164:167], v[48:51]
	v_mfma_f32_16x16x32_bf16 v[36:39], v[140:143], v[172:175], v[36:39]
	v_mfma_f32_16x16x32_bf16 v[32:35], v[148:151], v[172:175], v[32:35]
	v_mfma_f32_16x16x32_bf16 v[20:23], v[140:143], v[180:183], v[20:23]
	v_mfma_f32_16x16x32_bf16 v[16:19], v[148:151], v[180:183], v[16:19]
	v_mfma_f32_16x16x32_bf16 v[4:7], v[140:143], v[208:211], v[4:7]
	v_mfma_f32_16x16x32_bf16 v[0:3], v[148:151], v[208:211], v[0:3]
	s_barrier
	s_add_i32 s72, s72, 2
	s_add_u32 s26, s26, 0x100
	s_addc_u32 s27, s27, 0
	s_add_u32 s67, s67, 0x100
	s_addc_u32 s68, s68, 0
	s_cmpk_gt_u32 s72, 0x7d
	s_cbranch_scc0 .LBB0_757
	s_setprio 0
	s_and_b64 vcc, exec, s[16:17]
	s_cbranch_vccz .LBB0_760
	s_barrier

;     __device__ __forceinline__ bool next(int i, Unit& u) const { Unit t; if (!so.next(i / 3, t)) return false; const int br = i % 3; u.pm = t.pm + br * so.nM; u.pn = t.pn + br * so.nN; return true; }
; template <class Epi, class Sched, bool ALIGN_EPI = false, bool SP2 = false>
; __device__ __forceinline__ void gemm_phase(PG8_LAS unsigned char* lds, const Gemm g, const Sched& S, const Epi& E) {
;     ...
;     f32x4 acc[2][2][4][2];
; #pragma unroll
;     for (int a = 0; a < 2; ++a)
; #pragma unroll
;         for (int b = 0; b < 2; ++b)
; #pragma unroll
;             for (int m = 0; m < 4; ++m)
; #pragma unroll
;                 for (int n = 0; n < 2; ++n) acc[a][b][m][n] = (f32x4){0.f, 0.f, 0.f, 0.f};
;     ...
;     for (;;) {
;         const bool has_next = S.next(ui + 1, nxt);
;         const char* nA = has_next ? (const char*)g.A + (size_t)nxt.pm * tstep : cA; const char* nB = has_next ? (const char*)g.Bt + (size_t)nxt.pn * tstep : cB;
;         for (int t = 0; t < nt; t += 2) {
.LBB0_849:
	v_mov_b32_e32 v123, 0
	s_andn2_b64 vcc, exec, s[16:17]
	v_mov_b32_e32 v122, v123
	v_mov_b32_e32 v121, v123
	v_mov_b32_e32 v120, v123
	v_mov_b32_e32 v127, v123
	v_mov_b32_e32 v126, v123
	v_mov_b32_e32 v125, v123
	v_mov_b32_e32 v124, v123
	v_mov_b32_e32 v111, v123
	v_mov_b32_e32 v110, v123
	v_mov_b32_e32 v109, v123
	v_mov_b32_e32 v108, v123
	v_mov_b32_e32 v107, v123
	v_mov_b32_e32 v106, v123
	v_mov_b32_e32 v105, v123
	v_mov_b32_e32 v104, v123
	v_mov_b32_e32 v95, v123
	v_mov_b32_e32 v94, v123
	v_mov_b32_e32 v93, v123
	v_mov_b32_e32 v92, v123
	v_mov_b32_e32 v91, v123
	v_mov_b32_e32 v90, v123
	v_mov_b32_e32 v89, v123
	v_mov_b32_e32 v88, v123
	v_mov_b32_e32 v79, v123
	v_mov_b32_e32 v78, v123
	v_mov_b32_e32 v77, v123
	v_mov_b32_e32 v76, v123
	v_mov_b32_e32 v75, v123
	v_mov_b32_e32 v74, v123
	v_mov_b32_e32 v73, v123
	v_mov_b32_e32 v72, v123
	v_mov_b32_e32 v119, v123
	v_mov_b32_e32 v118, v123
	v_mov_b32_e32 v117, v123
	v_mov_b32_e32 v116, v123
	v_mov_b32_e32 v115, v123
	v_mov_b32_e32 v114, v123
	v_mov_b32_e32 v113, v123
	v_mov_b32_e32 v112, v123
	v_mov_b32_e32 v103, v123
	v_mov_b32_e32 v102, v123
	v_mov_b32_e32 v101, v123
	v_mov_b32_e32 v100, v123
	v_mov_b32_e32 v99, v123
	v_mov_b32_e32 v98, v123
	v_mov_b32_e32 v97, v123
	v_mov_b32_e32 v96, v123
	v_mov_b32_e32 v87, v123
	v_mov_b32_e32 v86, v123
	v_mov_b32_e32 v85, v123
	v_mov_b32_e32 v84, v123
	v_mov_b32_e32 v83, v123
	v_mov_b32_e32 v82, v123
	v_mov_b32_e32 v81, v123
	v_mov_b32_e32 v80, v123
	v_mov_b32_e32 v71, v123
	v_mov_b32_e32 v70, v123
	v_mov_b32_e32 v69, v123
	v_mov_b32_e32 v68, v123
	v_mov_b32_e32 v67, v123
	v_mov_b32_e32 v66, v123
	v_mov_b32_e32 v65, v123
	v_mov_b32_e32 v64, v123
	v_mov_b32_e32 v63, v123
	v_mov_b32_e32 v62, v123
	v_mov_b32_e32 v61, v123
	v_mov_b32_e32 v60, v123
	v_mov_b32_e32 v59, v123
	v_mov_b32_e32 v58, v123
	v_mov_b32_e32 v57, v123
	v_mov_b32_e32 v56, v123
	v_mov_b32_e32 v47, v123
	v_mov_b32_e32 v46, v123
	v_mov_b32_e32 v45, v123
	v_mov_b32_e32 v44, v123
	v_mov_b32_e32 v43, v123
	v_mov_b32_e32 v42, v123
	v_mov_b32_e32 v41, v123
	v_mov_b32_e32 v40, v123
	v_mov_b32_e32 v31, v123
	v_mov_b32_e32 v30, v123
	v_mov_b32_e32 v29, v123
	v_mov_b32_e32 v28, v123
	v_mov_b32_e32 v27, v123
	v_mov_b32_e32 v26, v123
	v_mov_b32_e32 v25, v123
	v_mov_b32_e32 v24, v123
	v_mov_b32_e32 v15, v123
	v_mov_b32_e32 v14, v123
	v_mov_b32_e32 v13, v123
	v_mov_b32_e32 v12, v123
	v_mov_b32_e32 v11, v123
	v_mov_b32_e32 v10, v123
	v_mov_b32_e32 v9, v123
	v_mov_b32_e32 v8, v123
	v_mov_b32_e32 v55, v123
	v_mov_b32_e32 v54, v123
	v_mov_b32_e32 v53, v123
	v_mov_b32_e32 v52, v123
	v_mov_b32_e32 v51, v123
	v_mov_b32_e32 v50, v123
	v_mov_b32_e32 v49, v123
	v_mov_b32_e32 v48, v123
	v_mov_b32_e32 v39, v123
	v_mov_b32_e32 v38, v123
	v_mov_b32_e32 v37, v123
	v_mov_b32_e32 v36, v123
	v_mov_b32_e32 v35, v123
	v_mov_b32_e32 v34, v123
	v_mov_b32_e32 v33, v123
	v_mov_b32_e32 v32, v123
	v_mov_b32_e32 v23, v123
	v_mov_b32_e32 v22, v123
	v_mov_b32_e32 v21, v123
	v_mov_b32_e32 v20, v123
	v_mov_b32_e32 v19, v123
	v_mov_b32_e32 v18, v123
	v_mov_b32_e32 v17, v123
	v_mov_b32_e32 v16, v123
	v_mov_b32_e32 v7, v123
	v_mov_b32_e32 v6, v123
	v_mov_b32_e32 v5, v123
	v_mov_b32_e32 v4, v123
	v_mov_b32_e32 v3, v123
	v_mov_b32_e32 v2, v123
	v_mov_b32_e32 v1, v123
	v_mov_b32_e32 v0, v123
	s_cbranch_vccnz .LBB0_853
	s_add_u32 s22, s22, 0x80
	s_addc_u32 s23, s23, 0
	s_add_u32 s58, s24, 0x100
	s_addc_u32 s62, s25, 0
	s_mov_b32 s24, 0
	v_mov_b64_e32 v[0:1], 0
	v_mov_b64_e32 v[2:3], 0
	v_mov_b64_e32 v[4:5], 0
	v_mov_b64_e32 v[6:7], 0
	v_mov_b64_e32 v[8:9], 0
	v_mov_b64_e32 v[10:11], 0
	v_mov_b64_e32 v[12:13], 0
	v_mov_b64_e32 v[14:15], 0
	v_mov_b64_e32 v[16:17], 0
	v_mov_b64_e32 v[18:19], 0
	v_mov_b64_e32 v[20:21], 0
	v_mov_b64_e32 v[22:23], 0
	v_mov_b64_e32 v[24:25], 0
	v_mov_b64_e32 v[26:27], 0
	v_mov_b64_e32 v[28:29], 0
	v_mov_b64_e32 v[30:31], 0
	v_mov_b64_e32 v[32:33], 0
	v_mov_b64_e32 v[34:35], 0
	v_mov_b64_e32 v[36:37], 0
	v_mov_b64_e32 v[38:39], 0
	v_mov_b64_e32 v[40:41], 0
	v_mov_b64_e32 v[42:43], 0
	v_mov_b64_e32 v[44:45], 0
	v_mov_b64_e32 v[46:47], 0
	v_mov_b64_e32 v[48:49], 0
	v_mov_b64_e32 v[50:51], 0
	v_mov_b64_e32 v[52:53], 0
	v_mov_b64_e32 v[54:55], 0
	v_mov_b64_e32 v[56:57], 0
	v_mov_b64_e32 v[58:59], 0
	v_mov_b64_e32 v[60:61], 0
	v_mov_b64_e32 v[62:63], 0
	v_mov_b64_e32 v[64:65], 0
	v_mov_b64_e32 v[66:67], 0
	v_mov_b64_e32 v[68:69], 0
	v_mov_b64_e32 v[70:71], 0
	v_mov_b64_e32 v[72:73], 0
	v_mov_b64_e32 v[74:75], 0
	v_mov_b64_e32 v[76:77], 0
	v_mov_b64_e32 v[78:79], 0
	v_mov_b64_e32 v[80:81], 0
	v_mov_b64_e32 v[82:83], 0
	v_mov_b64_e32 v[84:85], 0
	v_mov_b64_e32 v[86:87], 0
	v_mov_b64_e32 v[88:89], 0
	v_mov_b64_e32 v[90:91], 0
	v_mov_b64_e32 v[92:93], 0
	v_mov_b64_e32 v[94:95], 0
	v_mov_b64_e32 v[96:97], 0
	v_mov_b64_e32 v[98:99], 0
	v_mov_b64_e32 v[100:101], 0
	v_mov_b64_e32 v[102:103], 0
	v_mov_b64_e32 v[104:105], 0
	v_mov_b64_e32 v[106:107], 0
	v_mov_b64_e32 v[108:109], 0
	v_mov_b64_e32 v[110:111], 0
	v_mov_b64_e32 v[112:113], 0
	v_mov_b64_e32 v[114:115], 0
	v_mov_b64_e32 v[116:117], 0
	v_mov_b64_e32 v[118:119], 0
	v_mov_b64_e32 v[120:121], 0
	v_mov_b64_e32 v[122:123], 0
	v_mov_b64_e32 v[124:125], 0
	v_mov_b64_e32 v[126:127], 0
	s_cmp_eq_u64 s[18:19], 0
	s_cbranch_scc0 .Lprio_skip_851
	s_setprio 1
; #define PG8_STAGE(bufoff, gbase, voff) do { _Pragma("unroll") for (int _i = 0; _i < 2; ++_i) \
;         __builtin_amdgcn_global_load_lds((const unsigned*)((const char*)(gbase) + (voff)[_i]), (PG8_LAS unsigned*)(lds + (bufoff) + ldsw + _i * 8192), 16, 0, 0); } while (0)
; #define PG8_LDA(dst, b, h) do { _Pragma("unroll") for (int m = 0; m < 4; ++m) _Pragma("unroll") for (int k = 0; k < 2; ++k) dst[m][k] = *(const PG8_LAS bf16x8*)(lds + PG8_SA(b, h) + aoff + m * 2048 + k * 1024); } while (0)
; #define PG8_LDB(dst, b, h) do { _Pragma("unroll") for (int n = 0; n < 2; ++n) _Pragma("unroll") for (int k = 0; k < 2; ++k) dst[n][k] = *(const PG8_LAS bf16x8*)(lds + PG8_SB(b, h) + boff + n * 2048 + k * 1024); } while (0)
; #define PG8_MMA(ai, bj, At, Bt) do { __builtin_amdgcn_s_setprio(1); _Pragma("unroll") for (int m = 0; m < 4; ++m) _Pragma("unroll") for (int n = 0; n < 2; ++n) _Pragma("unroll") for (int k = 0; k < 2; ++k) \
;         acc[ai][bj][m][n] = __builtin_amdgcn_mfma_f32_16x16x32_bf16(Bt[n][k], At[m][k], acc[ai][bj][m][n], 0, 0, 0); __builtin_amdgcn_s_setprio(0); } while (0)
; #define PG8_WAIT_V(n) asm volatile("s_waitcnt vmcnt(" #n ")" ::: "memory")
; #define PG8_BAR __builtin_amdgcn_s_barrier()
; template <class Epi, class Sched, bool ALIGN_EPI = false, bool SP2 = false>
; __device__ __forceinline__ void gemm_phase(PG8_LAS unsigned char* lds, const Gemm g, const Sched& S, const Epi& E) {
;     ...
;         for (int t = 0; t < nt; t += 2) {
;             const bool last = (t == nt - 2);
;             const char* a1 = cA + (size_t)(t + 1) * kstep;
;             const char* a2 = last ? nA : cA + (size_t)(t + 2) * kstep; const char* b2 = last ? nB : cB + (size_t)(t + 2) * kstep;
;             const char* a3 = a2 + kstep; const char* b3 = b2 + kstep;
;             if (last && has_next) S.a_ready(nxt);
;             if constexpr (SP2) {
;             PG8_LDB(B0, 0, 0); PG8_LDB(B1, 0, 1); PG8_SCHED; PG8_LDA(At, 0, 0); PG8_STAGE(PG8_SA(1, 1), a1 + hstep, voffA);
;             PG8_WAIT_V(8); PG8_WAIT_L(0); PG8_BAR; PG8_MMA(0, 0, At, B0); PG8_MMA(0, 1, At, B1); PG8_BAR; PG8_SCHED;
;             PG8_LDA(At, 0, 1); PG8_STAGE(PG8_SB(0, 0), b2, voffB); PG8_STAGE(PG8_SB(0, 1), b2 + hstep, voffB); PG8_STAGE(PG8_SA(0, 0), a2, voffA);
;             PG8_WAIT_V(8); PG8_WAIT_L(0); PG8_BAR; PG8_MMA(1, 0, At, B0); PG8_MMA(1, 1, At, B1); PG8_BAR; PG8_SCHED;
.Lprio_skip_851:
.LBB0_851:
	s_add_i32 s63, s24, 2
	s_add_u32 s60, s22, 0x80
	s_addc_u32 s25, s23, 0
	s_add_i32 s66, 0, 0x10000
	s_cmp_eq_u32 s39, s24
	s_cselect_b32 s25, s7, s25
	s_cselect_b32 s24, s6, s60
	s_cselect_b32 s61, s21, s62
	s_cselect_b32 s60, s20, s58
	s_add_i32 s67, 0, 0x14000
	v_add_u32_e32 v154, s66, v139
	v_add_u32_e32 v170, s67, v139
	ds_read_b128 v[142:145], v154
	ds_read_b128 v[146:149], v154 offset:1024
	ds_read_b128 v[150:153], v154 offset:2048
	ds_read_b128 v[154:157], v154 offset:3072
	ds_read_b128 v[158:161], v170
	ds_read_b128 v[162:165], v170 offset:1024
	ds_read_b128 v[166:169], v170 offset:2048
	ds_read_b128 v[170:173], v170 offset:3072
	v_lshl_add_u64 v[186:187], s[22:23], 0, v[134:135]
	s_add_i32 m0, s30, 0xc000
	ds_read_b128 v[174:177], v141
	ds_read_b128 v[178:181], v141 offset:1024
	ds_read_b128 v[182:185], v141 offset:2048
	ds_read_b128 v[198:201], v141 offset:3072
	ds_read_b128 v[202:205], v141 offset:4096
	ds_read_b128 v[206:209], v141 offset:5120
	ds_read_b128 v[210:213], v141 offset:6144
	ds_read_b128 v[214:217], v141 offset:7168
	global_load_lds_dwordx4 v[186:187], off
	v_lshl_add_u64 v[186:187], s[22:23], 0, v[136:137]
	s_add_i32 m0, s30, 0xe000
	s_nop 0
	global_load_lds_dwordx4 v[186:187], off
	s_waitcnt vmcnt(8)
	s_waitcnt lgkmcnt(0)
	s_barrier
	v_mfma_f32_16x16x32_bf16 v[120:123], v[142:145], v[174:177], v[120:123]
	v_mfma_f32_16x16x32_bf16 v[124:127], v[150:153], v[174:177], v[124:127]
	v_mfma_f32_16x16x32_bf16 v[108:111], v[142:145], v[182:185], v[108:111]
	v_mfma_f32_16x16x32_bf16 v[104:107], v[150:153], v[182:185], v[104:107]
	v_mfma_f32_16x16x32_bf16 v[92:95], v[142:145], v[202:205], v[92:95]
	v_mfma_f32_16x16x32_bf16 v[88:91], v[150:153], v[202:205], v[88:91]
	v_mfma_f32_16x16x32_bf16 v[76:79], v[142:145], v[210:213], v[76:79]
	v_mfma_f32_16x16x32_bf16 v[72:75], v[150:153], v[210:213], v[72:75]
	v_mfma_f32_16x16x32_bf16 v[120:123], v[146:149], v[178:181], v[120:123]
	v_mfma_f32_16x16x32_bf16 v[124:127], v[154:157], v[178:181], v[124:127]
	v_mfma_f32_16x16x32_bf16 v[108:111], v[146:149], v[198:201], v[108:111]
	v_mfma_f32_16x16x32_bf16 v[104:107], v[154:157], v[198:201], v[104:107]
	v_mfma_f32_16x16x32_bf16 v[92:95], v[146:149], v[206:209], v[92:95]
	v_mfma_f32_16x16x32_bf16 v[88:91], v[154:157], v[206:209], v[88:91]
	v_mfma_f32_16x16x32_bf16 v[76:79], v[146:149], v[214:217], v[76:79]
	v_mfma_f32_16x16x32_bf16 v[72:75], v[154:157], v[214:217], v[72:75]
	v_mfma_f32_16x16x32_bf16 v[116:119], v[158:161], v[174:177], v[116:119]
	v_mfma_f32_16x16x32_bf16 v[112:115], v[166:169], v[174:177], v[112:115]
	v_mfma_f32_16x16x32_bf16 v[100:103], v[158:161], v[182:185], v[100:103]
	v_mfma_f32_16x16x32_bf16 v[96:99], v[166:169], v[182:185], v[96:99]
	v_mfma_f32_16x16x32_bf16 v[84:87], v[158:161], v[202:205], v[84:87]
	v_mfma_f32_16x16x32_bf16 v[80:83], v[166:169], v[202:205], v[80:83]
	v_mfma_f32_16x16x32_bf16 v[68:71], v[158:161], v[210:213], v[68:71]
	v_mfma_f32_16x16x32_bf16 v[64:67], v[166:169], v[210:213], v[64:67]
	v_mfma_f32_16x16x32_bf16 v[116:119], v[162:165], v[178:181], v[116:119]
	v_mfma_f32_16x16x32_bf16 v[112:115], v[170:173], v[178:181], v[112:115]
	v_mfma_f32_16x16x32_bf16 v[100:103], v[162:165], v[198:201], v[100:103]
	v_mfma_f32_16x16x32_bf16 v[96:99], v[170:173], v[198:201], v[96:99]
	v_mfma_f32_16x16x32_bf16 v[84:87], v[162:165], v[206:209], v[84:87]
	v_mfma_f32_16x16x32_bf16 v[80:83], v[170:173], v[206:209], v[80:83]
	v_mfma_f32_16x16x32_bf16 v[68:71], v[162:165], v[214:217], v[68:71]
	v_mfma_f32_16x16x32_bf16 v[64:67], v[170:173], v[214:217], v[64:67]
	s_barrier
	s_add_i32 s66, s66, s29
	v_lshl_add_u64 v[186:187], s[60:61], 0, v[188:189]
	s_mov_b32 m0, s66
	ds_read_b128 v[174:177], v141 offset:16384
	ds_read_b128 v[178:181], v141 offset:17408
	ds_read_b128 v[182:185], v141 offset:18432
	ds_read_b128 v[198:201], v141 offset:19456
	ds_read_b128 v[202:205], v141 offset:20480
	ds_read_b128 v[206:209], v141 offset:21504
	ds_read_b128 v[210:213], v141 offset:22528
	ds_read_b128 v[214:217], v141 offset:23552
	global_load_lds_dwordx4 v[186:187], off
	s_add_i32 m0, s66, 0x2000
	v_lshl_add_u64 v[218:219], s[60:61], 0, v[128:129]
	s_add_u32 s60, s60, s0
	s_addc_u32 s61, s61, s1
	s_add_i32 s66, s67, s29
	global_load_lds_dwordx4 v[218:219], off
	v_lshl_add_u64 v[220:221], s[60:61], 0, v[188:189]
	s_mov_b32 m0, s66
	v_lshl_add_u64 v[222:223], s[60:61], 0, v[128:129]
	global_load_lds_dwordx4 v[220:221], off
	s_add_i32 m0, s66, 0x2000
	v_lshl_add_u64 v[224:225], s[24:25], 0, v[132:133]
	global_load_lds_dwordx4 v[222:223], off
	s_mov_b32 m0, s30
	v_lshl_add_u64 v[226:227], s[24:25], 0, v[130:131]
	global_load_lds_dwordx4 v[224:225], off
	s_mov_b32 m0, s31
	s_nop 0
	global_load_lds_dwordx4 v[226:227], off
	s_waitcnt vmcnt(8)
	s_waitcnt lgkmcnt(0)
	s_barrier
; #define PG8_STAGE(bufoff, gbase, voff) do { _Pragma("unroll") for (int _i = 0; _i < 2; ++_i) \
;         __builtin_amdgcn_global_load_lds((const unsigned*)((const char*)(gbase) + (voff)[_i]), (PG8_LAS unsigned*)(lds + (bufoff) + ldsw + _i * 8192), 16, 0, 0); } while (0)
; #define PG8_LDA(dst, b, h) do { _Pragma("unroll") for (int m = 0; m < 4; ++m) _Pragma("unroll") for (int k = 0; k < 2; ++k) dst[m][k] = *(const PG8_LAS bf16x8*)(lds + PG8_SA(b, h) + aoff + m * 2048 + k * 1024); } while (0)
; #define PG8_LDB(dst, b, h) do { _Pragma("unroll") for (int n = 0; n < 2; ++n) _Pragma("unroll") for (int k = 0; k < 2; ++k) dst[n][k] = *(const PG8_LAS bf16x8*)(lds + PG8_SB(b, h) + boff + n * 2048 + k * 1024); } while (0)
; #define PG8_MMA(ai, bj, At, Bt) do { __builtin_amdgcn_s_setprio(1); _Pragma("unroll") for (int m = 0; m < 4; ++m) _Pragma("unroll") for (int n = 0; n < 2; ++n) _Pragma("unroll") for (int k = 0; k < 2; ++k) \
;         acc[ai][bj][m][n] = __builtin_amdgcn_mfma_f32_16x16x32_bf16(Bt[n][k], At[m][k], acc[ai][bj][m][n], 0, 0, 0); __builtin_amdgcn_s_setprio(0); } while (0)
; #define PG8_WAIT_V(n) asm volatile("s_waitcnt vmcnt(" #n ")" ::: "memory")
; #define PG8_WAIT_L(n) asm volatile("s_waitcnt lgkmcnt(" #n ")" ::: "memory")
; #define PG8_BAR __builtin_amdgcn_s_barrier()
; #define PG8_SCHED __builtin_amdgcn_sched_barrier(0)
; template <class Epi, class Sched, bool ALIGN_EPI = false, bool SP2 = false>
; __device__ __forceinline__ void gemm_phase(PG8_LAS unsigned char* lds, const Gemm g, const Sched& S, const Epi& E) {
;     ...
;             PG8_WAIT_V(8); PG8_WAIT_L(0); PG8_BAR; PG8_MMA(1, 0, At, B0); PG8_MMA(1, 1, At, B1); PG8_BAR; PG8_SCHED;
;             PG8_LDB(B0, 1, 0); PG8_LDB(B1, 1, 1); PG8_SCHED; PG8_LDA(At, 1, 0); PG8_STAGE(PG8_SA(0, 1), a2 + hstep, voffA);
;             PG8_WAIT_V(8); PG8_WAIT_L(0); PG8_BAR; PG8_MMA(0, 0, At, B0); PG8_MMA(0, 1, At, B1); PG8_BAR; PG8_SCHED;
	v_mfma_f32_16x16x32_bf16 v[60:63], v[142:145], v[174:177], v[60:63]
	v_mfma_f32_16x16x32_bf16 v[56:59], v[150:153], v[174:177], v[56:59]
	v_mfma_f32_16x16x32_bf16 v[44:47], v[142:145], v[182:185], v[44:47]
	v_mfma_f32_16x16x32_bf16 v[40:43], v[150:153], v[182:185], v[40:43]
	v_mfma_f32_16x16x32_bf16 v[28:31], v[142:145], v[202:205], v[28:31]
	v_mfma_f32_16x16x32_bf16 v[24:27], v[150:153], v[202:205], v[24:27]
	v_mfma_f32_16x16x32_bf16 v[12:15], v[142:145], v[210:213], v[12:15]
	v_mfma_f32_16x16x32_bf16 v[8:11], v[150:153], v[210:213], v[8:11]
	v_mfma_f32_16x16x32_bf16 v[60:63], v[146:149], v[178:181], v[60:63]
	v_mfma_f32_16x16x32_bf16 v[56:59], v[154:157], v[178:181], v[56:59]
	v_mfma_f32_16x16x32_bf16 v[44:47], v[146:149], v[198:201], v[44:47]
	v_mfma_f32_16x16x32_bf16 v[40:43], v[154:157], v[198:201], v[40:43]
	v_mfma_f32_16x16x32_bf16 v[28:31], v[146:149], v[206:209], v[28:31]
	v_mfma_f32_16x16x32_bf16 v[24:27], v[154:157], v[206:209], v[24:27]
	v_mfma_f32_16x16x32_bf16 v[12:15], v[146:149], v[214:217], v[12:15]
	v_mfma_f32_16x16x32_bf16 v[8:11], v[154:157], v[214:217], v[8:11]
	v_mfma_f32_16x16x32_bf16 v[52:55], v[158:161], v[174:177], v[52:55]
	v_mfma_f32_16x16x32_bf16 v[48:51], v[166:169], v[174:177], v[48:51]
	v_mfma_f32_16x16x32_bf16 v[36:39], v[158:161], v[182:185], v[36:39]
	v_mfma_f32_16x16x32_bf16 v[32:35], v[166:169], v[182:185], v[32:35]
	v_mfma_f32_16x16x32_bf16 v[20:23], v[158:161], v[202:205], v[20:23]
	v_mfma_f32_16x16x32_bf16 v[16:19], v[166:169], v[202:205], v[16:19]
	v_mfma_f32_16x16x32_bf16 v[4:7], v[158:161], v[210:213], v[4:7]
	v_mfma_f32_16x16x32_bf16 v[0:3], v[166:169], v[210:213], v[0:3]
	v_mfma_f32_16x16x32_bf16 v[52:55], v[162:165], v[178:181], v[52:55]
	v_mfma_f32_16x16x32_bf16 v[48:51], v[170:173], v[178:181], v[48:51]
	v_mfma_f32_16x16x32_bf16 v[36:39], v[162:165], v[198:201], v[36:39]
	v_mfma_f32_16x16x32_bf16 v[32:35], v[170:173], v[198:201], v[32:35]
	v_mfma_f32_16x16x32_bf16 v[20:23], v[162:165], v[206:209], v[20:23]
	v_mfma_f32_16x16x32_bf16 v[16:19], v[170:173], v[206:209], v[16:19]
	v_mfma_f32_16x16x32_bf16 v[4:7], v[162:165], v[214:217], v[4:7]
	v_mfma_f32_16x16x32_bf16 v[0:3], v[170:173], v[214:217], v[0:3]
	s_barrier
	s_add_i32 s60, 0, 0x18000
	s_add_i32 s61, 0, 0x1c000
	v_add_u32_e32 v154, s60, v139
	v_add_u32_e32 v170, s61, v139
	ds_read_b128 v[142:145], v154
	ds_read_b128 v[146:149], v154 offset:1024
	ds_read_b128 v[150:153], v154 offset:2048
	ds_read_b128 v[154:157], v154 offset:3072
	ds_read_b128 v[158:161], v170
	ds_read_b128 v[162:165], v170 offset:1024
	ds_read_b128 v[166:169], v170 offset:2048
	ds_read_b128 v[170:173], v170 offset:3072
	s_add_u32 s24, s24, s0
	s_addc_u32 s25, s25, s1
	s_mov_b32 m0, s34
	v_lshl_add_u64 v[228:229], s[24:25], 0, v[132:133]
	ds_read_b128 v[174:177], v141 offset:32768
	ds_read_b128 v[178:181], v141 offset:33792
	ds_read_b128 v[182:185], v141 offset:34816
	ds_read_b128 v[198:201], v141 offset:35840
	ds_read_b128 v[202:205], v141 offset:36864
	ds_read_b128 v[206:209], v141 offset:37888
	ds_read_b128 v[210:213], v141 offset:38912
	ds_read_b128 v[214:217], v141 offset:39936
	global_load_lds_dwordx4 v[228:229], off
	v_lshl_add_u64 v[228:229], s[24:25], 0, v[130:131]
	s_mov_b32 m0, s35
	s_nop 0
	global_load_lds_dwordx4 v[228:229], off
	s_waitcnt vmcnt(8)
	s_waitcnt lgkmcnt(0)
	s_barrier
	v_mfma_f32_16x16x32_bf16 v[120:123], v[142:145], v[174:177], v[120:123]
	v_mfma_f32_16x16x32_bf16 v[124:127], v[150:153], v[174:177], v[124:127]
	v_mfma_f32_16x16x32_bf16 v[108:111], v[142:145], v[182:185], v[108:111]
	v_mfma_f32_16x16x32_bf16 v[104:107], v[150:153], v[182:185], v[104:107]
	v_mfma_f32_16x16x32_bf16 v[92:95], v[142:145], v[202:205], v[92:95]
	v_mfma_f32_16x16x32_bf16 v[88:91], v[150:153], v[202:205], v[88:91]
	v_mfma_f32_16x16x32_bf16 v[76:79], v[142:145], v[210:213], v[76:79]
	v_mfma_f32_16x16x32_bf16 v[72:75], v[150:153], v[210:213], v[72:75]
	v_mfma_f32_16x16x32_bf16 v[120:123], v[146:149], v[178:181], v[120:123]
	v_mfma_f32_16x16x32_bf16 v[124:127], v[154:157], v[178:181], v[124:127]
	v_mfma_f32_16x16x32_bf16 v[108:111], v[146:149], v[198:201], v[108:111]
	v_mfma_f32_16x16x32_bf16 v[104:107], v[154:157], v[198:201], v[104:107]
	v_mfma_f32_16x16x32_bf16 v[92:95], v[146:149], v[206:209], v[92:95]
	v_mfma_f32_16x16x32_bf16 v[88:91], v[154:157], v[206:209], v[88:91]
	v_mfma_f32_16x16x32_bf16 v[76:79], v[146:149], v[214:217], v[76:79]
	v_mfma_f32_16x16x32_bf16 v[72:75], v[154:157], v[214:217], v[72:75]
	v_mfma_f32_16x16x32_bf16 v[116:119], v[158:161], v[174:177], v[116:119]
	v_mfma_f32_16x16x32_bf16 v[112:115], v[166:169], v[174:177], v[112:115]
	v_mfma_f32_16x16x32_bf16 v[100:103], v[158:161], v[182:185], v[100:103]
	v_mfma_f32_16x16x32_bf16 v[96:99], v[166:169], v[182:185], v[96:99]
	v_mfma_f32_16x16x32_bf16 v[84:87], v[158:161], v[202:205], v[84:87]
	v_mfma_f32_16x16x32_bf16 v[80:83], v[166:169], v[202:205], v[80:83]
	v_mfma_f32_16x16x32_bf16 v[68:71], v[158:161], v[210:213], v[68:71]
	v_mfma_f32_16x16x32_bf16 v[64:67], v[166:169], v[210:213], v[64:67]
	v_mfma_f32_16x16x32_bf16 v[116:119], v[162:165], v[178:181], v[116:119]
	v_mfma_f32_16x16x32_bf16 v[112:115], v[170:173], v[178:181], v[112:115]
	v_mfma_f32_16x16x32_bf16 v[100:103], v[162:165], v[198:201], v[100:103]
	v_mfma_f32_16x16x32_bf16 v[96:99], v[170:173], v[198:201], v[96:99]
	v_mfma_f32_16x16x32_bf16 v[84:87], v[162:165], v[206:209], v[84:87]
	v_mfma_f32_16x16x32_bf16 v[80:83], v[170:173], v[206:209], v[80:83]
	v_mfma_f32_16x16x32_bf16 v[68:71], v[162:165], v[214:217], v[68:71]
	v_mfma_f32_16x16x32_bf16 v[64:67], v[170:173], v[214:217], v[64:67]
	s_barrier
; #define PG8_STAGE(bufoff, gbase, voff) do { _Pragma("unroll") for (int _i = 0; _i < 2; ++_i) \
;         __builtin_amdgcn_global_load_lds((const unsigned*)((const char*)(gbase) + (voff)[_i]), (PG8_LAS unsigned*)(lds + (bufoff) + ldsw + _i * 8192), 16, 0, 0); } while (0)
; #define PG8_LDA(dst, b, h) do { _Pragma("unroll") for (int m = 0; m < 4; ++m) _Pragma("unroll") for (int k = 0; k < 2; ++k) dst[m][k] = *(const PG8_LAS bf16x8*)(lds + PG8_SA(b, h) + aoff + m * 2048 + k * 1024); } while (0)
; #define PG8_MMA(ai, bj, At, Bt) do { __builtin_amdgcn_s_setprio(1); _Pragma("unroll") for (int m = 0; m < 4; ++m) _Pragma("unroll") for (int n = 0; n < 2; ++n) _Pragma("unroll") for (int k = 0; k < 2; ++k) \
;         acc[ai][bj][m][n] = __builtin_amdgcn_mfma_f32_16x16x32_bf16(Bt[n][k], At[m][k], acc[ai][bj][m][n], 0, 0, 0); __builtin_amdgcn_s_setprio(0); } while (0)
; #define PG8_WAIT_V(n) asm volatile("s_waitcnt vmcnt(" #n ")" ::: "memory")
; #define PG8_WAIT_L(n) asm volatile("s_waitcnt lgkmcnt(" #n ")" ::: "memory")
; #define PG8_BAR __builtin_amdgcn_s_barrier()
; #define PG8_SCHED __builtin_amdgcn_sched_barrier(0)
; template <class Epi, class Sched, bool ALIGN_EPI = false, bool SP2 = false>
; __device__ __forceinline__ void gemm_phase(PG8_LAS unsigned char* lds, const Gemm g, const Sched& S, const Epi& E) {
;     ...
;         for (int t = 0; t < nt; t += 2) {
;     ...
;             PG8_LDA(At, 1, 1); PG8_STAGE(PG8_SB(1, 0), b3, voffB); PG8_STAGE(PG8_SB(1, 1), b3 + hstep, voffB); PG8_STAGE(PG8_SA(1, 0), a3, voffA);
;             PG8_WAIT_V(8); PG8_WAIT_L(0); PG8_BAR; PG8_MMA(1, 0, At, B0); PG8_MMA(1, 1, At, B1); PG8_BAR; PG8_SCHED;
	s_add_i32 s24, s60, s29
	v_lshl_add_u64 v[186:187], v[186:187], 0, s[78:79]
	s_mov_b32 m0, s24
	ds_read_b128 v[174:177], v141 offset:49152
	ds_read_b128 v[178:181], v141 offset:50176
	ds_read_b128 v[182:185], v141 offset:51200
	ds_read_b128 v[198:201], v141 offset:52224
	ds_read_b128 v[202:205], v141 offset:53248
	ds_read_b128 v[206:209], v141 offset:54272
	ds_read_b128 v[210:213], v141 offset:55296
	ds_read_b128 v[214:217], v141 offset:56320
	global_load_lds_dwordx4 v[186:187], off
	v_lshl_add_u64 v[186:187], v[218:219], 0, s[78:79]
	s_add_i32 m0, s24, 0x2000
	s_add_i32 s24, s61, s29
	global_load_lds_dwordx4 v[186:187], off
	v_lshl_add_u64 v[186:187], v[220:221], 0, s[78:79]
	s_mov_b32 m0, s24
	s_nop 0
	global_load_lds_dwordx4 v[186:187], off
	v_lshl_add_u64 v[186:187], v[222:223], 0, s[78:79]
	s_add_i32 m0, s24, 0x2000
	s_nop 0
	global_load_lds_dwordx4 v[186:187], off
	v_lshl_add_u64 v[186:187], v[224:225], 0, s[78:79]
	s_mov_b32 m0, s37
	s_nop 0
	global_load_lds_dwordx4 v[186:187], off
	v_lshl_add_u64 v[186:187], v[226:227], 0, s[78:79]
	s_mov_b32 m0, s38
	s_nop 0
	global_load_lds_dwordx4 v[186:187], off
	s_waitcnt vmcnt(8)
	s_waitcnt lgkmcnt(0)
	s_barrier
	v_mfma_f32_16x16x32_bf16 v[60:63], v[142:145], v[174:177], v[60:63]
	v_mfma_f32_16x16x32_bf16 v[56:59], v[150:153], v[174:177], v[56:59]
	v_mfma_f32_16x16x32_bf16 v[44:47], v[142:145], v[182:185], v[44:47]
	v_mfma_f32_16x16x32_bf16 v[40:43], v[150:153], v[182:185], v[40:43]
	v_mfma_f32_16x16x32_bf16 v[28:31], v[142:145], v[202:205], v[28:31]
	v_mfma_f32_16x16x32_bf16 v[24:27], v[150:153], v[202:205], v[24:27]
	v_mfma_f32_16x16x32_bf16 v[12:15], v[142:145], v[210:213], v[12:15]
	v_mfma_f32_16x16x32_bf16 v[8:11], v[150:153], v[210:213], v[8:11]
	v_mfma_f32_16x16x32_bf16 v[60:63], v[146:149], v[178:181], v[60:63]
	v_mfma_f32_16x16x32_bf16 v[56:59], v[154:157], v[178:181], v[56:59]
	v_mfma_f32_16x16x32_bf16 v[44:47], v[146:149], v[198:201], v[44:47]
	v_mfma_f32_16x16x32_bf16 v[40:43], v[154:157], v[198:201], v[40:43]
	v_mfma_f32_16x16x32_bf16 v[28:31], v[146:149], v[206:209], v[28:31]
	v_mfma_f32_16x16x32_bf16 v[24:27], v[154:157], v[206:209], v[24:27]
	v_mfma_f32_16x16x32_bf16 v[12:15], v[146:149], v[214:217], v[12:15]
	v_mfma_f32_16x16x32_bf16 v[8:11], v[154:157], v[214:217], v[8:11]
	v_mfma_f32_16x16x32_bf16 v[52:55], v[158:161], v[174:177], v[52:55]
	v_mfma_f32_16x16x32_bf16 v[48:51], v[166:169], v[174:177], v[48:51]
	v_mfma_f32_16x16x32_bf16 v[36:39], v[158:161], v[182:185], v[36:39]
	v_mfma_f32_16x16x32_bf16 v[32:35], v[166:169], v[182:185], v[32:35]
	v_mfma_f32_16x16x32_bf16 v[20:23], v[158:161], v[202:205], v[20:23]
	v_mfma_f32_16x16x32_bf16 v[16:19], v[166:169], v[202:205], v[16:19]
	v_mfma_f32_16x16x32_bf16 v[4:7], v[158:161], v[210:213], v[4:7]
	v_mfma_f32_16x16x32_bf16 v[0:3], v[166:169], v[210:213], v[0:3]
	v_mfma_f32_16x16x32_bf16 v[52:55], v[162:165], v[178:181], v[52:55]
	v_mfma_f32_16x16x32_bf16 v[48:51], v[170:173], v[178:181], v[48:51]
	v_mfma_f32_16x16x32_bf16 v[36:39], v[162:165], v[198:201], v[36:39]
	v_mfma_f32_16x16x32_bf16 v[32:35], v[170:173], v[198:201], v[32:35]
	v_mfma_f32_16x16x32_bf16 v[20:23], v[162:165], v[206:209], v[20:23]
	v_mfma_f32_16x16x32_bf16 v[16:19], v[170:173], v[206:209], v[16:19]
	v_mfma_f32_16x16x32_bf16 v[4:7], v[162:165], v[214:217], v[4:7]
	v_mfma_f32_16x16x32_bf16 v[0:3], v[170:173], v[214:217], v[0:3]
	s_barrier
	s_add_u32 s22, s22, 0x100
	s_addc_u32 s23, s23, 0
	s_add_u32 s58, s58, 0x100
	s_addc_u32 s62, s62, 0
	s_cmp_ge_i32 s63, s36
	s_mov_b32 s24, s63
	s_cbranch_scc0 .LBB0_851
	s_setprio 0
	s_mov_b32 s67, 0x20000
	s_mov_b32 s66, 0x30000

;     __device__ __forceinline__ bool next(int i, Unit& u) const { Unit t; if (!so.next(i / 3, t)) return false; const int br = i % 3; u.pm = t.pm + br * so.nM; u.pn = t.pn + br * so.nN; return true; }
;     __device__ __forceinline__ bool zero_after(const Unit& u) const { return (u.pn / nN) == 2; }
; #define PG8_STAGE(bufoff, gbase, voff) do { _Pragma("unroll") for (int _i = 0; _i < 2; ++_i) \
;         __builtin_amdgcn_global_load_lds((const unsigned*)((const char*)(gbase) + (voff)[_i]), (PG8_LAS unsigned*)(lds + (bufoff) + ldsw + _i * 8192), 16, 0, 0); } while (0)
; #define PG8_LDA(dst, b, h) do { _Pragma("unroll") for (int m = 0; m < 4; ++m) _Pragma("unroll") for (int k = 0; k < 2; ++k) dst[m][k] = *(const PG8_LAS bf16x8*)(lds + PG8_SA(b, h) + aoff + m * 2048 + k * 1024); } while (0)
; #define PG8_WAIT_V(n) asm volatile("s_waitcnt vmcnt(" #n ")" ::: "memory")
; #define PG8_WAIT_L(n) asm volatile("s_waitcnt lgkmcnt(" #n ")" ::: "memory")
; template <class Epi, class Sched, bool ALIGN_EPI = false, bool SP2 = false>
; __device__ __forceinline__ void gemm_phase(PG8_LAS unsigned char* lds, const Gemm g, const Sched& S, const Epi& E) {
;     ...
;         const bool has_next = S.next(ui + 1, nxt);
;         const char* nA = has_next ? (const char*)g.A + (size_t)nxt.pm * tstep : cA; const char* nB = has_next ? (const char*)g.Bt + (size_t)nxt.pn * tstep : cB;
;         for (int t = 0; t < nt; t += 2) {
;             const bool last = (t == nt - 2);
;             const char* a1 = cA + (size_t)(t + 1) * kstep;
;             const char* a2 = last ? nA : cA + (size_t)(t + 2) * kstep; const char* b2 = last ? nB : cB + (size_t)(t + 2) * kstep;
;             const char* a3 = a2 + kstep; const char* b3 = b2 + kstep;
;             if (last && has_next) S.a_ready(nxt);
;             if constexpr (SP2) {
;             PG8_LDB(B0, 0, 0); PG8_LDB(B1, 0, 1); PG8_SCHED; PG8_LDA(At, 0, 0); PG8_STAGE(PG8_SA(1, 1), a1 + hstep, voffA);
;             PG8_WAIT_V(8); PG8_WAIT_L(0); PG8_BAR; PG8_MMA(0, 0, At, B0); PG8_MMA(0, 1, At, B1); PG8_BAR; PG8_SCHED;
;     ...
;         if (E.zero_after(cur)) {
; #pragma unroll
;         for (int a = 0; a < 2; ++a)
; #pragma unroll
;             for (int b = 0; b < 2; ++b)
; #pragma unroll
;                 for (int m = 0; m < 4; ++m)
; #pragma unroll
;                     for (int n = 0; n < 2; ++n) acc[a][b][m][n] = (f32x4){0.f, 0.f, 0.f, 0.f};
.LBB0_871:
	s_ashr_i32 s23, s22, 31
	s_lshl_b64 s[24:25], s[22:23], 20
	s_add_u32 s24, s0, s24
	s_addc_u32 s25, s1, s25
	s_and_b64 s[26:27], s[4:5], exec
	s_cselect_b32 s23, s25, s35
	s_cselect_b32 s29, s24, s34
	s_ashr_i32 s21, s20, 31
	s_lshl_b64 s[26:27], s[20:21], 20
	s_add_u32 s26, s40, s26
	s_addc_u32 s27, s41, s27
	s_and_b64 s[38:39], s[4:5], exec
	s_cselect_b32 s21, s27, s37
	s_cselect_b32 s66, s26, s36
	s_add_u32 s34, s34, 0x80080
	s_addc_u32 s35, s35, 0
	s_add_u32 s67, s36, 0x100
	v_mov_b32_e32 v0, 0
	s_addc_u32 s68, s37, 0
	s_mov_b32 s72, -2
	v_mov_b32_e32 v1, v0
	v_mov_b32_e32 v2, v0
	v_mov_b32_e32 v3, v0
	v_mov_b32_e32 v4, v0
	v_mov_b32_e32 v5, v0
	v_mov_b32_e32 v6, v0
	v_mov_b32_e32 v7, v0
	v_mov_b32_e32 v16, v0
	v_mov_b32_e32 v17, v0
	v_mov_b32_e32 v18, v0
	v_mov_b32_e32 v19, v0
	v_mov_b32_e32 v20, v0
	v_mov_b32_e32 v21, v0
	v_mov_b32_e32 v22, v0
	v_mov_b32_e32 v23, v0
	v_mov_b32_e32 v32, v0
	v_mov_b32_e32 v33, v0
	v_mov_b32_e32 v34, v0
	v_mov_b32_e32 v35, v0
	v_mov_b32_e32 v36, v0
	v_mov_b32_e32 v37, v0
	v_mov_b32_e32 v38, v0
	v_mov_b32_e32 v39, v0
	v_mov_b32_e32 v48, v0
	v_mov_b32_e32 v49, v0
	v_mov_b32_e32 v50, v0
	v_mov_b32_e32 v51, v0
	v_mov_b32_e32 v52, v0
	v_mov_b32_e32 v53, v0
	v_mov_b32_e32 v54, v0
	v_mov_b32_e32 v55, v0
	v_mov_b32_e32 v8, v0
	v_mov_b32_e32 v9, v0
	v_mov_b32_e32 v10, v0
	v_mov_b32_e32 v11, v0
	v_mov_b32_e32 v12, v0
	v_mov_b32_e32 v13, v0
	v_mov_b32_e32 v14, v0
	v_mov_b32_e32 v15, v0
	v_mov_b32_e32 v24, v0
	v_mov_b32_e32 v25, v0
	v_mov_b32_e32 v26, v0
	v_mov_b32_e32 v27, v0
	v_mov_b32_e32 v28, v0
	v_mov_b32_e32 v29, v0
	v_mov_b32_e32 v30, v0
	v_mov_b32_e32 v31, v0
	v_mov_b32_e32 v40, v0
	v_mov_b32_e32 v41, v0
	v_mov_b32_e32 v42, v0
	v_mov_b32_e32 v43, v0
	v_mov_b32_e32 v44, v0
	v_mov_b32_e32 v45, v0
	v_mov_b32_e32 v46, v0
	v_mov_b32_e32 v47, v0
	v_mov_b32_e32 v56, v0
	v_mov_b32_e32 v57, v0
	v_mov_b32_e32 v58, v0
	v_mov_b32_e32 v59, v0
	v_mov_b32_e32 v60, v0
	v_mov_b32_e32 v61, v0
	v_mov_b32_e32 v62, v0
	v_mov_b32_e32 v63, v0
	v_mov_b32_e32 v64, v0
	v_mov_b32_e32 v65, v0
	v_mov_b32_e32 v66, v0
	v_mov_b32_e32 v67, v0
	v_mov_b32_e32 v68, v0
	v_mov_b32_e32 v69, v0
	v_mov_b32_e32 v70, v0
	v_mov_b32_e32 v71, v0
	v_mov_b32_e32 v80, v0
	v_mov_b32_e32 v81, v0
	v_mov_b32_e32 v82, v0
	v_mov_b32_e32 v83, v0
	v_mov_b32_e32 v84, v0
	v_mov_b32_e32 v85, v0
	v_mov_b32_e32 v86, v0
	v_mov_b32_e32 v87, v0
	v_mov_b32_e32 v96, v0
	v_mov_b32_e32 v97, v0
	v_mov_b32_e32 v98, v0
	v_mov_b32_e32 v99, v0
	v_mov_b32_e32 v100, v0
	v_mov_b32_e32 v101, v0
	v_mov_b32_e32 v102, v0
	v_mov_b32_e32 v103, v0
	v_mov_b32_e32 v124, v0
	v_mov_b32_e32 v125, v0
	v_mov_b32_e32 v126, v0
	v_mov_b32_e32 v127, v0
	v_mov_b32_e32 v128, v0
	v_mov_b32_e32 v129, v0
	v_mov_b32_e32 v130, v0
	v_mov_b32_e32 v131, v0
	v_mov_b32_e32 v72, v0
	v_mov_b32_e32 v73, v0
	v_mov_b32_e32 v74, v0
	v_mov_b32_e32 v75, v0
	v_mov_b32_e32 v76, v0
	v_mov_b32_e32 v77, v0
	v_mov_b32_e32 v78, v0
	v_mov_b32_e32 v79, v0
	v_mov_b32_e32 v88, v0
	v_mov_b32_e32 v89, v0
	v_mov_b32_e32 v90, v0
	v_mov_b32_e32 v91, v0
	v_mov_b32_e32 v92, v0
	v_mov_b32_e32 v93, v0
	v_mov_b32_e32 v94, v0
	v_mov_b32_e32 v95, v0
	v_mov_b32_e32 v104, v0
	v_mov_b32_e32 v105, v0
	v_mov_b32_e32 v106, v0
	v_mov_b32_e32 v107, v0
	v_mov_b32_e32 v108, v0
	v_mov_b32_e32 v109, v0
	v_mov_b32_e32 v110, v0
	v_mov_b32_e32 v111, v0
	v_mov_b32_e32 v136, v0
	v_mov_b32_e32 v137, v0
	v_mov_b32_e32 v138, v0
	v_mov_b32_e32 v139, v0
	v_mov_b32_e32 v144, v0
	v_mov_b32_e32 v145, v0
	v_mov_b32_e32 v146, v0
	v_mov_b32_e32 v147, v0
	s_cmp_eq_u64 s[18:19], 0
	s_cbranch_scc0 .Lprio_skip_872
	s_setprio 1
.Lprio_skip_872:
.LBB0_872:
	s_add_u32 s36, s34, 0xfff80080
	s_addc_u32 s37, s35, -1
	s_add_i32 s60, 0, 0x10000
	s_cmp_eq_u32 s72, 28
	s_cselect_b32 s39, s23, s37
	s_cselect_b32 s38, s29, s36
	s_cselect_b32 s37, s21, s68
	s_cselect_b32 s36, s66, s67
	s_add_i32 s73, 0, 0x14000
	v_add_u32_e32 v132, s60, v225
	v_add_u32_e32 v156, s73, v225
	ds_read_b128 v[112:115], v132
	ds_read_b128 v[116:119], v132 offset:1024
	ds_read_b128 v[120:123], v132 offset:2048
	ds_read_b128 v[132:135], v132 offset:3072
	ds_read_b128 v[140:143], v156
	ds_read_b128 v[148:151], v156 offset:1024
	ds_read_b128 v[152:155], v156 offset:2048
	ds_read_b128 v[156:159], v156 offset:3072
	v_lshl_add_u64 v[212:213], s[34:35], 0, v[186:187]
	s_add_i32 m0, s2, 0xc000
	ds_read_b128 v[160:163], v227
	ds_read_b128 v[164:167], v227 offset:1024
	ds_read_b128 v[168:171], v227 offset:2048
	ds_read_b128 v[172:175], v227 offset:3072
	ds_read_b128 v[176:179], v227 offset:4096
	ds_read_b128 v[200:203], v227 offset:5120
	ds_read_b128 v[204:207], v227 offset:6144
	ds_read_b128 v[208:211], v227 offset:7168
	global_load_lds_dwordx4 v[212:213], off
	v_lshl_add_u64 v[212:213], s[34:35], 0, v[198:199]
	s_add_i32 m0, s2, 0xe000
	s_nop 0
	global_load_lds_dwordx4 v[212:213], off
	s_waitcnt vmcnt(8)
	s_waitcnt lgkmcnt(0)
	s_barrier
; #define PG8_STAGE(bufoff, gbase, voff) do { _Pragma("unroll") for (int _i = 0; _i < 2; ++_i) \
;         __builtin_amdgcn_global_load_lds((const unsigned*)((const char*)(gbase) + (voff)[_i]), (PG8_LAS unsigned*)(lds + (bufoff) + ldsw + _i * 8192), 16, 0, 0); } while (0)
; #define PG8_LDA(dst, b, h) do { _Pragma("unroll") for (int m = 0; m < 4; ++m) _Pragma("unroll") for (int k = 0; k < 2; ++k) dst[m][k] = *(const PG8_LAS bf16x8*)(lds + PG8_SA(b, h) + aoff + m * 2048 + k * 1024); } while (0)
; #define PG8_MMA(ai, bj, At, Bt) do { __builtin_amdgcn_s_setprio(1); _Pragma("unroll") for (int m = 0; m < 4; ++m) _Pragma("unroll") for (int n = 0; n < 2; ++n) _Pragma("unroll") for (int k = 0; k < 2; ++k) \
;         acc[ai][bj][m][n] = __builtin_amdgcn_mfma_f32_16x16x32_bf16(Bt[n][k], At[m][k], acc[ai][bj][m][n], 0, 0, 0); __builtin_amdgcn_s_setprio(0); } while (0)
; #define PG8_WAIT_V(n) asm volatile("s_waitcnt vmcnt(" #n ")" ::: "memory")
; #define PG8_WAIT_L(n) asm volatile("s_waitcnt lgkmcnt(" #n ")" ::: "memory")
; #define PG8_BAR __builtin_amdgcn_s_barrier()
; #define PG8_SCHED __builtin_amdgcn_sched_barrier(0)
; template <class Epi, class Sched, bool ALIGN_EPI = false, bool SP2 = false>
; __device__ __forceinline__ void gemm_phase(PG8_LAS unsigned char* lds, const Gemm g, const Sched& S, const Epi& E) {
;     ...
;             PG8_WAIT_V(8); PG8_WAIT_L(0); PG8_BAR; PG8_MMA(0, 0, At, B0); PG8_MMA(0, 1, At, B1); PG8_BAR; PG8_SCHED;
;             PG8_LDA(At, 0, 1); PG8_STAGE(PG8_SB(0, 0), b2, voffB); PG8_STAGE(PG8_SB(0, 1), b2 + hstep, voffB); PG8_STAGE(PG8_SA(0, 0), a2, voffA);
;             PG8_WAIT_V(8); PG8_WAIT_L(0); PG8_BAR; PG8_MMA(1, 0, At, B0); PG8_MMA(1, 1, At, B1); PG8_BAR; PG8_SCHED;
	v_mfma_f32_16x16x32_bf16 v[144:147], v[112:115], v[160:163], v[144:147]
	v_mfma_f32_16x16x32_bf16 v[136:139], v[120:123], v[160:163], v[136:139]
	v_mfma_f32_16x16x32_bf16 v[108:111], v[112:115], v[168:171], v[108:111]
	v_mfma_f32_16x16x32_bf16 v[104:107], v[120:123], v[168:171], v[104:107]
	v_mfma_f32_16x16x32_bf16 v[92:95], v[112:115], v[176:179], v[92:95]
	v_mfma_f32_16x16x32_bf16 v[88:91], v[120:123], v[176:179], v[88:91]
	v_mfma_f32_16x16x32_bf16 v[76:79], v[112:115], v[204:207], v[76:79]
	v_mfma_f32_16x16x32_bf16 v[72:75], v[120:123], v[204:207], v[72:75]
	v_mfma_f32_16x16x32_bf16 v[144:147], v[116:119], v[164:167], v[144:147]
	v_mfma_f32_16x16x32_bf16 v[136:139], v[132:135], v[164:167], v[136:139]
	v_mfma_f32_16x16x32_bf16 v[108:111], v[116:119], v[172:175], v[108:111]
	v_mfma_f32_16x16x32_bf16 v[104:107], v[132:135], v[172:175], v[104:107]
	v_mfma_f32_16x16x32_bf16 v[92:95], v[116:119], v[200:203], v[92:95]
	v_mfma_f32_16x16x32_bf16 v[88:91], v[132:135], v[200:203], v[88:91]
	v_mfma_f32_16x16x32_bf16 v[76:79], v[116:119], v[208:211], v[76:79]
	v_mfma_f32_16x16x32_bf16 v[72:75], v[132:135], v[208:211], v[72:75]
	v_mfma_f32_16x16x32_bf16 v[128:131], v[140:143], v[160:163], v[128:131]
	v_mfma_f32_16x16x32_bf16 v[124:127], v[152:155], v[160:163], v[124:127]
	v_mfma_f32_16x16x32_bf16 v[100:103], v[140:143], v[168:171], v[100:103]
	v_mfma_f32_16x16x32_bf16 v[96:99], v[152:155], v[168:171], v[96:99]
	v_mfma_f32_16x16x32_bf16 v[84:87], v[140:143], v[176:179], v[84:87]
	v_mfma_f32_16x16x32_bf16 v[80:83], v[152:155], v[176:179], v[80:83]
	v_mfma_f32_16x16x32_bf16 v[68:71], v[140:143], v[204:207], v[68:71]
	v_mfma_f32_16x16x32_bf16 v[64:67], v[152:155], v[204:207], v[64:67]
	v_mfma_f32_16x16x32_bf16 v[128:131], v[148:151], v[164:167], v[128:131]
	v_mfma_f32_16x16x32_bf16 v[124:127], v[156:159], v[164:167], v[124:127]
	v_mfma_f32_16x16x32_bf16 v[100:103], v[148:151], v[172:175], v[100:103]
	v_mfma_f32_16x16x32_bf16 v[96:99], v[156:159], v[172:175], v[96:99]
	v_mfma_f32_16x16x32_bf16 v[84:87], v[148:151], v[200:203], v[84:87]
	v_mfma_f32_16x16x32_bf16 v[80:83], v[156:159], v[200:203], v[80:83]
	v_mfma_f32_16x16x32_bf16 v[68:71], v[148:151], v[208:211], v[68:71]
	v_mfma_f32_16x16x32_bf16 v[64:67], v[156:159], v[208:211], v[64:67]
	s_barrier
	s_add_i32 s60, s60, s44
	v_lshl_add_u64 v[212:213], s[36:37], 0, v[188:189]
	s_mov_b32 m0, s60
	ds_read_b128 v[160:163], v227 offset:16384
	ds_read_b128 v[164:167], v227 offset:17408
	ds_read_b128 v[168:171], v227 offset:18432
	ds_read_b128 v[172:175], v227 offset:19456
	ds_read_b128 v[176:179], v227 offset:20480
	ds_read_b128 v[200:203], v227 offset:21504
	ds_read_b128 v[204:207], v227 offset:22528
	ds_read_b128 v[208:211], v227 offset:23552
	global_load_lds_dwordx4 v[212:213], off
	s_add_i32 m0, s60, 0x2000
	s_add_u32 s60, s36, 0x80000
	v_lshl_add_u64 v[214:215], s[36:37], 0, v[180:181]
	s_addc_u32 s61, s37, 0
	s_add_i32 s73, s73, s44
	global_load_lds_dwordx4 v[214:215], off
	v_lshl_add_u64 v[216:217], s[60:61], 0, v[188:189]
	s_mov_b32 m0, s73
	v_lshl_add_u64 v[218:219], s[38:39], 0, v[182:183]
	global_load_lds_dwordx4 v[216:217], off
	v_lshl_add_u64 v[216:217], s[60:61], 0, v[180:181]
	s_add_i32 m0, s73, 0x2000
	s_nop 0
	global_load_lds_dwordx4 v[216:217], off
	v_lshl_add_u64 v[216:217], s[38:39], 0, v[184:185]
	s_mov_b32 m0, s2
	s_nop 0
	global_load_lds_dwordx4 v[216:217], off
	s_mov_b32 m0, s31
	s_nop 0
	global_load_lds_dwordx4 v[218:219], off
	s_waitcnt vmcnt(8)
	s_waitcnt lgkmcnt(0)
	s_barrier
	v_mfma_f32_16x16x32_bf16 v[60:63], v[112:115], v[160:163], v[60:63]
	v_mfma_f32_16x16x32_bf16 v[56:59], v[120:123], v[160:163], v[56:59]
	v_mfma_f32_16x16x32_bf16 v[44:47], v[112:115], v[168:171], v[44:47]
	v_mfma_f32_16x16x32_bf16 v[40:43], v[120:123], v[168:171], v[40:43]
	v_mfma_f32_16x16x32_bf16 v[28:31], v[112:115], v[176:179], v[28:31]
	v_mfma_f32_16x16x32_bf16 v[24:27], v[120:123], v[176:179], v[24:27]
	v_mfma_f32_16x16x32_bf16 v[12:15], v[112:115], v[204:207], v[12:15]
	v_mfma_f32_16x16x32_bf16 v[8:11], v[120:123], v[204:207], v[8:11]
	v_mfma_f32_16x16x32_bf16 v[60:63], v[116:119], v[164:167], v[60:63]
	v_mfma_f32_16x16x32_bf16 v[56:59], v[132:135], v[164:167], v[56:59]
	v_mfma_f32_16x16x32_bf16 v[44:47], v[116:119], v[172:175], v[44:47]
	v_mfma_f32_16x16x32_bf16 v[40:43], v[132:135], v[172:175], v[40:43]
	v_mfma_f32_16x16x32_bf16 v[28:31], v[116:119], v[200:203], v[28:31]
	v_mfma_f32_16x16x32_bf16 v[24:27], v[132:135], v[200:203], v[24:27]
	v_mfma_f32_16x16x32_bf16 v[12:15], v[116:119], v[208:211], v[12:15]
	v_mfma_f32_16x16x32_bf16 v[8:11], v[132:135], v[208:211], v[8:11]
	v_mfma_f32_16x16x32_bf16 v[52:55], v[140:143], v[160:163], v[52:55]
	v_mfma_f32_16x16x32_bf16 v[48:51], v[152:155], v[160:163], v[48:51]
	v_mfma_f32_16x16x32_bf16 v[36:39], v[140:143], v[168:171], v[36:39]
	v_mfma_f32_16x16x32_bf16 v[32:35], v[152:155], v[168:171], v[32:35]
	v_mfma_f32_16x16x32_bf16 v[20:23], v[140:143], v[176:179], v[20:23]
	v_mfma_f32_16x16x32_bf16 v[16:19], v[152:155], v[176:179], v[16:19]
	v_mfma_f32_16x16x32_bf16 v[4:7], v[140:143], v[204:207], v[4:7]
	v_mfma_f32_16x16x32_bf16 v[0:3], v[152:155], v[204:207], v[0:3]
	v_mfma_f32_16x16x32_bf16 v[52:55], v[148:151], v[164:167], v[52:55]
	v_mfma_f32_16x16x32_bf16 v[48:51], v[156:159], v[164:167], v[48:51]
	v_mfma_f32_16x16x32_bf16 v[36:39], v[148:151], v[172:175], v[36:39]
	v_mfma_f32_16x16x32_bf16 v[32:35], v[156:159], v[172:175], v[32:35]
	v_mfma_f32_16x16x32_bf16 v[20:23], v[148:151], v[200:203], v[20:23]
	v_mfma_f32_16x16x32_bf16 v[16:19], v[156:159], v[200:203], v[16:19]
	v_mfma_f32_16x16x32_bf16 v[4:7], v[148:151], v[208:211], v[4:7]
	v_mfma_f32_16x16x32_bf16 v[0:3], v[156:159], v[208:211], v[0:3]
	s_barrier
; #define PG8_STAGE(bufoff, gbase, voff) do { _Pragma("unroll") for (int _i = 0; _i < 2; ++_i) \
;         __builtin_amdgcn_global_load_lds((const unsigned*)((const char*)(gbase) + (voff)[_i]), (PG8_LAS unsigned*)(lds + (bufoff) + ldsw + _i * 8192), 16, 0, 0); } while (0)
; #define PG8_LDA(dst, b, h) do { _Pragma("unroll") for (int m = 0; m < 4; ++m) _Pragma("unroll") for (int k = 0; k < 2; ++k) dst[m][k] = *(const PG8_LAS bf16x8*)(lds + PG8_SA(b, h) + aoff + m * 2048 + k * 1024); } while (0)
; #define PG8_LDB(dst, b, h) do { _Pragma("unroll") for (int n = 0; n < 2; ++n) _Pragma("unroll") for (int k = 0; k < 2; ++k) dst[n][k] = *(const PG8_LAS bf16x8*)(lds + PG8_SB(b, h) + boff + n * 2048 + k * 1024); } while (0)
; #define PG8_MMA(ai, bj, At, Bt) do { __builtin_amdgcn_s_setprio(1); _Pragma("unroll") for (int m = 0; m < 4; ++m) _Pragma("unroll") for (int n = 0; n < 2; ++n) _Pragma("unroll") for (int k = 0; k < 2; ++k) \
;         acc[ai][bj][m][n] = __builtin_amdgcn_mfma_f32_16x16x32_bf16(Bt[n][k], At[m][k], acc[ai][bj][m][n], 0, 0, 0); __builtin_amdgcn_s_setprio(0); } while (0)
; #define PG8_WAIT_V(n) asm volatile("s_waitcnt vmcnt(" #n ")" ::: "memory")
; #define PG8_WAIT_L(n) asm volatile("s_waitcnt lgkmcnt(" #n ")" ::: "memory")
; #define PG8_BAR __builtin_amdgcn_s_barrier()
; #define PG8_SCHED __builtin_amdgcn_sched_barrier(0)
; template <class Epi, class Sched, bool ALIGN_EPI = false, bool SP2 = false>
; __device__ __forceinline__ void gemm_phase(PG8_LAS unsigned char* lds, const Gemm g, const Sched& S, const Epi& E) {
;     ...
;             PG8_LDB(B0, 1, 0); PG8_LDB(B1, 1, 1); PG8_SCHED; PG8_LDA(At, 1, 0); PG8_STAGE(PG8_SA(0, 1), a2 + hstep, voffA);
;             PG8_WAIT_V(8); PG8_WAIT_L(0); PG8_BAR; PG8_MMA(0, 0, At, B0); PG8_MMA(0, 1, At, B1); PG8_BAR; PG8_SCHED;
	s_add_i32 s60, 0, 0x18000
	s_add_i32 s61, 0, 0x1c000
	v_add_u32_e32 v132, s60, v225
	v_add_u32_e32 v156, s61, v225
	ds_read_b128 v[112:115], v132
	ds_read_b128 v[116:119], v132 offset:1024
	ds_read_b128 v[120:123], v132 offset:2048
	ds_read_b128 v[132:135], v132 offset:3072
	ds_read_b128 v[140:143], v156
	ds_read_b128 v[148:151], v156 offset:1024
	ds_read_b128 v[152:155], v156 offset:2048
	ds_read_b128 v[156:159], v156 offset:3072
	s_add_u32 s38, s38, 0x80000
	s_addc_u32 s39, s39, 0
	s_mov_b32 m0, s45
	v_lshl_add_u64 v[220:221], s[38:39], 0, v[184:185]
	ds_read_b128 v[160:163], v227 offset:32768
	ds_read_b128 v[164:167], v227 offset:33792
	ds_read_b128 v[168:171], v227 offset:34816
	ds_read_b128 v[172:175], v227 offset:35840
	ds_read_b128 v[176:179], v227 offset:36864
	ds_read_b128 v[200:203], v227 offset:37888
	ds_read_b128 v[204:207], v227 offset:38912
	ds_read_b128 v[208:211], v227 offset:39936
	global_load_lds_dwordx4 v[220:221], off
	v_lshl_add_u64 v[220:221], s[38:39], 0, v[182:183]
	s_mov_b32 m0, s52
	s_nop 0
	global_load_lds_dwordx4 v[220:221], off
	s_waitcnt vmcnt(8)
	s_waitcnt lgkmcnt(0)
	s_barrier
	v_mfma_f32_16x16x32_bf16 v[144:147], v[112:115], v[160:163], v[144:147]
	v_mfma_f32_16x16x32_bf16 v[136:139], v[120:123], v[160:163], v[136:139]
	v_mfma_f32_16x16x32_bf16 v[108:111], v[112:115], v[168:171], v[108:111]
	v_mfma_f32_16x16x32_bf16 v[104:107], v[120:123], v[168:171], v[104:107]
	v_mfma_f32_16x16x32_bf16 v[92:95], v[112:115], v[176:179], v[92:95]
	v_mfma_f32_16x16x32_bf16 v[88:91], v[120:123], v[176:179], v[88:91]
	v_mfma_f32_16x16x32_bf16 v[76:79], v[112:115], v[204:207], v[76:79]
	v_mfma_f32_16x16x32_bf16 v[72:75], v[120:123], v[204:207], v[72:75]
	v_mfma_f32_16x16x32_bf16 v[144:147], v[116:119], v[164:167], v[144:147]
	v_mfma_f32_16x16x32_bf16 v[136:139], v[132:135], v[164:167], v[136:139]
	v_mfma_f32_16x16x32_bf16 v[108:111], v[116:119], v[172:175], v[108:111]
	v_mfma_f32_16x16x32_bf16 v[104:107], v[132:135], v[172:175], v[104:107]
	v_mfma_f32_16x16x32_bf16 v[92:95], v[116:119], v[200:203], v[92:95]
	v_mfma_f32_16x16x32_bf16 v[88:91], v[132:135], v[200:203], v[88:91]
	v_mfma_f32_16x16x32_bf16 v[76:79], v[116:119], v[208:211], v[76:79]
	v_mfma_f32_16x16x32_bf16 v[72:75], v[132:135], v[208:211], v[72:75]
	v_mfma_f32_16x16x32_bf16 v[128:131], v[140:143], v[160:163], v[128:131]
	v_mfma_f32_16x16x32_bf16 v[124:127], v[152:155], v[160:163], v[124:127]
	v_mfma_f32_16x16x32_bf16 v[100:103], v[140:143], v[168:171], v[100:103]
	v_mfma_f32_16x16x32_bf16 v[96:99], v[152:155], v[168:171], v[96:99]
	v_mfma_f32_16x16x32_bf16 v[84:87], v[140:143], v[176:179], v[84:87]
	v_mfma_f32_16x16x32_bf16 v[80:83], v[152:155], v[176:179], v[80:83]
	v_mfma_f32_16x16x32_bf16 v[68:71], v[140:143], v[204:207], v[68:71]
	v_mfma_f32_16x16x32_bf16 v[64:67], v[152:155], v[204:207], v[64:67]
	v_mfma_f32_16x16x32_bf16 v[128:131], v[148:151], v[164:167], v[128:131]
	v_mfma_f32_16x16x32_bf16 v[124:127], v[156:159], v[164:167], v[124:127]
	v_mfma_f32_16x16x32_bf16 v[100:103], v[148:151], v[172:175], v[100:103]
	v_mfma_f32_16x16x32_bf16 v[96:99], v[156:159], v[172:175], v[96:99]
	v_mfma_f32_16x16x32_bf16 v[84:87], v[148:151], v[200:203], v[84:87]
	v_mfma_f32_16x16x32_bf16 v[80:83], v[156:159], v[200:203], v[80:83]
	v_mfma_f32_16x16x32_bf16 v[68:71], v[148:151], v[208:211], v[68:71]
	v_mfma_f32_16x16x32_bf16 v[64:67], v[156:159], v[208:211], v[64:67]
	s_barrier
; #define PG8_STAGE(bufoff, gbase, voff) do { _Pragma("unroll") for (int _i = 0; _i < 2; ++_i) \
;         __builtin_amdgcn_global_load_lds((const unsigned*)((const char*)(gbase) + (voff)[_i]), (PG8_LAS unsigned*)(lds + (bufoff) + ldsw + _i * 8192), 16, 0, 0); } while (0)
; #define PG8_LDA(dst, b, h) do { _Pragma("unroll") for (int m = 0; m < 4; ++m) _Pragma("unroll") for (int k = 0; k < 2; ++k) dst[m][k] = *(const PG8_LAS bf16x8*)(lds + PG8_SA(b, h) + aoff + m * 2048 + k * 1024); } while (0)
; #define PG8_MMA(ai, bj, At, Bt) do { __builtin_amdgcn_s_setprio(1); _Pragma("unroll") for (int m = 0; m < 4; ++m) _Pragma("unroll") for (int n = 0; n < 2; ++n) _Pragma("unroll") for (int k = 0; k < 2; ++k) \
;         acc[ai][bj][m][n] = __builtin_amdgcn_mfma_f32_16x16x32_bf16(Bt[n][k], At[m][k], acc[ai][bj][m][n], 0, 0, 0); __builtin_amdgcn_s_setprio(0); } while (0)
; #define PG8_WAIT_V(n) asm volatile("s_waitcnt vmcnt(" #n ")" ::: "memory")
; #define PG8_WAIT_L(n) asm volatile("s_waitcnt lgkmcnt(" #n ")" ::: "memory")
; #define PG8_BAR __builtin_amdgcn_s_barrier()
; #define PG8_SCHED __builtin_amdgcn_sched_barrier(0)
; template <class Epi, class Sched, bool ALIGN_EPI = false, bool SP2 = false>
; __device__ __forceinline__ void gemm_phase(PG8_LAS unsigned char* lds, const Gemm g, const Sched& S, const Epi& E) {
;     ...
;             PG8_LDA(At, 1, 1); PG8_STAGE(PG8_SB(1, 0), b3, voffB); PG8_STAGE(PG8_SB(1, 1), b3 + hstep, voffB); PG8_STAGE(PG8_SA(1, 0), a3, voffA);
;             PG8_WAIT_V(8); PG8_WAIT_L(0); PG8_BAR; PG8_MMA(1, 0, At, B0); PG8_MMA(1, 1, At, B1); PG8_BAR; PG8_SCHED;
;     ...
;         if constexpr (ALIGN_EPI) { if (wr == 0) PG8_BAR; }
	s_add_i32 s38, s60, s44
	v_lshl_add_u64 v[212:213], v[212:213], 0, s[78:79]
	s_mov_b32 m0, s38
	ds_read_b128 v[160:163], v227 offset:49152
	ds_read_b128 v[164:167], v227 offset:50176
	ds_read_b128 v[168:171], v227 offset:51200
	ds_read_b128 v[172:175], v227 offset:52224
	ds_read_b128 v[176:179], v227 offset:53248
	ds_read_b128 v[200:203], v227 offset:54272
	ds_read_b128 v[204:207], v227 offset:55296
	ds_read_b128 v[208:211], v227 offset:56320
	global_load_lds_dwordx4 v[212:213], off
	s_add_i32 m0, s38, 0x2000
	s_add_u32 s36, s36, 0x80080
	v_lshl_add_u64 v[212:213], v[214:215], 0, s[78:79]
	s_addc_u32 s37, s37, 0
	s_add_i32 s38, s61, s44
	global_load_lds_dwordx4 v[212:213], off
	v_lshl_add_u64 v[212:213], s[36:37], 0, v[188:189]
	s_mov_b32 m0, s38
	s_nop 0
	global_load_lds_dwordx4 v[212:213], off
	v_lshl_add_u64 v[212:213], s[36:37], 0, v[180:181]
	s_add_i32 m0, s38, 0x2000
	s_nop 0
	global_load_lds_dwordx4 v[212:213], off
	v_lshl_add_u64 v[212:213], v[216:217], 0, s[78:79]
	s_mov_b32 m0, s58
	s_nop 0
	global_load_lds_dwordx4 v[212:213], off
	v_lshl_add_u64 v[212:213], v[218:219], 0, s[78:79]
	s_mov_b32 m0, s62
	s_nop 0
	global_load_lds_dwordx4 v[212:213], off
	s_waitcnt vmcnt(8)
	s_waitcnt lgkmcnt(0)
	s_barrier
	v_mfma_f32_16x16x32_bf16 v[60:63], v[112:115], v[160:163], v[60:63]
	v_mfma_f32_16x16x32_bf16 v[56:59], v[120:123], v[160:163], v[56:59]
	v_mfma_f32_16x16x32_bf16 v[44:47], v[112:115], v[168:171], v[44:47]
	v_mfma_f32_16x16x32_bf16 v[40:43], v[120:123], v[168:171], v[40:43]
	v_mfma_f32_16x16x32_bf16 v[28:31], v[112:115], v[176:179], v[28:31]
	v_mfma_f32_16x16x32_bf16 v[24:27], v[120:123], v[176:179], v[24:27]
	v_mfma_f32_16x16x32_bf16 v[12:15], v[112:115], v[204:207], v[12:15]
	v_mfma_f32_16x16x32_bf16 v[8:11], v[120:123], v[204:207], v[8:11]
	v_mfma_f32_16x16x32_bf16 v[60:63], v[116:119], v[164:167], v[60:63]
	v_mfma_f32_16x16x32_bf16 v[56:59], v[132:135], v[164:167], v[56:59]
	v_mfma_f32_16x16x32_bf16 v[44:47], v[116:119], v[172:175], v[44:47]
	v_mfma_f32_16x16x32_bf16 v[40:43], v[132:135], v[172:175], v[40:43]
	v_mfma_f32_16x16x32_bf16 v[28:31], v[116:119], v[200:203], v[28:31]
	v_mfma_f32_16x16x32_bf16 v[24:27], v[132:135], v[200:203], v[24:27]
	v_mfma_f32_16x16x32_bf16 v[12:15], v[116:119], v[208:211], v[12:15]
	v_mfma_f32_16x16x32_bf16 v[8:11], v[132:135], v[208:211], v[8:11]
	v_mfma_f32_16x16x32_bf16 v[52:55], v[140:143], v[160:163], v[52:55]
	v_mfma_f32_16x16x32_bf16 v[48:51], v[152:155], v[160:163], v[48:51]
	v_mfma_f32_16x16x32_bf16 v[36:39], v[140:143], v[168:171], v[36:39]
	v_mfma_f32_16x16x32_bf16 v[32:35], v[152:155], v[168:171], v[32:35]
	v_mfma_f32_16x16x32_bf16 v[20:23], v[140:143], v[176:179], v[20:23]
	v_mfma_f32_16x16x32_bf16 v[16:19], v[152:155], v[176:179], v[16:19]
	v_mfma_f32_16x16x32_bf16 v[4:7], v[140:143], v[204:207], v[4:7]
	v_mfma_f32_16x16x32_bf16 v[0:3], v[152:155], v[204:207], v[0:3]
	v_mfma_f32_16x16x32_bf16 v[52:55], v[148:151], v[164:167], v[52:55]
	v_mfma_f32_16x16x32_bf16 v[48:51], v[156:159], v[164:167], v[48:51]
	v_mfma_f32_16x16x32_bf16 v[36:39], v[148:151], v[172:175], v[36:39]
	v_mfma_f32_16x16x32_bf16 v[32:35], v[156:159], v[172:175], v[32:35]
	v_mfma_f32_16x16x32_bf16 v[20:23], v[148:151], v[200:203], v[20:23]
	v_mfma_f32_16x16x32_bf16 v[16:19], v[156:159], v[200:203], v[16:19]
	v_mfma_f32_16x16x32_bf16 v[4:7], v[148:151], v[208:211], v[4:7]
	v_mfma_f32_16x16x32_bf16 v[0:3], v[156:159], v[208:211], v[0:3]
	s_barrier
	s_add_i32 s72, s72, 2
	s_add_u32 s34, s34, 0x100
	s_addc_u32 s35, s35, 0
	s_add_u32 s67, s67, 0x100
	s_addc_u32 s68, s68, 0
	s_cmp_gt_u32 s72, 29
	s_cbranch_scc0 .LBB0_872
	s_setprio 0
	v_mov_b32_e32 v196, 0x2000
	s_and_b64 vcc, exec, s[18:19]
	s_cbranch_vccz .LBB0_875
	s_barrier
